# early3 + tail priority 2 + faster wake, and m0-hazard s_nop folded away in the load segments (m0 write, then address VALU, then LDS-DMA)
# speedup vs baseline: 1.0080x; 1.0080x over previous
; #define PG8_STAGE(bufoff, gbase, voff) do { _Pragma("unroll") for (int _i = 0; _i < 2; ++_i) \
;         __builtin_amdgcn_global_load_lds((const unsigned*)((const char*)(gbase) + (voff)[_i]), (PG8_LAS unsigned*)(lds + (bufoff) + ldsw + _i * 8192), 16, 0, 0); } while (0)
; #define PG8_LDA(dst, b, h) do { _Pragma("unroll") for (int m = 0; m < 4; ++m) _Pragma("unroll") for (int k = 0; k < 2; ++k) dst[m][k] = *(const PG8_LAS bf16x8*)(lds + PG8_SA(b, h) + aoff + m * 2048 + k * 1024); } while (0)
; #define PG8_LDB(dst, b, h) do { _Pragma("unroll") for (int n = 0; n < 2; ++n) _Pragma("unroll") for (int k = 0; k < 2; ++k) dst[n][k] = *(const PG8_LAS bf16x8*)(lds + PG8_SB(b, h) + boff + n * 2048 + k * 1024); } while (0)
; #define PG8_MMA(ai, bj, At, Bt) do { __builtin_amdgcn_s_setprio(1); _Pragma("unroll") for (int m = 0; m < 4; ++m) _Pragma("unroll") for (int n = 0; n < 2; ++n) _Pragma("unroll") for (int k = 0; k < 2; ++k) \
;         acc[ai][bj][m][n] = __builtin_amdgcn_mfma_f32_16x16x32_bf16(Bt[n][k], At[m][k], acc[ai][bj][m][n], 0, 0, 0); __builtin_amdgcn_s_setprio(0); } while (0)
; #define PG8_WAIT_V(n) asm volatile("s_waitcnt vmcnt(" #n ")" ::: "memory")
; #define PG8_WAIT_L(n) asm volatile("s_waitcnt lgkmcnt(" #n ")" ::: "memory")
; #define PG8_BAR __builtin_amdgcn_s_barrier()
; template <class Epi, class Sched, bool ALIGN_EPI = false, bool SP2 = false>
; __device__ __forceinline__ void gemm_phase(PG8_LAS unsigned char* lds, const Gemm g, const Sched& S, const Epi& E) {
;     ...
;             const bool last = (t == nt - 2);
;             const char* a1 = cA + (size_t)(t + 1) * kstep;
;             const char* a2 = last ? nA : cA + (size_t)(t + 2) * kstep; const char* b2 = last ? nB : cB + (size_t)(t + 2) * kstep;
;             const char* a3 = a2 + kstep; const char* b3 = b2 + kstep;
;             if constexpr (SP2) {
;             PG8_LDB(B0, 0, 0); PG8_LDB(B1, 0, 1); PG8_SCHED; PG8_LDA(At, 0, 0); PG8_STAGE(PG8_SA(1, 1), a1 + hstep, voffA);
;             PG8_WAIT_V(8); PG8_WAIT_L(0); PG8_BAR; PG8_MMA(0, 0, At, B0); PG8_MMA(0, 1, At, B1); PG8_BAR; PG8_SCHED;
;             PG8_LDA(At, 0, 1); PG8_STAGE(PG8_SB(0, 0), b2, voffB); PG8_STAGE(PG8_SB(0, 1), b2 + hstep, voffB); PG8_STAGE(PG8_SA(0, 0), a2, voffA);
;             PG8_WAIT_V(8); PG8_WAIT_L(0); PG8_BAR; PG8_MMA(1, 0, At, B0); PG8_MMA(1, 1, At, B1); PG8_BAR; PG8_SCHED;
.LBB0_200:
	ds_read_b128 v[148:151], v164
	ds_read_b128 v[152:155], v164 offset:1024
	ds_read_b128 v[156:159], v164 offset:2048
	ds_read_b128 v[168:171], v164 offset:3072
	ds_read_b128 v[172:175], v165
	ds_read_b128 v[176:179], v165 offset:1024
	ds_read_b128 v[180:183], v165 offset:2048
	ds_read_b128 v[184:187], v165 offset:3072
	s_add_u32 s52, s70, 0xfff80080
	s_addc_u32 s53, s71, -1
	s_cmp_eq_u32 s93, 28
	s_cselect_b32 s75, s39, s53
	s_cselect_b32 s74, s69, s52
	s_cselect_b32 s73, s35, s92
	s_cselect_b32 s72, s90, s91
	v_lshl_add_u64 v[220:221], s[70:71], 0, v[138:139]
	s_add_i32 m0, s33, 0xc000
	ds_read_b128 v[188:191], v166
	ds_read_b128 v[192:195], v166 offset:1024
	ds_read_b128 v[196:199], v166 offset:2048
	ds_read_b128 v[200:203], v166 offset:3072
	ds_read_b128 v[204:207], v166 offset:4096
	ds_read_b128 v[208:211], v166 offset:5120
	ds_read_b128 v[212:215], v166 offset:6144
	ds_read_b128 v[216:219], v166 offset:7168
	global_load_lds_dwordx4 v[220:221], off
	s_add_i32 m0, s33, 0xe000
	v_lshl_add_u64 v[220:221], s[70:71], 0, v[140:141]
	global_load_lds_dwordx4 v[220:221], off
	s_waitcnt vmcnt(8)
	s_waitcnt lgkmcnt(0)
	s_setprio 1
	s_barrier
	v_mfma_f32_16x16x32_bf16 v[124:127], v[148:151], v[188:191], v[124:127]
	v_mfma_f32_16x16x32_bf16 v[120:123], v[156:159], v[188:191], v[120:123]
	v_mfma_f32_16x16x32_bf16 v[116:119], v[148:151], v[196:199], v[116:119]
	v_mfma_f32_16x16x32_bf16 v[108:111], v[156:159], v[196:199], v[108:111]
	v_mfma_f32_16x16x32_bf16 v[100:103], v[148:151], v[204:207], v[100:103]
	v_mfma_f32_16x16x32_bf16 v[92:95], v[156:159], v[204:207], v[92:95]
	v_mfma_f32_16x16x32_bf16 v[84:87], v[148:151], v[212:215], v[84:87]
	v_mfma_f32_16x16x32_bf16 v[76:79], v[156:159], v[212:215], v[76:79]
	v_mfma_f32_16x16x32_bf16 v[124:127], v[152:155], v[192:195], v[124:127]
	v_mfma_f32_16x16x32_bf16 v[120:123], v[168:171], v[192:195], v[120:123]
	v_mfma_f32_16x16x32_bf16 v[116:119], v[152:155], v[200:203], v[116:119]
	v_mfma_f32_16x16x32_bf16 v[108:111], v[168:171], v[200:203], v[108:111]
	v_mfma_f32_16x16x32_bf16 v[100:103], v[152:155], v[208:211], v[100:103]
	v_mfma_f32_16x16x32_bf16 v[92:95], v[168:171], v[208:211], v[92:95]
	v_mfma_f32_16x16x32_bf16 v[84:87], v[152:155], v[216:219], v[84:87]
	v_mfma_f32_16x16x32_bf16 v[76:79], v[168:171], v[216:219], v[76:79]
	s_setprio 0
	s_setprio 1
	v_mfma_f32_16x16x32_bf16 v[112:115], v[172:175], v[188:191], v[112:115]
	v_mfma_f32_16x16x32_bf16 v[104:107], v[180:183], v[188:191], v[104:107]
	v_mfma_f32_16x16x32_bf16 v[96:99], v[172:175], v[196:199], v[96:99]
	v_mfma_f32_16x16x32_bf16 v[88:91], v[180:183], v[196:199], v[88:91]
	v_mfma_f32_16x16x32_bf16 v[80:83], v[172:175], v[204:207], v[80:83]
	v_mfma_f32_16x16x32_bf16 v[72:75], v[180:183], v[204:207], v[72:75]
	v_mfma_f32_16x16x32_bf16 v[68:71], v[172:175], v[212:215], v[68:71]
	v_mfma_f32_16x16x32_bf16 v[64:67], v[180:183], v[212:215], v[64:67]
	v_mfma_f32_16x16x32_bf16 v[112:115], v[176:179], v[192:195], v[112:115]
	v_mfma_f32_16x16x32_bf16 v[104:107], v[184:187], v[192:195], v[104:107]
	v_mfma_f32_16x16x32_bf16 v[96:99], v[176:179], v[200:203], v[96:99]
	v_mfma_f32_16x16x32_bf16 v[88:91], v[184:187], v[200:203], v[88:91]
	v_mfma_f32_16x16x32_bf16 v[80:83], v[176:179], v[208:211], v[80:83]
	s_setprio 2
	s_barrier
	v_mfma_f32_16x16x32_bf16 v[72:75], v[184:187], v[208:211], v[72:75]
	v_mfma_f32_16x16x32_bf16 v[68:71], v[176:179], v[216:219], v[68:71]
	v_mfma_f32_16x16x32_bf16 v[64:67], v[184:187], v[216:219], v[64:67]
	s_setprio 0
	s_add_i32 s52, s84, s3
	v_lshl_add_u64 v[220:221], s[72:73], 0, v[132:133]
	s_mov_b32 m0, s52
	ds_read_b128 v[188:191], v166 offset:16384
	ds_read_b128 v[192:195], v166 offset:17408
	ds_read_b128 v[196:199], v166 offset:18432
	ds_read_b128 v[200:203], v166 offset:19456
	ds_read_b128 v[204:207], v166 offset:20480
	ds_read_b128 v[208:211], v166 offset:21504
	ds_read_b128 v[212:215], v166 offset:22528
	ds_read_b128 v[216:219], v166 offset:23552
	global_load_lds_dwordx4 v[220:221], off
	s_add_i32 m0, s52, 0x2000
	s_add_u32 s96, s72, 0x80000
	v_lshl_add_u64 v[222:223], s[72:73], 0, v[128:129]
	s_addc_u32 s97, s73, 0
	s_add_i32 s52, s85, s3
	global_load_lds_dwordx4 v[222:223], off
	v_lshl_add_u64 v[224:225], s[96:97], 0, v[132:133]
	s_mov_b32 m0, s52
	v_lshl_add_u64 v[226:227], s[74:75], 0, v[130:131]
	global_load_lds_dwordx4 v[224:225], off
	s_add_i32 m0, s52, 0x2000
	v_lshl_add_u64 v[224:225], s[96:97], 0, v[128:129]
	global_load_lds_dwordx4 v[224:225], off
	s_mov_b32 m0, s33
	v_lshl_add_u64 v[224:225], s[74:75], 0, v[134:135]
	global_load_lds_dwordx4 v[224:225], off
	s_mov_b32 m0, s76
	s_nop 0
	global_load_lds_dwordx4 v[226:227], off
	s_waitcnt vmcnt(8)
	s_waitcnt lgkmcnt(0)
	s_setprio 1
	s_barrier
; #define PG8_STAGE(bufoff, gbase, voff) do { _Pragma("unroll") for (int _i = 0; _i < 2; ++_i) \
;         __builtin_amdgcn_global_load_lds((const unsigned*)((const char*)(gbase) + (voff)[_i]), (PG8_LAS unsigned*)(lds + (bufoff) + ldsw + _i * 8192), 16, 0, 0); } while (0)
; #define PG8_LDA(dst, b, h) do { _Pragma("unroll") for (int m = 0; m < 4; ++m) _Pragma("unroll") for (int k = 0; k < 2; ++k) dst[m][k] = *(const PG8_LAS bf16x8*)(lds + PG8_SA(b, h) + aoff + m * 2048 + k * 1024); } while (0)
; #define PG8_LDB(dst, b, h) do { _Pragma("unroll") for (int n = 0; n < 2; ++n) _Pragma("unroll") for (int k = 0; k < 2; ++k) dst[n][k] = *(const PG8_LAS bf16x8*)(lds + PG8_SB(b, h) + boff + n * 2048 + k * 1024); } while (0)
; #define PG8_MMA(ai, bj, At, Bt) do { __builtin_amdgcn_s_setprio(1); _Pragma("unroll") for (int m = 0; m < 4; ++m) _Pragma("unroll") for (int n = 0; n < 2; ++n) _Pragma("unroll") for (int k = 0; k < 2; ++k) \
;         acc[ai][bj][m][n] = __builtin_amdgcn_mfma_f32_16x16x32_bf16(Bt[n][k], At[m][k], acc[ai][bj][m][n], 0, 0, 0); __builtin_amdgcn_s_setprio(0); } while (0)
; #define PG8_WAIT_V(n) asm volatile("s_waitcnt vmcnt(" #n ")" ::: "memory")
; #define PG8_WAIT_L(n) asm volatile("s_waitcnt lgkmcnt(" #n ")" ::: "memory")
; #define PG8_BAR __builtin_amdgcn_s_barrier()
; #define PG8_SCHED __builtin_amdgcn_sched_barrier(0)
; template <class Epi, class Sched, bool ALIGN_EPI = false, bool SP2 = false>
; __device__ __forceinline__ void gemm_phase(PG8_LAS unsigned char* lds, const Gemm g, const Sched& S, const Epi& E) {
;     ...
;             PG8_LDB(B0, 0, 0); PG8_LDB(B1, 0, 1); PG8_SCHED; PG8_LDA(At, 0, 0); PG8_STAGE(PG8_SA(1, 1), a1 + hstep, voffA);
;             PG8_WAIT_V(8); PG8_WAIT_L(0); PG8_BAR; PG8_MMA(0, 0, At, B0); PG8_MMA(0, 1, At, B1); PG8_BAR; PG8_SCHED;
;             PG8_LDA(At, 0, 1); PG8_STAGE(PG8_SB(0, 0), b2, voffB); PG8_STAGE(PG8_SB(0, 1), b2 + hstep, voffB); PG8_STAGE(PG8_SA(0, 0), a2, voffA);
;             PG8_WAIT_V(8); PG8_WAIT_L(0); PG8_BAR; PG8_MMA(1, 0, At, B0); PG8_MMA(1, 1, At, B1); PG8_BAR; PG8_SCHED;
;             PG8_LDB(B0, 1, 0); PG8_LDB(B1, 1, 1); PG8_SCHED; PG8_LDA(At, 1, 0); PG8_STAGE(PG8_SA(0, 1), a2 + hstep, voffA);
;             PG8_WAIT_V(8); PG8_WAIT_L(0); PG8_BAR; PG8_MMA(0, 0, At, B0); PG8_MMA(0, 1, At, B1); PG8_BAR; PG8_SCHED;
	v_mfma_f32_16x16x32_bf16 v[60:63], v[148:151], v[188:191], v[60:63]
	v_mfma_f32_16x16x32_bf16 v[56:59], v[156:159], v[188:191], v[56:59]
	v_mfma_f32_16x16x32_bf16 v[52:55], v[148:151], v[196:199], v[52:55]
	v_mfma_f32_16x16x32_bf16 v[44:47], v[156:159], v[196:199], v[44:47]
	v_mfma_f32_16x16x32_bf16 v[36:39], v[148:151], v[204:207], v[36:39]
	v_mfma_f32_16x16x32_bf16 v[28:31], v[156:159], v[204:207], v[28:31]
	v_mfma_f32_16x16x32_bf16 v[20:23], v[148:151], v[212:215], v[20:23]
	v_mfma_f32_16x16x32_bf16 v[12:15], v[156:159], v[212:215], v[12:15]
	v_mfma_f32_16x16x32_bf16 v[60:63], v[152:155], v[192:195], v[60:63]
	v_mfma_f32_16x16x32_bf16 v[56:59], v[168:171], v[192:195], v[56:59]
	v_mfma_f32_16x16x32_bf16 v[52:55], v[152:155], v[200:203], v[52:55]
	v_mfma_f32_16x16x32_bf16 v[44:47], v[168:171], v[200:203], v[44:47]
	v_mfma_f32_16x16x32_bf16 v[36:39], v[152:155], v[208:211], v[36:39]
	v_mfma_f32_16x16x32_bf16 v[28:31], v[168:171], v[208:211], v[28:31]
	v_mfma_f32_16x16x32_bf16 v[20:23], v[152:155], v[216:219], v[20:23]
	v_mfma_f32_16x16x32_bf16 v[12:15], v[168:171], v[216:219], v[12:15]
	s_setprio 0
	s_setprio 1
	v_mfma_f32_16x16x32_bf16 v[48:51], v[172:175], v[188:191], v[48:51]
	v_mfma_f32_16x16x32_bf16 v[40:43], v[180:183], v[188:191], v[40:43]
	v_mfma_f32_16x16x32_bf16 v[32:35], v[172:175], v[196:199], v[32:35]
	v_mfma_f32_16x16x32_bf16 v[24:27], v[180:183], v[196:199], v[24:27]
	v_mfma_f32_16x16x32_bf16 v[16:19], v[172:175], v[204:207], v[16:19]
	v_mfma_f32_16x16x32_bf16 v[8:11], v[180:183], v[204:207], v[8:11]
	v_mfma_f32_16x16x32_bf16 v[4:7], v[172:175], v[212:215], v[4:7]
	v_mfma_f32_16x16x32_bf16 v[0:3], v[180:183], v[212:215], v[0:3]
	v_mfma_f32_16x16x32_bf16 v[48:51], v[176:179], v[192:195], v[48:51]
	v_mfma_f32_16x16x32_bf16 v[40:43], v[184:187], v[192:195], v[40:43]
	v_mfma_f32_16x16x32_bf16 v[32:35], v[176:179], v[200:203], v[32:35]
	v_mfma_f32_16x16x32_bf16 v[24:27], v[184:187], v[200:203], v[24:27]
	v_mfma_f32_16x16x32_bf16 v[16:19], v[176:179], v[208:211], v[16:19]
	s_setprio 2
	s_barrier
	v_mfma_f32_16x16x32_bf16 v[8:11], v[184:187], v[208:211], v[8:11]
	v_mfma_f32_16x16x32_bf16 v[4:7], v[176:179], v[216:219], v[4:7]
	v_mfma_f32_16x16x32_bf16 v[0:3], v[184:187], v[216:219], v[0:3]
	s_setprio 0
	s_add_i32 s52, 0, 0x18000
	v_add_u32_e32 v136, s52, v161
	s_add_i32 s53, 0, 0x1c000
	ds_read_b128 v[148:151], v136
	ds_read_b128 v[152:155], v136 offset:1024
	ds_read_b128 v[156:159], v136 offset:2048
	ds_read_b128 v[168:171], v136 offset:3072
	v_add_u32_e32 v136, s53, v161
	ds_read_b128 v[172:175], v136
	ds_read_b128 v[176:179], v136 offset:1024
	ds_read_b128 v[180:183], v136 offset:2048
	ds_read_b128 v[184:187], v136 offset:3072
	s_add_u32 s74, s74, 0x80000
	s_addc_u32 s75, s75, 0
	s_mov_b32 m0, s77
	v_lshl_add_u64 v[228:229], s[74:75], 0, v[134:135]
	ds_read_b128 v[188:191], v166 offset:32768
	ds_read_b128 v[192:195], v166 offset:33792
	ds_read_b128 v[196:199], v166 offset:34816
	ds_read_b128 v[200:203], v166 offset:35840
	ds_read_b128 v[204:207], v166 offset:36864
	ds_read_b128 v[208:211], v166 offset:37888
	ds_read_b128 v[212:215], v166 offset:38912
	ds_read_b128 v[216:219], v166 offset:39936
	global_load_lds_dwordx4 v[228:229], off
	s_mov_b32 m0, s78
	v_lshl_add_u64 v[228:229], s[74:75], 0, v[130:131]
	global_load_lds_dwordx4 v[228:229], off
	s_waitcnt vmcnt(8)
	s_waitcnt lgkmcnt(0)
	s_setprio 1
	s_barrier
	v_mfma_f32_16x16x32_bf16 v[124:127], v[148:151], v[188:191], v[124:127]
	v_mfma_f32_16x16x32_bf16 v[120:123], v[156:159], v[188:191], v[120:123]
	v_mfma_f32_16x16x32_bf16 v[116:119], v[148:151], v[196:199], v[116:119]
	v_mfma_f32_16x16x32_bf16 v[108:111], v[156:159], v[196:199], v[108:111]
	v_mfma_f32_16x16x32_bf16 v[100:103], v[148:151], v[204:207], v[100:103]
	v_mfma_f32_16x16x32_bf16 v[92:95], v[156:159], v[204:207], v[92:95]
	v_mfma_f32_16x16x32_bf16 v[84:87], v[148:151], v[212:215], v[84:87]
	v_mfma_f32_16x16x32_bf16 v[76:79], v[156:159], v[212:215], v[76:79]
	v_mfma_f32_16x16x32_bf16 v[124:127], v[152:155], v[192:195], v[124:127]
	v_mfma_f32_16x16x32_bf16 v[120:123], v[168:171], v[192:195], v[120:123]
	v_mfma_f32_16x16x32_bf16 v[116:119], v[152:155], v[200:203], v[116:119]
	v_mfma_f32_16x16x32_bf16 v[108:111], v[168:171], v[200:203], v[108:111]
	v_mfma_f32_16x16x32_bf16 v[100:103], v[152:155], v[208:211], v[100:103]
	v_mfma_f32_16x16x32_bf16 v[92:95], v[168:171], v[208:211], v[92:95]
	v_mfma_f32_16x16x32_bf16 v[84:87], v[152:155], v[216:219], v[84:87]
	v_mfma_f32_16x16x32_bf16 v[76:79], v[168:171], v[216:219], v[76:79]
	s_setprio 0
	s_setprio 1
	v_mfma_f32_16x16x32_bf16 v[112:115], v[172:175], v[188:191], v[112:115]
	v_mfma_f32_16x16x32_bf16 v[104:107], v[180:183], v[188:191], v[104:107]
	v_mfma_f32_16x16x32_bf16 v[96:99], v[172:175], v[196:199], v[96:99]
	v_mfma_f32_16x16x32_bf16 v[88:91], v[180:183], v[196:199], v[88:91]
	v_mfma_f32_16x16x32_bf16 v[80:83], v[172:175], v[204:207], v[80:83]
	v_mfma_f32_16x16x32_bf16 v[72:75], v[180:183], v[204:207], v[72:75]
	v_mfma_f32_16x16x32_bf16 v[68:71], v[172:175], v[212:215], v[68:71]
	v_mfma_f32_16x16x32_bf16 v[64:67], v[180:183], v[212:215], v[64:67]
	v_mfma_f32_16x16x32_bf16 v[112:115], v[176:179], v[192:195], v[112:115]
	v_mfma_f32_16x16x32_bf16 v[104:107], v[184:187], v[192:195], v[104:107]
	v_mfma_f32_16x16x32_bf16 v[96:99], v[176:179], v[200:203], v[96:99]
	v_mfma_f32_16x16x32_bf16 v[88:91], v[184:187], v[200:203], v[88:91]
	v_mfma_f32_16x16x32_bf16 v[80:83], v[176:179], v[208:211], v[80:83]
	s_setprio 2
	s_barrier
; #define PG8_STAGE(bufoff, gbase, voff) do { _Pragma("unroll") for (int _i = 0; _i < 2; ++_i) \
;         __builtin_amdgcn_global_load_lds((const unsigned*)((const char*)(gbase) + (voff)[_i]), (PG8_LAS unsigned*)(lds + (bufoff) + ldsw + _i * 8192), 16, 0, 0); } while (0)
; #define PG8_LDA(dst, b, h) do { _Pragma("unroll") for (int m = 0; m < 4; ++m) _Pragma("unroll") for (int k = 0; k < 2; ++k) dst[m][k] = *(const PG8_LAS bf16x8*)(lds + PG8_SA(b, h) + aoff + m * 2048 + k * 1024); } while (0)
; #define PG8_MMA(ai, bj, At, Bt) do { __builtin_amdgcn_s_setprio(1); _Pragma("unroll") for (int m = 0; m < 4; ++m) _Pragma("unroll") for (int n = 0; n < 2; ++n) _Pragma("unroll") for (int k = 0; k < 2; ++k) \
;         acc[ai][bj][m][n] = __builtin_amdgcn_mfma_f32_16x16x32_bf16(Bt[n][k], At[m][k], acc[ai][bj][m][n], 0, 0, 0); __builtin_amdgcn_s_setprio(0); } while (0)
; #define PG8_WAIT_V(n) asm volatile("s_waitcnt vmcnt(" #n ")" ::: "memory")
; #define PG8_WAIT_L(n) asm volatile("s_waitcnt lgkmcnt(" #n ")" ::: "memory")
; #define PG8_BAR __builtin_amdgcn_s_barrier()
; #define PG8_SCHED __builtin_amdgcn_sched_barrier(0)
; template <class Epi, class Sched, bool ALIGN_EPI = false, bool SP2 = false>
; __device__ __forceinline__ void gemm_phase(PG8_LAS unsigned char* lds, const Gemm g, const Sched& S, const Epi& E) {
;     ...
;             PG8_WAIT_V(8); PG8_WAIT_L(0); PG8_BAR; PG8_MMA(0, 0, At, B0); PG8_MMA(0, 1, At, B1); PG8_BAR; PG8_SCHED;
;             PG8_LDA(At, 1, 1); PG8_STAGE(PG8_SB(1, 0), b3, voffB); PG8_STAGE(PG8_SB(1, 1), b3 + hstep, voffB); PG8_STAGE(PG8_SA(1, 0), a3, voffA);
;             PG8_WAIT_V(8); PG8_WAIT_L(0); PG8_BAR; PG8_MMA(1, 0, At, B0); PG8_MMA(1, 1, At, B1); PG8_BAR; PG8_SCHED;
	v_mfma_f32_16x16x32_bf16 v[72:75], v[184:187], v[208:211], v[72:75]
	v_mfma_f32_16x16x32_bf16 v[68:71], v[176:179], v[216:219], v[68:71]
	v_mfma_f32_16x16x32_bf16 v[64:67], v[184:187], v[216:219], v[64:67]
	s_setprio 0
	s_add_i32 s52, s52, s3
	v_lshl_add_u64 v[220:221], v[220:221], 0, s[12:13]
	s_mov_b32 m0, s52
	ds_read_b128 v[188:191], v166 offset:49152
	ds_read_b128 v[192:195], v166 offset:50176
	ds_read_b128 v[196:199], v166 offset:51200
	ds_read_b128 v[200:203], v166 offset:52224
	ds_read_b128 v[204:207], v166 offset:53248
	ds_read_b128 v[208:211], v166 offset:54272
	ds_read_b128 v[212:215], v166 offset:55296
	ds_read_b128 v[216:219], v166 offset:56320
	global_load_lds_dwordx4 v[220:221], off
	s_add_i32 m0, s52, 0x2000
	s_add_u32 s72, s72, 0x80080
	v_lshl_add_u64 v[220:221], v[222:223], 0, s[12:13]
	s_addc_u32 s73, s73, 0
	s_add_i32 s52, s53, s3
	global_load_lds_dwordx4 v[220:221], off
	s_mov_b32 m0, s52
	v_lshl_add_u64 v[220:221], s[72:73], 0, v[132:133]
	global_load_lds_dwordx4 v[220:221], off
	s_add_i32 m0, s52, 0x2000
	v_lshl_add_u64 v[220:221], s[72:73], 0, v[128:129]
	global_load_lds_dwordx4 v[220:221], off
	s_mov_b32 m0, s80
	v_lshl_add_u64 v[220:221], v[224:225], 0, s[12:13]
	global_load_lds_dwordx4 v[220:221], off
	s_mov_b32 m0, s81
	v_lshl_add_u64 v[220:221], v[226:227], 0, s[12:13]
	global_load_lds_dwordx4 v[220:221], off
	s_waitcnt vmcnt(8)
	s_waitcnt lgkmcnt(0)
	s_setprio 1
	s_barrier
	v_mfma_f32_16x16x32_bf16 v[60:63], v[148:151], v[188:191], v[60:63]
	v_mfma_f32_16x16x32_bf16 v[56:59], v[156:159], v[188:191], v[56:59]
	v_mfma_f32_16x16x32_bf16 v[52:55], v[148:151], v[196:199], v[52:55]
	v_mfma_f32_16x16x32_bf16 v[44:47], v[156:159], v[196:199], v[44:47]
	v_mfma_f32_16x16x32_bf16 v[36:39], v[148:151], v[204:207], v[36:39]
	v_mfma_f32_16x16x32_bf16 v[28:31], v[156:159], v[204:207], v[28:31]
	v_mfma_f32_16x16x32_bf16 v[20:23], v[148:151], v[212:215], v[20:23]
	v_mfma_f32_16x16x32_bf16 v[12:15], v[156:159], v[212:215], v[12:15]
	v_mfma_f32_16x16x32_bf16 v[60:63], v[152:155], v[192:195], v[60:63]
	v_mfma_f32_16x16x32_bf16 v[56:59], v[168:171], v[192:195], v[56:59]
	v_mfma_f32_16x16x32_bf16 v[52:55], v[152:155], v[200:203], v[52:55]
	v_mfma_f32_16x16x32_bf16 v[44:47], v[168:171], v[200:203], v[44:47]
	v_mfma_f32_16x16x32_bf16 v[36:39], v[152:155], v[208:211], v[36:39]
	v_mfma_f32_16x16x32_bf16 v[28:31], v[168:171], v[208:211], v[28:31]
	v_mfma_f32_16x16x32_bf16 v[20:23], v[152:155], v[216:219], v[20:23]
	v_mfma_f32_16x16x32_bf16 v[12:15], v[168:171], v[216:219], v[12:15]
	s_setprio 0
	s_setprio 1
	v_mfma_f32_16x16x32_bf16 v[48:51], v[172:175], v[188:191], v[48:51]
	v_mfma_f32_16x16x32_bf16 v[40:43], v[180:183], v[188:191], v[40:43]
	v_mfma_f32_16x16x32_bf16 v[32:35], v[172:175], v[196:199], v[32:35]
	v_mfma_f32_16x16x32_bf16 v[24:27], v[180:183], v[196:199], v[24:27]
	v_mfma_f32_16x16x32_bf16 v[16:19], v[172:175], v[204:207], v[16:19]
	v_mfma_f32_16x16x32_bf16 v[8:11], v[180:183], v[204:207], v[8:11]
	v_mfma_f32_16x16x32_bf16 v[4:7], v[172:175], v[212:215], v[4:7]
	v_mfma_f32_16x16x32_bf16 v[0:3], v[180:183], v[212:215], v[0:3]
	v_mfma_f32_16x16x32_bf16 v[48:51], v[176:179], v[192:195], v[48:51]
	v_mfma_f32_16x16x32_bf16 v[40:43], v[184:187], v[192:195], v[40:43]
	v_mfma_f32_16x16x32_bf16 v[32:35], v[176:179], v[200:203], v[32:35]
	v_mfma_f32_16x16x32_bf16 v[24:27], v[184:187], v[200:203], v[24:27]
	v_mfma_f32_16x16x32_bf16 v[16:19], v[176:179], v[208:211], v[16:19]
	s_setprio 2
	s_barrier
	v_mfma_f32_16x16x32_bf16 v[8:11], v[184:187], v[208:211], v[8:11]
	v_mfma_f32_16x16x32_bf16 v[4:7], v[176:179], v[216:219], v[4:7]
	v_mfma_f32_16x16x32_bf16 v[0:3], v[184:187], v[216:219], v[0:3]
	s_setprio 0
	s_add_i32 s93, s93, 2
	s_add_u32 s70, s70, 0x100
	s_addc_u32 s71, s71, 0
	s_add_u32 s91, s91, 0x100
	s_addc_u32 s92, s92, 0
	s_cmp_gt_u32 s93, 29
	s_cbranch_scc0 .LBB0_200
	s_and_b64 vcc, exec, s[14:15]
	s_cbranch_vccz .LBB0_203
	s_barrier

; #define PG8_STAGE(bufoff, gbase, voff) do { _Pragma("unroll") for (int _i = 0; _i < 2; ++_i) \
;         __builtin_amdgcn_global_load_lds((const unsigned*)((const char*)(gbase) + (voff)[_i]), (PG8_LAS unsigned*)(lds + (bufoff) + ldsw + _i * 8192), 16, 0, 0); } while (0)
; #define PG8_LDA(dst, b, h) do { _Pragma("unroll") for (int m = 0; m < 4; ++m) _Pragma("unroll") for (int k = 0; k < 2; ++k) dst[m][k] = *(const PG8_LAS bf16x8*)(lds + PG8_SA(b, h) + aoff + m * 2048 + k * 1024); } while (0)
; #define PG8_LDB(dst, b, h) do { _Pragma("unroll") for (int n = 0; n < 2; ++n) _Pragma("unroll") for (int k = 0; k < 2; ++k) dst[n][k] = *(const PG8_LAS bf16x8*)(lds + PG8_SB(b, h) + boff + n * 2048 + k * 1024); } while (0)
; #define PG8_MMA(ai, bj, At, Bt) do { __builtin_amdgcn_s_setprio(1); _Pragma("unroll") for (int m = 0; m < 4; ++m) _Pragma("unroll") for (int n = 0; n < 2; ++n) _Pragma("unroll") for (int k = 0; k < 2; ++k) \
;         acc[ai][bj][m][n] = __builtin_amdgcn_mfma_f32_16x16x32_bf16(Bt[n][k], At[m][k], acc[ai][bj][m][n], 0, 0, 0); __builtin_amdgcn_s_setprio(0); } while (0)
; #define PG8_WAIT_V(n) asm volatile("s_waitcnt vmcnt(" #n ")" ::: "memory")
; #define PG8_WAIT_L(n) asm volatile("s_waitcnt lgkmcnt(" #n ")" ::: "memory")
; #define PG8_BAR __builtin_amdgcn_s_barrier()
; template <class Epi, class Sched, bool ALIGN_EPI = false, bool SP2 = false>
; __device__ __forceinline__ void gemm_phase(PG8_LAS unsigned char* lds, const Gemm g, const Sched& S, const Epi& E) {
;     ...
;             const bool last = (t == nt - 2);
;             const char* a1 = cA + (size_t)(t + 1) * kstep;
;             const char* a2 = last ? nA : cA + (size_t)(t + 2) * kstep; const char* b2 = last ? nB : cB + (size_t)(t + 2) * kstep;
;             const char* a3 = a2 + kstep; const char* b3 = b2 + kstep;
;             if constexpr (SP2) {
;             PG8_LDB(B0, 0, 0); PG8_LDB(B1, 0, 1); PG8_SCHED; PG8_LDA(At, 0, 0); PG8_STAGE(PG8_SA(1, 1), a1 + hstep, voffA);
;             PG8_WAIT_V(8); PG8_WAIT_L(0); PG8_BAR; PG8_MMA(0, 0, At, B0); PG8_MMA(0, 1, At, B1); PG8_BAR; PG8_SCHED;
;             PG8_LDA(At, 0, 1); PG8_STAGE(PG8_SB(0, 0), b2, voffB); PG8_STAGE(PG8_SB(0, 1), b2 + hstep, voffB); PG8_STAGE(PG8_SA(0, 0), a2, voffA);
;             PG8_WAIT_V(8); PG8_WAIT_L(0); PG8_BAR; PG8_MMA(1, 0, At, B0); PG8_MMA(1, 1, At, B1); PG8_BAR; PG8_SCHED;
.LBB0_374:
	ds_read_b128 v[128:131], v230
	ds_read_b128 v[132:135], v230 offset:1024
	ds_read_b128 v[158:161], v230 offset:2048
	ds_read_b128 v[162:165], v230 offset:3072
	ds_read_b128 v[166:169], v231
	ds_read_b128 v[170:173], v231 offset:1024
	ds_read_b128 v[174:177], v231 offset:2048
	ds_read_b128 v[178:181], v231 offset:3072
	s_add_u32 s52, s76, 0xfff80080
	s_addc_u32 s53, s77, -1
	s_cmp_eq_u32 vcc_hi, 28
	s_cselect_b32 s81, s11, s53
	s_cselect_b32 s80, s55, s52
	s_cselect_b32 s79, s51, vcc_lo
	s_cselect_b32 s78, s73, s75
	v_lshl_add_u64 v[214:215], s[76:77], 0, v[150:151]
	s_add_i32 m0, s28, 0xc000
	ds_read_b128 v[182:185], v232
	ds_read_b128 v[186:189], v232 offset:1024
	ds_read_b128 v[190:193], v232 offset:2048
	ds_read_b128 v[194:197], v232 offset:3072
	ds_read_b128 v[198:201], v232 offset:4096
	ds_read_b128 v[202:205], v232 offset:5120
	ds_read_b128 v[206:209], v232 offset:6144
	ds_read_b128 v[210:213], v232 offset:7168
	global_load_lds_dwordx4 v[214:215], off
	s_add_i32 m0, s28, 0xe000
	v_lshl_add_u64 v[214:215], s[76:77], 0, v[152:153]
	global_load_lds_dwordx4 v[214:215], off
	s_waitcnt vmcnt(8)
	s_waitcnt lgkmcnt(0)
	s_setprio 1
	s_barrier
	v_mfma_f32_16x16x32_bf16 v[124:127], v[128:131], v[182:185], v[124:127]
	v_mfma_f32_16x16x32_bf16 v[120:123], v[158:161], v[182:185], v[120:123]
	v_mfma_f32_16x16x32_bf16 v[116:119], v[128:131], v[190:193], v[116:119]
	v_mfma_f32_16x16x32_bf16 v[112:115], v[158:161], v[190:193], v[112:115]
	v_mfma_f32_16x16x32_bf16 v[108:111], v[128:131], v[198:201], v[108:111]
	v_mfma_f32_16x16x32_bf16 v[104:107], v[158:161], v[198:201], v[104:107]
	v_mfma_f32_16x16x32_bf16 v[100:103], v[128:131], v[206:209], v[100:103]
	v_mfma_f32_16x16x32_bf16 v[96:99], v[158:161], v[206:209], v[96:99]
	v_mfma_f32_16x16x32_bf16 v[124:127], v[132:135], v[186:189], v[124:127]
	v_mfma_f32_16x16x32_bf16 v[120:123], v[162:165], v[186:189], v[120:123]
	v_mfma_f32_16x16x32_bf16 v[116:119], v[132:135], v[194:197], v[116:119]
	v_mfma_f32_16x16x32_bf16 v[112:115], v[162:165], v[194:197], v[112:115]
	v_mfma_f32_16x16x32_bf16 v[108:111], v[132:135], v[202:205], v[108:111]
	v_mfma_f32_16x16x32_bf16 v[104:107], v[162:165], v[202:205], v[104:107]
	v_mfma_f32_16x16x32_bf16 v[100:103], v[132:135], v[210:213], v[100:103]
	v_mfma_f32_16x16x32_bf16 v[96:99], v[162:165], v[210:213], v[96:99]
	s_setprio 0
	s_setprio 1
	v_mfma_f32_16x16x32_bf16 v[60:63], v[166:169], v[182:185], v[60:63]
	v_mfma_f32_16x16x32_bf16 v[56:59], v[174:177], v[182:185], v[56:59]
	v_mfma_f32_16x16x32_bf16 v[52:55], v[166:169], v[190:193], v[52:55]
	v_mfma_f32_16x16x32_bf16 v[48:51], v[174:177], v[190:193], v[48:51]
	v_mfma_f32_16x16x32_bf16 v[44:47], v[166:169], v[198:201], v[44:47]
	v_mfma_f32_16x16x32_bf16 v[40:43], v[174:177], v[198:201], v[40:43]
	v_mfma_f32_16x16x32_bf16 v[36:39], v[166:169], v[206:209], v[36:39]
	v_mfma_f32_16x16x32_bf16 v[32:35], v[174:177], v[206:209], v[32:35]
	v_mfma_f32_16x16x32_bf16 v[60:63], v[170:173], v[186:189], v[60:63]
	v_mfma_f32_16x16x32_bf16 v[56:59], v[178:181], v[186:189], v[56:59]
	v_mfma_f32_16x16x32_bf16 v[52:55], v[170:173], v[194:197], v[52:55]
	v_mfma_f32_16x16x32_bf16 v[48:51], v[178:181], v[194:197], v[48:51]
	v_mfma_f32_16x16x32_bf16 v[44:47], v[170:173], v[202:205], v[44:47]
	s_setprio 2
	s_barrier
	v_mfma_f32_16x16x32_bf16 v[40:43], v[178:181], v[202:205], v[40:43]
	v_mfma_f32_16x16x32_bf16 v[36:39], v[170:173], v[210:213], v[36:39]
	v_mfma_f32_16x16x32_bf16 v[32:35], v[178:181], v[210:213], v[32:35]
	s_setprio 0
	s_add_i32 s52, s93, s3
	v_lshl_add_u64 v[214:215], s[78:79], 0, v[138:139]
	s_mov_b32 m0, s52
	ds_read_b128 v[182:185], v232 offset:16384
	ds_read_b128 v[186:189], v232 offset:17408
	ds_read_b128 v[190:193], v232 offset:18432
	ds_read_b128 v[194:197], v232 offset:19456
	ds_read_b128 v[198:201], v232 offset:20480
	ds_read_b128 v[202:205], v232 offset:21504
	ds_read_b128 v[206:209], v232 offset:22528
	ds_read_b128 v[210:213], v232 offset:23552
	global_load_lds_dwordx4 v[214:215], off
	s_add_i32 m0, s52, 0x2000
	s_add_u32 s52, s78, 0x80000
	v_lshl_add_u64 v[216:217], s[78:79], 0, v[142:143]
	s_addc_u32 s53, s79, 0
	s_add_i32 s56, s10, s3
	global_load_lds_dwordx4 v[216:217], off
	v_lshl_add_u64 v[218:219], s[52:53], 0, v[138:139]
	s_mov_b32 m0, s56
	v_lshl_add_u64 v[220:221], s[80:81], 0, v[140:141]
	global_load_lds_dwordx4 v[218:219], off
	s_add_i32 m0, s56, 0x2000
	v_lshl_add_u64 v[218:219], s[52:53], 0, v[142:143]
	global_load_lds_dwordx4 v[218:219], off
	s_mov_b32 m0, s28
	v_lshl_add_u64 v[218:219], s[80:81], 0, v[136:137]
	global_load_lds_dwordx4 v[218:219], off
	s_mov_b32 m0, s29
	s_nop 0
	global_load_lds_dwordx4 v[220:221], off
	s_waitcnt vmcnt(8)
	s_waitcnt lgkmcnt(0)
	s_setprio 1
	s_barrier
; #define PG8_STAGE(bufoff, gbase, voff) do { _Pragma("unroll") for (int _i = 0; _i < 2; ++_i) \
;         __builtin_amdgcn_global_load_lds((const unsigned*)((const char*)(gbase) + (voff)[_i]), (PG8_LAS unsigned*)(lds + (bufoff) + ldsw + _i * 8192), 16, 0, 0); } while (0)
; #define PG8_LDA(dst, b, h) do { _Pragma("unroll") for (int m = 0; m < 4; ++m) _Pragma("unroll") for (int k = 0; k < 2; ++k) dst[m][k] = *(const PG8_LAS bf16x8*)(lds + PG8_SA(b, h) + aoff + m * 2048 + k * 1024); } while (0)
; #define PG8_LDB(dst, b, h) do { _Pragma("unroll") for (int n = 0; n < 2; ++n) _Pragma("unroll") for (int k = 0; k < 2; ++k) dst[n][k] = *(const PG8_LAS bf16x8*)(lds + PG8_SB(b, h) + boff + n * 2048 + k * 1024); } while (0)
; #define PG8_MMA(ai, bj, At, Bt) do { __builtin_amdgcn_s_setprio(1); _Pragma("unroll") for (int m = 0; m < 4; ++m) _Pragma("unroll") for (int n = 0; n < 2; ++n) _Pragma("unroll") for (int k = 0; k < 2; ++k) \
;         acc[ai][bj][m][n] = __builtin_amdgcn_mfma_f32_16x16x32_bf16(Bt[n][k], At[m][k], acc[ai][bj][m][n], 0, 0, 0); __builtin_amdgcn_s_setprio(0); } while (0)
; #define PG8_WAIT_V(n) asm volatile("s_waitcnt vmcnt(" #n ")" ::: "memory")
; #define PG8_WAIT_L(n) asm volatile("s_waitcnt lgkmcnt(" #n ")" ::: "memory")
; #define PG8_BAR __builtin_amdgcn_s_barrier()
; #define PG8_SCHED __builtin_amdgcn_sched_barrier(0)
; template <class Epi, class Sched, bool ALIGN_EPI = false, bool SP2 = false>
; __device__ __forceinline__ void gemm_phase(PG8_LAS unsigned char* lds, const Gemm g, const Sched& S, const Epi& E) {
;     ...
;             PG8_LDB(B0, 0, 0); PG8_LDB(B1, 0, 1); PG8_SCHED; PG8_LDA(At, 0, 0); PG8_STAGE(PG8_SA(1, 1), a1 + hstep, voffA);
;             PG8_WAIT_V(8); PG8_WAIT_L(0); PG8_BAR; PG8_MMA(0, 0, At, B0); PG8_MMA(0, 1, At, B1); PG8_BAR; PG8_SCHED;
;             PG8_LDA(At, 0, 1); PG8_STAGE(PG8_SB(0, 0), b2, voffB); PG8_STAGE(PG8_SB(0, 1), b2 + hstep, voffB); PG8_STAGE(PG8_SA(0, 0), a2, voffA);
;             PG8_WAIT_V(8); PG8_WAIT_L(0); PG8_BAR; PG8_MMA(1, 0, At, B0); PG8_MMA(1, 1, At, B1); PG8_BAR; PG8_SCHED;
;             PG8_LDB(B0, 1, 0); PG8_LDB(B1, 1, 1); PG8_SCHED; PG8_LDA(At, 1, 0); PG8_STAGE(PG8_SA(0, 1), a2 + hstep, voffA);
;             PG8_WAIT_V(8); PG8_WAIT_L(0); PG8_BAR; PG8_MMA(0, 0, At, B0); PG8_MMA(0, 1, At, B1); PG8_BAR; PG8_SCHED;
	v_mfma_f32_16x16x32_bf16 v[92:95], v[128:131], v[182:185], v[92:95]
	v_mfma_f32_16x16x32_bf16 v[88:91], v[158:161], v[182:185], v[88:91]
	v_mfma_f32_16x16x32_bf16 v[84:87], v[128:131], v[190:193], v[84:87]
	v_mfma_f32_16x16x32_bf16 v[80:83], v[158:161], v[190:193], v[80:83]
	v_mfma_f32_16x16x32_bf16 v[76:79], v[128:131], v[198:201], v[76:79]
	v_mfma_f32_16x16x32_bf16 v[72:75], v[158:161], v[198:201], v[72:75]
	v_mfma_f32_16x16x32_bf16 v[68:71], v[128:131], v[206:209], v[68:71]
	v_mfma_f32_16x16x32_bf16 v[64:67], v[158:161], v[206:209], v[64:67]
	v_mfma_f32_16x16x32_bf16 v[92:95], v[132:135], v[186:189], v[92:95]
	v_mfma_f32_16x16x32_bf16 v[88:91], v[162:165], v[186:189], v[88:91]
	v_mfma_f32_16x16x32_bf16 v[84:87], v[132:135], v[194:197], v[84:87]
	v_mfma_f32_16x16x32_bf16 v[80:83], v[162:165], v[194:197], v[80:83]
	v_mfma_f32_16x16x32_bf16 v[76:79], v[132:135], v[202:205], v[76:79]
	v_mfma_f32_16x16x32_bf16 v[72:75], v[162:165], v[202:205], v[72:75]
	v_mfma_f32_16x16x32_bf16 v[68:71], v[132:135], v[210:213], v[68:71]
	v_mfma_f32_16x16x32_bf16 v[64:67], v[162:165], v[210:213], v[64:67]
	s_setprio 0
	s_setprio 1
	v_mfma_f32_16x16x32_bf16 v[28:31], v[166:169], v[182:185], v[28:31]
	v_mfma_f32_16x16x32_bf16 v[24:27], v[174:177], v[182:185], v[24:27]
	v_mfma_f32_16x16x32_bf16 v[20:23], v[166:169], v[190:193], v[20:23]
	v_mfma_f32_16x16x32_bf16 v[16:19], v[174:177], v[190:193], v[16:19]
	v_mfma_f32_16x16x32_bf16 v[12:15], v[166:169], v[198:201], v[12:15]
	v_mfma_f32_16x16x32_bf16 v[8:11], v[174:177], v[198:201], v[8:11]
	v_mfma_f32_16x16x32_bf16 v[4:7], v[166:169], v[206:209], v[4:7]
	v_mfma_f32_16x16x32_bf16 v[0:3], v[174:177], v[206:209], v[0:3]
	v_mfma_f32_16x16x32_bf16 v[28:31], v[170:173], v[186:189], v[28:31]
	v_mfma_f32_16x16x32_bf16 v[24:27], v[178:181], v[186:189], v[24:27]
	v_mfma_f32_16x16x32_bf16 v[20:23], v[170:173], v[194:197], v[20:23]
	v_mfma_f32_16x16x32_bf16 v[16:19], v[178:181], v[194:197], v[16:19]
	v_mfma_f32_16x16x32_bf16 v[12:15], v[170:173], v[202:205], v[12:15]
	s_setprio 2
	s_barrier
	v_mfma_f32_16x16x32_bf16 v[8:11], v[178:181], v[202:205], v[8:11]
	v_mfma_f32_16x16x32_bf16 v[4:7], v[170:173], v[210:213], v[4:7]
	v_mfma_f32_16x16x32_bf16 v[0:3], v[178:181], v[210:213], v[0:3]
	s_setprio 0
	s_add_i32 s56, 0, 0x18000
	s_add_i32 s57, 0, 0x1c000
	v_add_u32_e32 v162, s56, v228
	v_add_u32_e32 v178, s57, v228
	ds_read_b128 v[128:131], v162
	ds_read_b128 v[132:135], v162 offset:1024
	ds_read_b128 v[158:161], v162 offset:2048
	ds_read_b128 v[162:165], v162 offset:3072
	ds_read_b128 v[166:169], v178
	ds_read_b128 v[170:173], v178 offset:1024
	ds_read_b128 v[174:177], v178 offset:2048
	ds_read_b128 v[178:181], v178 offset:3072
	s_add_u32 s52, s80, 0x80000
	s_addc_u32 s53, s81, 0
	s_mov_b32 m0, s33
	v_lshl_add_u64 v[234:235], s[52:53], 0, v[136:137]
	ds_read_b128 v[182:185], v232 offset:32768
	ds_read_b128 v[186:189], v232 offset:33792
	ds_read_b128 v[190:193], v232 offset:34816
	ds_read_b128 v[194:197], v232 offset:35840
	ds_read_b128 v[198:201], v232 offset:36864
	ds_read_b128 v[202:205], v232 offset:37888
	ds_read_b128 v[206:209], v232 offset:38912
	ds_read_b128 v[210:213], v232 offset:39936
	global_load_lds_dwordx4 v[234:235], off
	s_mov_b32 m0, s38
	v_lshl_add_u64 v[234:235], s[52:53], 0, v[140:141]
	global_load_lds_dwordx4 v[234:235], off
	s_waitcnt vmcnt(8)
	s_waitcnt lgkmcnt(0)
	s_setprio 1
	s_barrier
	v_mfma_f32_16x16x32_bf16 v[124:127], v[128:131], v[182:185], v[124:127]
	v_mfma_f32_16x16x32_bf16 v[120:123], v[158:161], v[182:185], v[120:123]
	v_mfma_f32_16x16x32_bf16 v[116:119], v[128:131], v[190:193], v[116:119]
	v_mfma_f32_16x16x32_bf16 v[112:115], v[158:161], v[190:193], v[112:115]
	v_mfma_f32_16x16x32_bf16 v[108:111], v[128:131], v[198:201], v[108:111]
	v_mfma_f32_16x16x32_bf16 v[104:107], v[158:161], v[198:201], v[104:107]
	v_mfma_f32_16x16x32_bf16 v[100:103], v[128:131], v[206:209], v[100:103]
	v_mfma_f32_16x16x32_bf16 v[96:99], v[158:161], v[206:209], v[96:99]
	v_mfma_f32_16x16x32_bf16 v[124:127], v[132:135], v[186:189], v[124:127]
	v_mfma_f32_16x16x32_bf16 v[120:123], v[162:165], v[186:189], v[120:123]
	v_mfma_f32_16x16x32_bf16 v[116:119], v[132:135], v[194:197], v[116:119]
	v_mfma_f32_16x16x32_bf16 v[112:115], v[162:165], v[194:197], v[112:115]
	v_mfma_f32_16x16x32_bf16 v[108:111], v[132:135], v[202:205], v[108:111]
	v_mfma_f32_16x16x32_bf16 v[104:107], v[162:165], v[202:205], v[104:107]
	v_mfma_f32_16x16x32_bf16 v[100:103], v[132:135], v[210:213], v[100:103]
	v_mfma_f32_16x16x32_bf16 v[96:99], v[162:165], v[210:213], v[96:99]
	s_setprio 0
	s_setprio 1
	v_mfma_f32_16x16x32_bf16 v[60:63], v[166:169], v[182:185], v[60:63]
	v_mfma_f32_16x16x32_bf16 v[56:59], v[174:177], v[182:185], v[56:59]
	v_mfma_f32_16x16x32_bf16 v[52:55], v[166:169], v[190:193], v[52:55]
	v_mfma_f32_16x16x32_bf16 v[48:51], v[174:177], v[190:193], v[48:51]
	v_mfma_f32_16x16x32_bf16 v[44:47], v[166:169], v[198:201], v[44:47]
	v_mfma_f32_16x16x32_bf16 v[40:43], v[174:177], v[198:201], v[40:43]
	v_mfma_f32_16x16x32_bf16 v[36:39], v[166:169], v[206:209], v[36:39]
	v_mfma_f32_16x16x32_bf16 v[32:35], v[174:177], v[206:209], v[32:35]
	v_mfma_f32_16x16x32_bf16 v[60:63], v[170:173], v[186:189], v[60:63]
	v_mfma_f32_16x16x32_bf16 v[56:59], v[178:181], v[186:189], v[56:59]
	v_mfma_f32_16x16x32_bf16 v[52:55], v[170:173], v[194:197], v[52:55]
	v_mfma_f32_16x16x32_bf16 v[48:51], v[178:181], v[194:197], v[48:51]
	v_mfma_f32_16x16x32_bf16 v[44:47], v[170:173], v[202:205], v[44:47]
	s_setprio 2
	s_barrier
; #define PG8_STAGE(bufoff, gbase, voff) do { _Pragma("unroll") for (int _i = 0; _i < 2; ++_i) \
;         __builtin_amdgcn_global_load_lds((const unsigned*)((const char*)(gbase) + (voff)[_i]), (PG8_LAS unsigned*)(lds + (bufoff) + ldsw + _i * 8192), 16, 0, 0); } while (0)
; #define PG8_LDA(dst, b, h) do { _Pragma("unroll") for (int m = 0; m < 4; ++m) _Pragma("unroll") for (int k = 0; k < 2; ++k) dst[m][k] = *(const PG8_LAS bf16x8*)(lds + PG8_SA(b, h) + aoff + m * 2048 + k * 1024); } while (0)
; #define PG8_MMA(ai, bj, At, Bt) do { __builtin_amdgcn_s_setprio(1); _Pragma("unroll") for (int m = 0; m < 4; ++m) _Pragma("unroll") for (int n = 0; n < 2; ++n) _Pragma("unroll") for (int k = 0; k < 2; ++k) \
;         acc[ai][bj][m][n] = __builtin_amdgcn_mfma_f32_16x16x32_bf16(Bt[n][k], At[m][k], acc[ai][bj][m][n], 0, 0, 0); __builtin_amdgcn_s_setprio(0); } while (0)
; #define PG8_WAIT_V(n) asm volatile("s_waitcnt vmcnt(" #n ")" ::: "memory")
; #define PG8_WAIT_L(n) asm volatile("s_waitcnt lgkmcnt(" #n ")" ::: "memory")
; #define PG8_BAR __builtin_amdgcn_s_barrier()
; #define PG8_SCHED __builtin_amdgcn_sched_barrier(0)
; template <class Epi, class Sched, bool ALIGN_EPI = false, bool SP2 = false>
; __device__ __forceinline__ void gemm_phase(PG8_LAS unsigned char* lds, const Gemm g, const Sched& S, const Epi& E) {
;     ...
;             PG8_WAIT_V(8); PG8_WAIT_L(0); PG8_BAR; PG8_MMA(0, 0, At, B0); PG8_MMA(0, 1, At, B1); PG8_BAR; PG8_SCHED;
;             PG8_LDA(At, 1, 1); PG8_STAGE(PG8_SB(1, 0), b3, voffB); PG8_STAGE(PG8_SB(1, 1), b3 + hstep, voffB); PG8_STAGE(PG8_SA(1, 0), a3, voffA);
;             PG8_WAIT_V(8); PG8_WAIT_L(0); PG8_BAR; PG8_MMA(1, 0, At, B0); PG8_MMA(1, 1, At, B1); PG8_BAR; PG8_SCHED;
	v_mfma_f32_16x16x32_bf16 v[40:43], v[178:181], v[202:205], v[40:43]
	v_mfma_f32_16x16x32_bf16 v[36:39], v[170:173], v[210:213], v[36:39]
	v_mfma_f32_16x16x32_bf16 v[32:35], v[178:181], v[210:213], v[32:35]
	s_setprio 0
	s_add_i32 s52, s56, s3
	v_lshl_add_u64 v[214:215], v[214:215], 0, s[14:15]
	s_mov_b32 m0, s52
	ds_read_b128 v[182:185], v232 offset:49152
	ds_read_b128 v[186:189], v232 offset:50176
	ds_read_b128 v[190:193], v232 offset:51200
	ds_read_b128 v[194:197], v232 offset:52224
	ds_read_b128 v[198:201], v232 offset:53248
	ds_read_b128 v[202:205], v232 offset:54272
	ds_read_b128 v[206:209], v232 offset:55296
	ds_read_b128 v[210:213], v232 offset:56320
	global_load_lds_dwordx4 v[214:215], off
	s_add_i32 m0, s52, 0x2000
	s_add_u32 s52, s78, 0x80080
	v_lshl_add_u64 v[214:215], v[216:217], 0, s[14:15]
	s_addc_u32 s53, s79, 0
	s_add_i32 s56, s57, s3
	global_load_lds_dwordx4 v[214:215], off
	s_mov_b32 m0, s56
	v_lshl_add_u64 v[214:215], s[52:53], 0, v[138:139]
	global_load_lds_dwordx4 v[214:215], off
	s_add_i32 m0, s56, 0x2000
	v_lshl_add_u64 v[214:215], s[52:53], 0, v[142:143]
	global_load_lds_dwordx4 v[214:215], off
	s_mov_b32 m0, s88
	v_lshl_add_u64 v[214:215], v[218:219], 0, s[14:15]
	global_load_lds_dwordx4 v[214:215], off
	s_mov_b32 m0, s89
	v_lshl_add_u64 v[214:215], v[220:221], 0, s[14:15]
	global_load_lds_dwordx4 v[214:215], off
	s_waitcnt vmcnt(8)
	s_waitcnt lgkmcnt(0)
	s_setprio 1
	s_barrier
	v_mfma_f32_16x16x32_bf16 v[92:95], v[128:131], v[182:185], v[92:95]
	v_mfma_f32_16x16x32_bf16 v[88:91], v[158:161], v[182:185], v[88:91]
	v_mfma_f32_16x16x32_bf16 v[84:87], v[128:131], v[190:193], v[84:87]
	v_mfma_f32_16x16x32_bf16 v[80:83], v[158:161], v[190:193], v[80:83]
	v_mfma_f32_16x16x32_bf16 v[76:79], v[128:131], v[198:201], v[76:79]
	v_mfma_f32_16x16x32_bf16 v[72:75], v[158:161], v[198:201], v[72:75]
	v_mfma_f32_16x16x32_bf16 v[68:71], v[128:131], v[206:209], v[68:71]
	v_mfma_f32_16x16x32_bf16 v[64:67], v[158:161], v[206:209], v[64:67]
	v_mfma_f32_16x16x32_bf16 v[92:95], v[132:135], v[186:189], v[92:95]
	v_mfma_f32_16x16x32_bf16 v[88:91], v[162:165], v[186:189], v[88:91]
	v_mfma_f32_16x16x32_bf16 v[84:87], v[132:135], v[194:197], v[84:87]
	v_mfma_f32_16x16x32_bf16 v[80:83], v[162:165], v[194:197], v[80:83]
	v_mfma_f32_16x16x32_bf16 v[76:79], v[132:135], v[202:205], v[76:79]
	v_mfma_f32_16x16x32_bf16 v[72:75], v[162:165], v[202:205], v[72:75]
	v_mfma_f32_16x16x32_bf16 v[68:71], v[132:135], v[210:213], v[68:71]
	v_mfma_f32_16x16x32_bf16 v[64:67], v[162:165], v[210:213], v[64:67]
	s_setprio 0
	s_setprio 1
	v_mfma_f32_16x16x32_bf16 v[28:31], v[166:169], v[182:185], v[28:31]
	v_mfma_f32_16x16x32_bf16 v[24:27], v[174:177], v[182:185], v[24:27]
	v_mfma_f32_16x16x32_bf16 v[20:23], v[166:169], v[190:193], v[20:23]
	v_mfma_f32_16x16x32_bf16 v[16:19], v[174:177], v[190:193], v[16:19]
	v_mfma_f32_16x16x32_bf16 v[12:15], v[166:169], v[198:201], v[12:15]
	v_mfma_f32_16x16x32_bf16 v[8:11], v[174:177], v[198:201], v[8:11]
	v_mfma_f32_16x16x32_bf16 v[4:7], v[166:169], v[206:209], v[4:7]
	v_mfma_f32_16x16x32_bf16 v[0:3], v[174:177], v[206:209], v[0:3]
	v_mfma_f32_16x16x32_bf16 v[28:31], v[170:173], v[186:189], v[28:31]
	v_mfma_f32_16x16x32_bf16 v[24:27], v[178:181], v[186:189], v[24:27]
	v_mfma_f32_16x16x32_bf16 v[20:23], v[170:173], v[194:197], v[20:23]
	v_mfma_f32_16x16x32_bf16 v[16:19], v[178:181], v[194:197], v[16:19]
	v_mfma_f32_16x16x32_bf16 v[12:15], v[170:173], v[202:205], v[12:15]
	s_setprio 2
	s_barrier
	v_mfma_f32_16x16x32_bf16 v[8:11], v[178:181], v[202:205], v[8:11]
	v_mfma_f32_16x16x32_bf16 v[4:7], v[170:173], v[210:213], v[4:7]
	v_mfma_f32_16x16x32_bf16 v[0:3], v[178:181], v[210:213], v[0:3]
	s_setprio 0
	s_add_i32 vcc_hi, vcc_hi, 2
	s_add_u32 s76, s76, 0x100
	s_addc_u32 s77, s77, 0
	s_add_u32 s75, s75, 0x100
	s_addc_u32 vcc_lo, vcc_lo, 0
	s_cmp_gt_u32 vcc_hi, 29
	s_cbranch_scc0 .LBB0_374
	s_and_b64 vcc, exec, s[48:49]
	s_cbranch_vccz .LBB0_377
	s_barrier

; #define PG8_STAGE(bufoff, gbase, voff) do { _Pragma("unroll") for (int _i = 0; _i < 2; ++_i) \
;         __builtin_amdgcn_global_load_lds((const unsigned*)((const char*)(gbase) + (voff)[_i]), (PG8_LAS unsigned*)(lds + (bufoff) + ldsw + _i * 8192), 16, 0, 0); } while (0)
; #define PG8_LDA(dst, b, h) do { _Pragma("unroll") for (int m = 0; m < 4; ++m) _Pragma("unroll") for (int k = 0; k < 2; ++k) dst[m][k] = *(const PG8_LAS bf16x8*)(lds + PG8_SA(b, h) + aoff + m * 2048 + k * 1024); } while (0)
; #define PG8_LDB(dst, b, h) do { _Pragma("unroll") for (int n = 0; n < 2; ++n) _Pragma("unroll") for (int k = 0; k < 2; ++k) dst[n][k] = *(const PG8_LAS bf16x8*)(lds + PG8_SB(b, h) + boff + n * 2048 + k * 1024); } while (0)
; #define PG8_MMA(ai, bj, At, Bt) do { __builtin_amdgcn_s_setprio(1); _Pragma("unroll") for (int m = 0; m < 4; ++m) _Pragma("unroll") for (int n = 0; n < 2; ++n) _Pragma("unroll") for (int k = 0; k < 2; ++k) \
;         acc[ai][bj][m][n] = __builtin_amdgcn_mfma_f32_16x16x32_bf16(Bt[n][k], At[m][k], acc[ai][bj][m][n], 0, 0, 0); __builtin_amdgcn_s_setprio(0); } while (0)
; #define PG8_WAIT_V(n) asm volatile("s_waitcnt vmcnt(" #n ")" ::: "memory")
; #define PG8_WAIT_L(n) asm volatile("s_waitcnt lgkmcnt(" #n ")" ::: "memory")
; #define PG8_BAR __builtin_amdgcn_s_barrier()
; template <class Epi, class Sched, bool ALIGN_EPI = false, bool SP2 = false>
; __device__ __forceinline__ void gemm_phase(PG8_LAS unsigned char* lds, const Gemm g, const Sched& S, const Epi& E) {
;     ...
;             const bool last = (t == nt - 2);
;             const char* a1 = cA + (size_t)(t + 1) * kstep;
;             const char* a2 = last ? nA : cA + (size_t)(t + 2) * kstep; const char* b2 = last ? nB : cB + (size_t)(t + 2) * kstep;
;             const char* a3 = a2 + kstep; const char* b3 = b2 + kstep;
;             if constexpr (SP2) {
;             PG8_LDB(B0, 0, 0); PG8_LDB(B1, 0, 1); PG8_SCHED; PG8_LDA(At, 0, 0); PG8_STAGE(PG8_SA(1, 1), a1 + hstep, voffA);
;             PG8_WAIT_V(8); PG8_WAIT_L(0); PG8_BAR; PG8_MMA(0, 0, At, B0); PG8_MMA(0, 1, At, B1); PG8_BAR; PG8_SCHED;
;             PG8_LDA(At, 0, 1); PG8_STAGE(PG8_SB(0, 0), b2, voffB); PG8_STAGE(PG8_SB(0, 1), b2 + hstep, voffB); PG8_STAGE(PG8_SA(0, 0), a2, voffA);
;             PG8_WAIT_V(8); PG8_WAIT_L(0); PG8_BAR; PG8_MMA(1, 0, At, B0); PG8_MMA(1, 1, At, B1); PG8_BAR; PG8_SCHED;
.LBB0_410:
	ds_read_b128 v[166:169], v145
	ds_read_b128 v[170:173], v145 offset:1024
	ds_read_b128 v[174:177], v145 offset:2048
	ds_read_b128 v[178:181], v145 offset:3072
	ds_read_b128 v[182:185], v149
	ds_read_b128 v[186:189], v149 offset:1024
	ds_read_b128 v[190:193], v149 offset:2048
	ds_read_b128 v[194:197], v149 offset:3072
	s_add_u32 s52, s74, 0xfff80080
	s_addc_u32 s53, s75, -1
	s_cmp_eq_u32 s51, 4
	s_cselect_b32 s79, s55, s53
	s_cselect_b32 s78, s54, s52
	s_cselect_b32 s77, s69, s49
	s_cselect_b32 s76, s68, s37
	s_mov_b32 m0, s80
	v_lshl_add_u64 v[230:231], s[74:75], 0, v[160:161]
	ds_read_b128 v[198:201], v164
	ds_read_b128 v[202:205], v164 offset:1024
	ds_read_b128 v[206:209], v164 offset:2048
	ds_read_b128 v[210:213], v164 offset:3072
	ds_read_b128 v[214:217], v164 offset:4096
	ds_read_b128 v[218:221], v164 offset:5120
	ds_read_b128 v[222:225], v164 offset:6144
	ds_read_b128 v[226:229], v164 offset:7168
	global_load_lds_dwordx4 v[230:231], off
	s_mov_b32 m0, s81
	v_lshl_add_u64 v[230:231], s[74:75], 0, v[162:163]
	global_load_lds_dwordx4 v[230:231], off
	s_waitcnt vmcnt(8)
	s_waitcnt lgkmcnt(0)
	s_setprio 1
	s_barrier
	v_mfma_f32_16x16x32_bf16 v[124:127], v[166:169], v[198:201], v[124:127]
	v_mfma_f32_16x16x32_bf16 v[120:123], v[174:177], v[198:201], v[120:123]
	v_mfma_f32_16x16x32_bf16 v[116:119], v[166:169], v[206:209], v[116:119]
	v_mfma_f32_16x16x32_bf16 v[108:111], v[174:177], v[206:209], v[108:111]
	v_mfma_f32_16x16x32_bf16 v[100:103], v[166:169], v[214:217], v[100:103]
	v_mfma_f32_16x16x32_bf16 v[92:95], v[174:177], v[214:217], v[92:95]
	v_mfma_f32_16x16x32_bf16 v[84:87], v[166:169], v[222:225], v[84:87]
	v_mfma_f32_16x16x32_bf16 v[76:79], v[174:177], v[222:225], v[76:79]
	v_mfma_f32_16x16x32_bf16 v[124:127], v[170:173], v[202:205], v[124:127]
	v_mfma_f32_16x16x32_bf16 v[120:123], v[178:181], v[202:205], v[120:123]
	v_mfma_f32_16x16x32_bf16 v[116:119], v[170:173], v[210:213], v[116:119]
	v_mfma_f32_16x16x32_bf16 v[108:111], v[178:181], v[210:213], v[108:111]
	v_mfma_f32_16x16x32_bf16 v[100:103], v[170:173], v[218:221], v[100:103]
	v_mfma_f32_16x16x32_bf16 v[92:95], v[178:181], v[218:221], v[92:95]
	v_mfma_f32_16x16x32_bf16 v[84:87], v[170:173], v[226:229], v[84:87]
	v_mfma_f32_16x16x32_bf16 v[76:79], v[178:181], v[226:229], v[76:79]
	s_setprio 0
	s_setprio 1
	v_mfma_f32_16x16x32_bf16 v[112:115], v[182:185], v[198:201], v[112:115]
	v_mfma_f32_16x16x32_bf16 v[104:107], v[190:193], v[198:201], v[104:107]
	v_mfma_f32_16x16x32_bf16 v[96:99], v[182:185], v[206:209], v[96:99]
	v_mfma_f32_16x16x32_bf16 v[88:91], v[190:193], v[206:209], v[88:91]
	v_mfma_f32_16x16x32_bf16 v[80:83], v[182:185], v[214:217], v[80:83]
	v_mfma_f32_16x16x32_bf16 v[72:75], v[190:193], v[214:217], v[72:75]
	v_mfma_f32_16x16x32_bf16 v[68:71], v[182:185], v[222:225], v[68:71]
	v_mfma_f32_16x16x32_bf16 v[64:67], v[190:193], v[222:225], v[64:67]
	v_mfma_f32_16x16x32_bf16 v[112:115], v[186:189], v[202:205], v[112:115]
	v_mfma_f32_16x16x32_bf16 v[104:107], v[194:197], v[202:205], v[104:107]
	v_mfma_f32_16x16x32_bf16 v[96:99], v[186:189], v[210:213], v[96:99]
	v_mfma_f32_16x16x32_bf16 v[88:91], v[194:197], v[210:213], v[88:91]
	v_mfma_f32_16x16x32_bf16 v[80:83], v[186:189], v[218:221], v[80:83]
	s_setprio 2
	s_barrier
	v_mfma_f32_16x16x32_bf16 v[72:75], v[194:197], v[218:221], v[72:75]
	v_mfma_f32_16x16x32_bf16 v[68:71], v[186:189], v[226:229], v[68:71]
	v_mfma_f32_16x16x32_bf16 v[64:67], v[194:197], v[226:229], v[64:67]
	s_setprio 0
	s_mov_b32 m0, s84
	v_lshl_add_u64 v[230:231], s[76:77], 0, v[138:139]
	s_add_u32 s52, s76, 0x80000
	ds_read_b128 v[198:201], v164 offset:16384
	ds_read_b128 v[202:205], v164 offset:17408
	ds_read_b128 v[206:209], v164 offset:18432
	ds_read_b128 v[210:213], v164 offset:19456
	ds_read_b128 v[214:217], v164 offset:20480
	ds_read_b128 v[218:221], v164 offset:21504
	ds_read_b128 v[222:225], v164 offset:22528
	ds_read_b128 v[226:229], v164 offset:23552
	global_load_lds_dwordx4 v[230:231], off
	v_lshl_add_u64 v[232:233], s[76:77], 0, v[142:143]
	s_mov_b32 m0, s85
	s_addc_u32 s53, s77, 0
	global_load_lds_dwordx4 v[232:233], off
	v_lshl_add_u64 v[234:235], s[52:53], 0, v[138:139]
	s_mov_b32 m0, s86
	v_lshl_add_u64 v[236:237], s[78:79], 0, v[140:141]
	global_load_lds_dwordx4 v[234:235], off
	s_mov_b32 m0, s87
	v_lshl_add_u64 v[234:235], s[52:53], 0, v[142:143]
	global_load_lds_dwordx4 v[234:235], off
	s_mov_b32 m0, s10
	v_lshl_add_u64 v[234:235], s[78:79], 0, v[136:137]
	global_load_lds_dwordx4 v[234:235], off
	s_mov_b32 m0, s11
	s_nop 0
	global_load_lds_dwordx4 v[236:237], off
	s_waitcnt vmcnt(8)
	s_waitcnt lgkmcnt(0)
	s_setprio 1
	s_barrier
; #define PG8_STAGE(bufoff, gbase, voff) do { _Pragma("unroll") for (int _i = 0; _i < 2; ++_i) \
;         __builtin_amdgcn_global_load_lds((const unsigned*)((const char*)(gbase) + (voff)[_i]), (PG8_LAS unsigned*)(lds + (bufoff) + ldsw + _i * 8192), 16, 0, 0); } while (0)
; #define PG8_LDA(dst, b, h) do { _Pragma("unroll") for (int m = 0; m < 4; ++m) _Pragma("unroll") for (int k = 0; k < 2; ++k) dst[m][k] = *(const PG8_LAS bf16x8*)(lds + PG8_SA(b, h) + aoff + m * 2048 + k * 1024); } while (0)
; #define PG8_LDB(dst, b, h) do { _Pragma("unroll") for (int n = 0; n < 2; ++n) _Pragma("unroll") for (int k = 0; k < 2; ++k) dst[n][k] = *(const PG8_LAS bf16x8*)(lds + PG8_SB(b, h) + boff + n * 2048 + k * 1024); } while (0)
; #define PG8_MMA(ai, bj, At, Bt) do { __builtin_amdgcn_s_setprio(1); _Pragma("unroll") for (int m = 0; m < 4; ++m) _Pragma("unroll") for (int n = 0; n < 2; ++n) _Pragma("unroll") for (int k = 0; k < 2; ++k) \
;         acc[ai][bj][m][n] = __builtin_amdgcn_mfma_f32_16x16x32_bf16(Bt[n][k], At[m][k], acc[ai][bj][m][n], 0, 0, 0); __builtin_amdgcn_s_setprio(0); } while (0)
; #define PG8_WAIT_V(n) asm volatile("s_waitcnt vmcnt(" #n ")" ::: "memory")
; #define PG8_WAIT_L(n) asm volatile("s_waitcnt lgkmcnt(" #n ")" ::: "memory")
; #define PG8_BAR __builtin_amdgcn_s_barrier()
; #define PG8_SCHED __builtin_amdgcn_sched_barrier(0)
; template <class Epi, class Sched, bool ALIGN_EPI = false, bool SP2 = false>
; __device__ __forceinline__ void gemm_phase(PG8_LAS unsigned char* lds, const Gemm g, const Sched& S, const Epi& E) {
;     ...
;             PG8_LDB(B0, 0, 0); PG8_LDB(B1, 0, 1); PG8_SCHED; PG8_LDA(At, 0, 0); PG8_STAGE(PG8_SA(1, 1), a1 + hstep, voffA);
;             PG8_WAIT_V(8); PG8_WAIT_L(0); PG8_BAR; PG8_MMA(0, 0, At, B0); PG8_MMA(0, 1, At, B1); PG8_BAR; PG8_SCHED;
;             PG8_LDA(At, 0, 1); PG8_STAGE(PG8_SB(0, 0), b2, voffB); PG8_STAGE(PG8_SB(0, 1), b2 + hstep, voffB); PG8_STAGE(PG8_SA(0, 0), a2, voffA);
;             PG8_WAIT_V(8); PG8_WAIT_L(0); PG8_BAR; PG8_MMA(1, 0, At, B0); PG8_MMA(1, 1, At, B1); PG8_BAR; PG8_SCHED;
;             PG8_LDB(B0, 1, 0); PG8_LDB(B1, 1, 1); PG8_SCHED; PG8_LDA(At, 1, 0); PG8_STAGE(PG8_SA(0, 1), a2 + hstep, voffA);
;             PG8_WAIT_V(8); PG8_WAIT_L(0); PG8_BAR; PG8_MMA(0, 0, At, B0); PG8_MMA(0, 1, At, B1); PG8_BAR; PG8_SCHED;
	v_mfma_f32_16x16x32_bf16 v[60:63], v[166:169], v[198:201], v[60:63]
	v_mfma_f32_16x16x32_bf16 v[56:59], v[174:177], v[198:201], v[56:59]
	v_mfma_f32_16x16x32_bf16 v[52:55], v[166:169], v[206:209], v[52:55]
	v_mfma_f32_16x16x32_bf16 v[44:47], v[174:177], v[206:209], v[44:47]
	v_mfma_f32_16x16x32_bf16 v[36:39], v[166:169], v[214:217], v[36:39]
	v_mfma_f32_16x16x32_bf16 v[28:31], v[174:177], v[214:217], v[28:31]
	v_mfma_f32_16x16x32_bf16 v[20:23], v[166:169], v[222:225], v[20:23]
	v_mfma_f32_16x16x32_bf16 v[12:15], v[174:177], v[222:225], v[12:15]
	v_mfma_f32_16x16x32_bf16 v[60:63], v[170:173], v[202:205], v[60:63]
	v_mfma_f32_16x16x32_bf16 v[56:59], v[178:181], v[202:205], v[56:59]
	v_mfma_f32_16x16x32_bf16 v[52:55], v[170:173], v[210:213], v[52:55]
	v_mfma_f32_16x16x32_bf16 v[44:47], v[178:181], v[210:213], v[44:47]
	v_mfma_f32_16x16x32_bf16 v[36:39], v[170:173], v[218:221], v[36:39]
	v_mfma_f32_16x16x32_bf16 v[28:31], v[178:181], v[218:221], v[28:31]
	v_mfma_f32_16x16x32_bf16 v[20:23], v[170:173], v[226:229], v[20:23]
	v_mfma_f32_16x16x32_bf16 v[12:15], v[178:181], v[226:229], v[12:15]
	s_setprio 0
	s_setprio 1
	v_mfma_f32_16x16x32_bf16 v[48:51], v[182:185], v[198:201], v[48:51]
	v_mfma_f32_16x16x32_bf16 v[40:43], v[190:193], v[198:201], v[40:43]
	v_mfma_f32_16x16x32_bf16 v[32:35], v[182:185], v[206:209], v[32:35]
	v_mfma_f32_16x16x32_bf16 v[24:27], v[190:193], v[206:209], v[24:27]
	v_mfma_f32_16x16x32_bf16 v[16:19], v[182:185], v[214:217], v[16:19]
	v_mfma_f32_16x16x32_bf16 v[8:11], v[190:193], v[214:217], v[8:11]
	v_mfma_f32_16x16x32_bf16 v[4:7], v[182:185], v[222:225], v[4:7]
	v_mfma_f32_16x16x32_bf16 v[0:3], v[190:193], v[222:225], v[0:3]
	v_mfma_f32_16x16x32_bf16 v[48:51], v[186:189], v[202:205], v[48:51]
	v_mfma_f32_16x16x32_bf16 v[40:43], v[194:197], v[202:205], v[40:43]
	v_mfma_f32_16x16x32_bf16 v[32:35], v[186:189], v[210:213], v[32:35]
	v_mfma_f32_16x16x32_bf16 v[24:27], v[194:197], v[210:213], v[24:27]
	v_mfma_f32_16x16x32_bf16 v[16:19], v[186:189], v[218:221], v[16:19]
	s_setprio 2
	s_barrier
	v_mfma_f32_16x16x32_bf16 v[8:11], v[194:197], v[218:221], v[8:11]
	v_mfma_f32_16x16x32_bf16 v[4:7], v[186:189], v[226:229], v[4:7]
	v_mfma_f32_16x16x32_bf16 v[0:3], v[194:197], v[226:229], v[0:3]
	s_setprio 0
	ds_read_b128 v[166:169], v148
	ds_read_b128 v[170:173], v148 offset:1024
	ds_read_b128 v[174:177], v148 offset:2048
	ds_read_b128 v[178:181], v148 offset:3072
	ds_read_b128 v[182:185], v165
	ds_read_b128 v[186:189], v165 offset:1024
	ds_read_b128 v[190:193], v165 offset:2048
	ds_read_b128 v[194:197], v165 offset:3072
	s_add_u32 s52, s78, 0x80000
	s_addc_u32 s53, s79, 0
	s_mov_b32 m0, s28
	v_lshl_add_u64 v[238:239], s[52:53], 0, v[136:137]
	ds_read_b128 v[198:201], v164 offset:32768
	ds_read_b128 v[202:205], v164 offset:33792
	ds_read_b128 v[206:209], v164 offset:34816
	ds_read_b128 v[210:213], v164 offset:35840
	ds_read_b128 v[214:217], v164 offset:36864
	ds_read_b128 v[218:221], v164 offset:37888
	ds_read_b128 v[222:225], v164 offset:38912
	ds_read_b128 v[226:229], v164 offset:39936
	global_load_lds_dwordx4 v[238:239], off
	s_mov_b32 m0, s29
	v_lshl_add_u64 v[238:239], s[52:53], 0, v[140:141]
	global_load_lds_dwordx4 v[238:239], off
	s_waitcnt vmcnt(8)
	s_waitcnt lgkmcnt(0)
	s_setprio 1
	s_barrier
	v_mfma_f32_16x16x32_bf16 v[124:127], v[166:169], v[198:201], v[124:127]
	v_mfma_f32_16x16x32_bf16 v[120:123], v[174:177], v[198:201], v[120:123]
	v_mfma_f32_16x16x32_bf16 v[116:119], v[166:169], v[206:209], v[116:119]
	v_mfma_f32_16x16x32_bf16 v[108:111], v[174:177], v[206:209], v[108:111]
	v_mfma_f32_16x16x32_bf16 v[100:103], v[166:169], v[214:217], v[100:103]
	v_mfma_f32_16x16x32_bf16 v[92:95], v[174:177], v[214:217], v[92:95]
	v_mfma_f32_16x16x32_bf16 v[84:87], v[166:169], v[222:225], v[84:87]
	v_mfma_f32_16x16x32_bf16 v[76:79], v[174:177], v[222:225], v[76:79]
	v_mfma_f32_16x16x32_bf16 v[124:127], v[170:173], v[202:205], v[124:127]
	v_mfma_f32_16x16x32_bf16 v[120:123], v[178:181], v[202:205], v[120:123]
	v_mfma_f32_16x16x32_bf16 v[116:119], v[170:173], v[210:213], v[116:119]
	v_mfma_f32_16x16x32_bf16 v[108:111], v[178:181], v[210:213], v[108:111]
	v_mfma_f32_16x16x32_bf16 v[100:103], v[170:173], v[218:221], v[100:103]
	v_mfma_f32_16x16x32_bf16 v[92:95], v[178:181], v[218:221], v[92:95]
	v_mfma_f32_16x16x32_bf16 v[84:87], v[170:173], v[226:229], v[84:87]
	v_mfma_f32_16x16x32_bf16 v[76:79], v[178:181], v[226:229], v[76:79]
	s_setprio 0
	s_setprio 1
	v_mfma_f32_16x16x32_bf16 v[112:115], v[182:185], v[198:201], v[112:115]
	v_mfma_f32_16x16x32_bf16 v[104:107], v[190:193], v[198:201], v[104:107]
	v_mfma_f32_16x16x32_bf16 v[96:99], v[182:185], v[206:209], v[96:99]
	v_mfma_f32_16x16x32_bf16 v[88:91], v[190:193], v[206:209], v[88:91]
	v_mfma_f32_16x16x32_bf16 v[80:83], v[182:185], v[214:217], v[80:83]
	v_mfma_f32_16x16x32_bf16 v[72:75], v[190:193], v[214:217], v[72:75]
	v_mfma_f32_16x16x32_bf16 v[68:71], v[182:185], v[222:225], v[68:71]
	v_mfma_f32_16x16x32_bf16 v[64:67], v[190:193], v[222:225], v[64:67]
	v_mfma_f32_16x16x32_bf16 v[112:115], v[186:189], v[202:205], v[112:115]
	v_mfma_f32_16x16x32_bf16 v[104:107], v[194:197], v[202:205], v[104:107]
	v_mfma_f32_16x16x32_bf16 v[96:99], v[186:189], v[210:213], v[96:99]
	v_mfma_f32_16x16x32_bf16 v[88:91], v[194:197], v[210:213], v[88:91]
	v_mfma_f32_16x16x32_bf16 v[80:83], v[186:189], v[218:221], v[80:83]
	s_setprio 2
	s_barrier
; #define PG8_STAGE(bufoff, gbase, voff) do { _Pragma("unroll") for (int _i = 0; _i < 2; ++_i) \
;         __builtin_amdgcn_global_load_lds((const unsigned*)((const char*)(gbase) + (voff)[_i]), (PG8_LAS unsigned*)(lds + (bufoff) + ldsw + _i * 8192), 16, 0, 0); } while (0)
; #define PG8_LDA(dst, b, h) do { _Pragma("unroll") for (int m = 0; m < 4; ++m) _Pragma("unroll") for (int k = 0; k < 2; ++k) dst[m][k] = *(const PG8_LAS bf16x8*)(lds + PG8_SA(b, h) + aoff + m * 2048 + k * 1024); } while (0)
; #define PG8_MMA(ai, bj, At, Bt) do { __builtin_amdgcn_s_setprio(1); _Pragma("unroll") for (int m = 0; m < 4; ++m) _Pragma("unroll") for (int n = 0; n < 2; ++n) _Pragma("unroll") for (int k = 0; k < 2; ++k) \
;         acc[ai][bj][m][n] = __builtin_amdgcn_mfma_f32_16x16x32_bf16(Bt[n][k], At[m][k], acc[ai][bj][m][n], 0, 0, 0); __builtin_amdgcn_s_setprio(0); } while (0)
; #define PG8_WAIT_V(n) asm volatile("s_waitcnt vmcnt(" #n ")" ::: "memory")
; #define PG8_WAIT_L(n) asm volatile("s_waitcnt lgkmcnt(" #n ")" ::: "memory")
; #define PG8_BAR __builtin_amdgcn_s_barrier()
; #define PG8_SCHED __builtin_amdgcn_sched_barrier(0)
; template <class Epi, class Sched, bool ALIGN_EPI = false, bool SP2 = false>
; __device__ __forceinline__ void gemm_phase(PG8_LAS unsigned char* lds, const Gemm g, const Sched& S, const Epi& E) {
;     ...
;             PG8_WAIT_V(8); PG8_WAIT_L(0); PG8_BAR; PG8_MMA(0, 0, At, B0); PG8_MMA(0, 1, At, B1); PG8_BAR; PG8_SCHED;
;             PG8_LDA(At, 1, 1); PG8_STAGE(PG8_SB(1, 0), b3, voffB); PG8_STAGE(PG8_SB(1, 1), b3 + hstep, voffB); PG8_STAGE(PG8_SA(1, 0), a3, voffA);
;             PG8_WAIT_V(8); PG8_WAIT_L(0); PG8_BAR; PG8_MMA(1, 0, At, B0); PG8_MMA(1, 1, At, B1); PG8_BAR; PG8_SCHED;
	v_mfma_f32_16x16x32_bf16 v[72:75], v[194:197], v[218:221], v[72:75]
	v_mfma_f32_16x16x32_bf16 v[68:71], v[186:189], v[226:229], v[68:71]
	v_mfma_f32_16x16x32_bf16 v[64:67], v[194:197], v[226:229], v[64:67]
	s_setprio 0
	s_mov_b32 m0, s89
	v_lshl_add_u64 v[230:231], v[230:231], 0, s[12:13]
	ds_read_b128 v[198:201], v164 offset:49152
	ds_read_b128 v[202:205], v164 offset:50176
	ds_read_b128 v[206:209], v164 offset:51200
	ds_read_b128 v[210:213], v164 offset:52224
	ds_read_b128 v[214:217], v164 offset:53248
	ds_read_b128 v[218:221], v164 offset:54272
	ds_read_b128 v[222:225], v164 offset:55296
	ds_read_b128 v[226:229], v164 offset:56320
	global_load_lds_dwordx4 v[230:231], off
	s_add_i32 m0, s89, 0x2000
	s_add_u32 s52, s76, 0x80080
	v_lshl_add_u64 v[230:231], v[232:233], 0, s[12:13]
	s_addc_u32 s53, s77, 0
	s_add_i32 s56, s88, s3
	global_load_lds_dwordx4 v[230:231], off
	s_mov_b32 m0, s56
	v_lshl_add_u64 v[230:231], s[52:53], 0, v[138:139]
	global_load_lds_dwordx4 v[230:231], off
	s_add_i32 m0, s56, 0x2000
	v_lshl_add_u64 v[230:231], s[52:53], 0, v[142:143]
	global_load_lds_dwordx4 v[230:231], off
	s_mov_b32 m0, s38
	v_lshl_add_u64 v[230:231], v[234:235], 0, s[12:13]
	global_load_lds_dwordx4 v[230:231], off
	s_mov_b32 m0, s39
	v_lshl_add_u64 v[230:231], v[236:237], 0, s[12:13]
	global_load_lds_dwordx4 v[230:231], off
	s_waitcnt vmcnt(8)
	s_waitcnt lgkmcnt(0)
	s_setprio 1
	s_barrier
	v_mfma_f32_16x16x32_bf16 v[60:63], v[166:169], v[198:201], v[60:63]
	v_mfma_f32_16x16x32_bf16 v[56:59], v[174:177], v[198:201], v[56:59]
	v_mfma_f32_16x16x32_bf16 v[52:55], v[166:169], v[206:209], v[52:55]
	v_mfma_f32_16x16x32_bf16 v[44:47], v[174:177], v[206:209], v[44:47]
	v_mfma_f32_16x16x32_bf16 v[36:39], v[166:169], v[214:217], v[36:39]
	v_mfma_f32_16x16x32_bf16 v[28:31], v[174:177], v[214:217], v[28:31]
	v_mfma_f32_16x16x32_bf16 v[20:23], v[166:169], v[222:225], v[20:23]
	v_mfma_f32_16x16x32_bf16 v[12:15], v[174:177], v[222:225], v[12:15]
	v_mfma_f32_16x16x32_bf16 v[60:63], v[170:173], v[202:205], v[60:63]
	v_mfma_f32_16x16x32_bf16 v[56:59], v[178:181], v[202:205], v[56:59]
	v_mfma_f32_16x16x32_bf16 v[52:55], v[170:173], v[210:213], v[52:55]
	v_mfma_f32_16x16x32_bf16 v[44:47], v[178:181], v[210:213], v[44:47]
	v_mfma_f32_16x16x32_bf16 v[36:39], v[170:173], v[218:221], v[36:39]
	v_mfma_f32_16x16x32_bf16 v[28:31], v[178:181], v[218:221], v[28:31]
	v_mfma_f32_16x16x32_bf16 v[20:23], v[170:173], v[226:229], v[20:23]
	v_mfma_f32_16x16x32_bf16 v[12:15], v[178:181], v[226:229], v[12:15]
	s_setprio 0
	s_setprio 1
	v_mfma_f32_16x16x32_bf16 v[48:51], v[182:185], v[198:201], v[48:51]
	v_mfma_f32_16x16x32_bf16 v[40:43], v[190:193], v[198:201], v[40:43]
	v_mfma_f32_16x16x32_bf16 v[32:35], v[182:185], v[206:209], v[32:35]
	v_mfma_f32_16x16x32_bf16 v[24:27], v[190:193], v[206:209], v[24:27]
	v_mfma_f32_16x16x32_bf16 v[16:19], v[182:185], v[214:217], v[16:19]
	v_mfma_f32_16x16x32_bf16 v[8:11], v[190:193], v[214:217], v[8:11]
	v_mfma_f32_16x16x32_bf16 v[4:7], v[182:185], v[222:225], v[4:7]
	v_mfma_f32_16x16x32_bf16 v[0:3], v[190:193], v[222:225], v[0:3]
	v_mfma_f32_16x16x32_bf16 v[48:51], v[186:189], v[202:205], v[48:51]
	v_mfma_f32_16x16x32_bf16 v[40:43], v[194:197], v[202:205], v[40:43]
	v_mfma_f32_16x16x32_bf16 v[32:35], v[186:189], v[210:213], v[32:35]
	v_mfma_f32_16x16x32_bf16 v[24:27], v[194:197], v[210:213], v[24:27]
	v_mfma_f32_16x16x32_bf16 v[16:19], v[186:189], v[218:221], v[16:19]
	s_setprio 2
	s_barrier
	v_mfma_f32_16x16x32_bf16 v[8:11], v[194:197], v[218:221], v[8:11]
	v_mfma_f32_16x16x32_bf16 v[4:7], v[186:189], v[226:229], v[4:7]
	v_mfma_f32_16x16x32_bf16 v[0:3], v[194:197], v[226:229], v[0:3]
	s_setprio 0
	s_add_i32 s51, s51, 2
	s_add_u32 s74, s74, 0x100
	s_addc_u32 s75, s75, 0
	s_add_u32 s37, s37, 0x100
	s_addc_u32 s49, s49, 0
	s_cmp_gt_u32 s51, 5
	s_cbranch_scc0 .LBB0_410
	s_and_b64 vcc, exec, s[14:15]
	s_cbranch_vccz .LBB0_413
	s_barrier

; #define PG8_STAGE(bufoff, gbase, voff) do { _Pragma("unroll") for (int _i = 0; _i < 2; ++_i) \
;         __builtin_amdgcn_global_load_lds((const unsigned*)((const char*)(gbase) + (voff)[_i]), (PG8_LAS unsigned*)(lds + (bufoff) + ldsw + _i * 8192), 16, 0, 0); } while (0)
; #define PG8_LDA(dst, b, h) do { _Pragma("unroll") for (int m = 0; m < 4; ++m) _Pragma("unroll") for (int k = 0; k < 2; ++k) dst[m][k] = *(const PG8_LAS bf16x8*)(lds + PG8_SA(b, h) + aoff + m * 2048 + k * 1024); } while (0)
; #define PG8_LDB(dst, b, h) do { _Pragma("unroll") for (int n = 0; n < 2; ++n) _Pragma("unroll") for (int k = 0; k < 2; ++k) dst[n][k] = *(const PG8_LAS bf16x8*)(lds + PG8_SB(b, h) + boff + n * 2048 + k * 1024); } while (0)
; #define PG8_MMA(ai, bj, At, Bt) do { __builtin_amdgcn_s_setprio(1); _Pragma("unroll") for (int m = 0; m < 4; ++m) _Pragma("unroll") for (int n = 0; n < 2; ++n) _Pragma("unroll") for (int k = 0; k < 2; ++k) \
;         acc[ai][bj][m][n] = __builtin_amdgcn_mfma_f32_16x16x32_bf16(Bt[n][k], At[m][k], acc[ai][bj][m][n], 0, 0, 0); __builtin_amdgcn_s_setprio(0); } while (0)
; #define PG8_WAIT_V(n) asm volatile("s_waitcnt vmcnt(" #n ")" ::: "memory")
; #define PG8_WAIT_L(n) asm volatile("s_waitcnt lgkmcnt(" #n ")" ::: "memory")
; #define PG8_BAR __builtin_amdgcn_s_barrier()
; template <class Epi, class Sched, bool ALIGN_EPI = false, bool SP2 = false>
; __device__ __forceinline__ void gemm_phase(PG8_LAS unsigned char* lds, const Gemm g, const Sched& S, const Epi& E) {
;     ...
;             const bool last = (t == nt - 2);
;             const char* a1 = cA + (size_t)(t + 1) * kstep;
;             const char* a2 = last ? nA : cA + (size_t)(t + 2) * kstep; const char* b2 = last ? nB : cB + (size_t)(t + 2) * kstep;
;             const char* a3 = a2 + kstep; const char* b3 = b2 + kstep;
;             if constexpr (SP2) {
;             PG8_LDB(B0, 0, 0); PG8_LDB(B1, 0, 1); PG8_SCHED; PG8_LDA(At, 0, 0); PG8_STAGE(PG8_SA(1, 1), a1 + hstep, voffA);
;             PG8_WAIT_V(8); PG8_WAIT_L(0); PG8_BAR; PG8_MMA(0, 0, At, B0); PG8_MMA(0, 1, At, B1); PG8_BAR; PG8_SCHED;
;             PG8_LDA(At, 0, 1); PG8_STAGE(PG8_SB(0, 0), b2, voffB); PG8_STAGE(PG8_SB(0, 1), b2 + hstep, voffB); PG8_STAGE(PG8_SA(0, 0), a2, voffA);
;             PG8_WAIT_V(8); PG8_WAIT_L(0); PG8_BAR; PG8_MMA(1, 0, At, B0); PG8_MMA(1, 1, At, B1); PG8_BAR; PG8_SCHED;
.LBB0_545:
	ds_read_b128 v[112:115], v174
	ds_read_b128 v[116:119], v174 offset:1024
	ds_read_b128 v[120:123], v174 offset:2048
	ds_read_b128 v[124:127], v174 offset:3072
	ds_read_b128 v[164:167], v175
	ds_read_b128 v[168:171], v175 offset:1024
	ds_read_b128 v[178:181], v175 offset:2048
	ds_read_b128 v[182:185], v175 offset:3072
	s_add_u32 s52, s68, 0xfff80080
	s_addc_u32 s53, s69, -1
	s_cmp_eq_u32 s88, 28
	s_cselect_b32 s73, s41, s53
	s_cselect_b32 s72, s84, s52
	s_cselect_b32 s71, s37, s87
	s_cselect_b32 s70, s85, s86
	v_lshl_add_u64 v[218:219], s[68:69], 0, v[156:157]
	s_add_i32 m0, s39, 0xc000
	ds_read_b128 v[186:189], v176
	ds_read_b128 v[190:193], v176 offset:1024
	ds_read_b128 v[194:197], v176 offset:2048
	ds_read_b128 v[198:201], v176 offset:3072
	ds_read_b128 v[202:205], v176 offset:4096
	ds_read_b128 v[206:209], v176 offset:5120
	ds_read_b128 v[210:213], v176 offset:6144
	ds_read_b128 v[214:217], v176 offset:7168
	global_load_lds_dwordx4 v[218:219], off
	s_add_i32 m0, s39, 0xe000
	v_lshl_add_u64 v[218:219], s[68:69], 0, v[158:159]
	global_load_lds_dwordx4 v[218:219], off
	s_waitcnt vmcnt(8)
	s_waitcnt lgkmcnt(0)
	s_setprio 1
	s_barrier
	v_mfma_f32_16x16x32_bf16 v[140:143], v[112:115], v[186:189], v[140:143]
	v_mfma_f32_16x16x32_bf16 v[136:139], v[120:123], v[186:189], v[136:139]
	v_mfma_f32_16x16x32_bf16 v[108:111], v[112:115], v[194:197], v[108:111]
	v_mfma_f32_16x16x32_bf16 v[104:107], v[120:123], v[194:197], v[104:107]
	v_mfma_f32_16x16x32_bf16 v[92:95], v[112:115], v[202:205], v[92:95]
	v_mfma_f32_16x16x32_bf16 v[88:91], v[120:123], v[202:205], v[88:91]
	v_mfma_f32_16x16x32_bf16 v[76:79], v[112:115], v[210:213], v[76:79]
	v_mfma_f32_16x16x32_bf16 v[72:75], v[120:123], v[210:213], v[72:75]
	v_mfma_f32_16x16x32_bf16 v[140:143], v[116:119], v[190:193], v[140:143]
	v_mfma_f32_16x16x32_bf16 v[136:139], v[124:127], v[190:193], v[136:139]
	v_mfma_f32_16x16x32_bf16 v[108:111], v[116:119], v[198:201], v[108:111]
	v_mfma_f32_16x16x32_bf16 v[104:107], v[124:127], v[198:201], v[104:107]
	v_mfma_f32_16x16x32_bf16 v[92:95], v[116:119], v[206:209], v[92:95]
	v_mfma_f32_16x16x32_bf16 v[88:91], v[124:127], v[206:209], v[88:91]
	v_mfma_f32_16x16x32_bf16 v[76:79], v[116:119], v[214:217], v[76:79]
	v_mfma_f32_16x16x32_bf16 v[72:75], v[124:127], v[214:217], v[72:75]
	s_setprio 0
	s_setprio 1
	v_mfma_f32_16x16x32_bf16 v[132:135], v[164:167], v[186:189], v[132:135]
	v_mfma_f32_16x16x32_bf16 v[128:131], v[178:181], v[186:189], v[128:131]
	v_mfma_f32_16x16x32_bf16 v[100:103], v[164:167], v[194:197], v[100:103]
	v_mfma_f32_16x16x32_bf16 v[96:99], v[178:181], v[194:197], v[96:99]
	v_mfma_f32_16x16x32_bf16 v[84:87], v[164:167], v[202:205], v[84:87]
	v_mfma_f32_16x16x32_bf16 v[80:83], v[178:181], v[202:205], v[80:83]
	v_mfma_f32_16x16x32_bf16 v[68:71], v[164:167], v[210:213], v[68:71]
	v_mfma_f32_16x16x32_bf16 v[64:67], v[178:181], v[210:213], v[64:67]
	v_mfma_f32_16x16x32_bf16 v[132:135], v[168:171], v[190:193], v[132:135]
	v_mfma_f32_16x16x32_bf16 v[128:131], v[182:185], v[190:193], v[128:131]
	v_mfma_f32_16x16x32_bf16 v[100:103], v[168:171], v[198:201], v[100:103]
	v_mfma_f32_16x16x32_bf16 v[96:99], v[182:185], v[198:201], v[96:99]
	v_mfma_f32_16x16x32_bf16 v[84:87], v[168:171], v[206:209], v[84:87]
	s_setprio 2
	s_barrier
	v_mfma_f32_16x16x32_bf16 v[80:83], v[182:185], v[206:209], v[80:83]
	v_mfma_f32_16x16x32_bf16 v[68:71], v[168:171], v[214:217], v[68:71]
	v_mfma_f32_16x16x32_bf16 v[64:67], v[182:185], v[214:217], v[64:67]
	s_setprio 0
	s_add_i32 s52, s81, s29
	v_lshl_add_u64 v[218:219], s[70:71], 0, v[152:153]
	s_mov_b32 m0, s52
	ds_read_b128 v[186:189], v176 offset:16384
	ds_read_b128 v[190:193], v176 offset:17408
	ds_read_b128 v[194:197], v176 offset:18432
	ds_read_b128 v[198:201], v176 offset:19456
	ds_read_b128 v[202:205], v176 offset:20480
	ds_read_b128 v[206:209], v176 offset:21504
	ds_read_b128 v[210:213], v176 offset:22528
	ds_read_b128 v[214:217], v176 offset:23552
	global_load_lds_dwordx4 v[218:219], off
	s_add_i32 m0, s52, 0x2000
	s_add_u32 s52, s70, 0x80000
	v_lshl_add_u64 v[220:221], s[70:71], 0, v[148:149]
	s_addc_u32 s53, s71, 0
	s_add_i32 s56, s82, s29
	global_load_lds_dwordx4 v[220:221], off
	v_lshl_add_u64 v[222:223], s[52:53], 0, v[152:153]
	s_mov_b32 m0, s56
	v_lshl_add_u64 v[224:225], s[72:73], 0, v[150:151]
	global_load_lds_dwordx4 v[222:223], off
	s_add_i32 m0, s56, 0x2000
	v_lshl_add_u64 v[222:223], s[52:53], 0, v[148:149]
	global_load_lds_dwordx4 v[222:223], off
	s_mov_b32 m0, s39
	v_lshl_add_u64 v[222:223], s[72:73], 0, v[154:155]
	global_load_lds_dwordx4 v[222:223], off
	s_mov_b32 m0, s55
	s_nop 0
	global_load_lds_dwordx4 v[224:225], off
	s_waitcnt vmcnt(8)
	s_waitcnt lgkmcnt(0)
	s_setprio 1
	s_barrier
; #define PG8_STAGE(bufoff, gbase, voff) do { _Pragma("unroll") for (int _i = 0; _i < 2; ++_i) \
;         __builtin_amdgcn_global_load_lds((const unsigned*)((const char*)(gbase) + (voff)[_i]), (PG8_LAS unsigned*)(lds + (bufoff) + ldsw + _i * 8192), 16, 0, 0); } while (0)
; #define PG8_LDA(dst, b, h) do { _Pragma("unroll") for (int m = 0; m < 4; ++m) _Pragma("unroll") for (int k = 0; k < 2; ++k) dst[m][k] = *(const PG8_LAS bf16x8*)(lds + PG8_SA(b, h) + aoff + m * 2048 + k * 1024); } while (0)
; #define PG8_LDB(dst, b, h) do { _Pragma("unroll") for (int n = 0; n < 2; ++n) _Pragma("unroll") for (int k = 0; k < 2; ++k) dst[n][k] = *(const PG8_LAS bf16x8*)(lds + PG8_SB(b, h) + boff + n * 2048 + k * 1024); } while (0)
; #define PG8_MMA(ai, bj, At, Bt) do { __builtin_amdgcn_s_setprio(1); _Pragma("unroll") for (int m = 0; m < 4; ++m) _Pragma("unroll") for (int n = 0; n < 2; ++n) _Pragma("unroll") for (int k = 0; k < 2; ++k) \
;         acc[ai][bj][m][n] = __builtin_amdgcn_mfma_f32_16x16x32_bf16(Bt[n][k], At[m][k], acc[ai][bj][m][n], 0, 0, 0); __builtin_amdgcn_s_setprio(0); } while (0)
; #define PG8_WAIT_V(n) asm volatile("s_waitcnt vmcnt(" #n ")" ::: "memory")
; #define PG8_WAIT_L(n) asm volatile("s_waitcnt lgkmcnt(" #n ")" ::: "memory")
; #define PG8_BAR __builtin_amdgcn_s_barrier()
; #define PG8_SCHED __builtin_amdgcn_sched_barrier(0)
; template <class Epi, class Sched, bool ALIGN_EPI = false, bool SP2 = false>
; __device__ __forceinline__ void gemm_phase(PG8_LAS unsigned char* lds, const Gemm g, const Sched& S, const Epi& E) {
;     ...
;             PG8_LDB(B0, 0, 0); PG8_LDB(B1, 0, 1); PG8_SCHED; PG8_LDA(At, 0, 0); PG8_STAGE(PG8_SA(1, 1), a1 + hstep, voffA);
;             PG8_WAIT_V(8); PG8_WAIT_L(0); PG8_BAR; PG8_MMA(0, 0, At, B0); PG8_MMA(0, 1, At, B1); PG8_BAR; PG8_SCHED;
;             PG8_LDA(At, 0, 1); PG8_STAGE(PG8_SB(0, 0), b2, voffB); PG8_STAGE(PG8_SB(0, 1), b2 + hstep, voffB); PG8_STAGE(PG8_SA(0, 0), a2, voffA);
;             PG8_WAIT_V(8); PG8_WAIT_L(0); PG8_BAR; PG8_MMA(1, 0, At, B0); PG8_MMA(1, 1, At, B1); PG8_BAR; PG8_SCHED;
;             PG8_LDB(B0, 1, 0); PG8_LDB(B1, 1, 1); PG8_SCHED; PG8_LDA(At, 1, 0); PG8_STAGE(PG8_SA(0, 1), a2 + hstep, voffA);
;             PG8_WAIT_V(8); PG8_WAIT_L(0); PG8_BAR; PG8_MMA(0, 0, At, B0); PG8_MMA(0, 1, At, B1); PG8_BAR; PG8_SCHED;
	v_mfma_f32_16x16x32_bf16 v[60:63], v[112:115], v[186:189], v[60:63]
	v_mfma_f32_16x16x32_bf16 v[56:59], v[120:123], v[186:189], v[56:59]
	v_mfma_f32_16x16x32_bf16 v[44:47], v[112:115], v[194:197], v[44:47]
	v_mfma_f32_16x16x32_bf16 v[40:43], v[120:123], v[194:197], v[40:43]
	v_mfma_f32_16x16x32_bf16 v[28:31], v[112:115], v[202:205], v[28:31]
	v_mfma_f32_16x16x32_bf16 v[24:27], v[120:123], v[202:205], v[24:27]
	v_mfma_f32_16x16x32_bf16 v[12:15], v[112:115], v[210:213], v[12:15]
	v_mfma_f32_16x16x32_bf16 v[8:11], v[120:123], v[210:213], v[8:11]
	v_mfma_f32_16x16x32_bf16 v[60:63], v[116:119], v[190:193], v[60:63]
	v_mfma_f32_16x16x32_bf16 v[56:59], v[124:127], v[190:193], v[56:59]
	v_mfma_f32_16x16x32_bf16 v[44:47], v[116:119], v[198:201], v[44:47]
	v_mfma_f32_16x16x32_bf16 v[40:43], v[124:127], v[198:201], v[40:43]
	v_mfma_f32_16x16x32_bf16 v[28:31], v[116:119], v[206:209], v[28:31]
	v_mfma_f32_16x16x32_bf16 v[24:27], v[124:127], v[206:209], v[24:27]
	v_mfma_f32_16x16x32_bf16 v[12:15], v[116:119], v[214:217], v[12:15]
	v_mfma_f32_16x16x32_bf16 v[8:11], v[124:127], v[214:217], v[8:11]
	s_setprio 0
	s_setprio 1
	v_mfma_f32_16x16x32_bf16 v[52:55], v[164:167], v[186:189], v[52:55]
	v_mfma_f32_16x16x32_bf16 v[48:51], v[178:181], v[186:189], v[48:51]
	v_mfma_f32_16x16x32_bf16 v[36:39], v[164:167], v[194:197], v[36:39]
	v_mfma_f32_16x16x32_bf16 v[32:35], v[178:181], v[194:197], v[32:35]
	v_mfma_f32_16x16x32_bf16 v[20:23], v[164:167], v[202:205], v[20:23]
	v_mfma_f32_16x16x32_bf16 v[16:19], v[178:181], v[202:205], v[16:19]
	v_mfma_f32_16x16x32_bf16 v[4:7], v[164:167], v[210:213], v[4:7]
	v_mfma_f32_16x16x32_bf16 v[0:3], v[178:181], v[210:213], v[0:3]
	v_mfma_f32_16x16x32_bf16 v[52:55], v[168:171], v[190:193], v[52:55]
	v_mfma_f32_16x16x32_bf16 v[48:51], v[182:185], v[190:193], v[48:51]
	v_mfma_f32_16x16x32_bf16 v[36:39], v[168:171], v[198:201], v[36:39]
	v_mfma_f32_16x16x32_bf16 v[32:35], v[182:185], v[198:201], v[32:35]
	v_mfma_f32_16x16x32_bf16 v[20:23], v[168:171], v[206:209], v[20:23]
	s_setprio 2
	s_barrier
	v_mfma_f32_16x16x32_bf16 v[16:19], v[182:185], v[206:209], v[16:19]
	v_mfma_f32_16x16x32_bf16 v[4:7], v[168:171], v[214:217], v[4:7]
	v_mfma_f32_16x16x32_bf16 v[0:3], v[182:185], v[214:217], v[0:3]
	s_setprio 0
	s_add_i32 s56, 0, 0x18000
	s_add_i32 s57, 0, 0x1c000
	v_add_u32_e32 v124, s56, v172
	v_add_u32_e32 v177, s57, v172
	ds_read_b128 v[112:115], v124
	ds_read_b128 v[116:119], v124 offset:1024
	ds_read_b128 v[120:123], v124 offset:2048
	ds_read_b128 v[124:127], v124 offset:3072
	ds_read_b128 v[164:167], v177
	ds_read_b128 v[168:171], v177 offset:1024
	ds_read_b128 v[178:181], v177 offset:2048
	ds_read_b128 v[182:185], v177 offset:3072
	s_add_u32 s52, s72, 0x80000
	s_addc_u32 s53, s73, 0
	s_mov_b32 m0, s74
	v_lshl_add_u64 v[226:227], s[52:53], 0, v[154:155]
	ds_read_b128 v[186:189], v176 offset:32768
	ds_read_b128 v[190:193], v176 offset:33792
	ds_read_b128 v[194:197], v176 offset:34816
	ds_read_b128 v[198:201], v176 offset:35840
	ds_read_b128 v[202:205], v176 offset:36864
	ds_read_b128 v[206:209], v176 offset:37888
	ds_read_b128 v[210:213], v176 offset:38912
	ds_read_b128 v[214:217], v176 offset:39936
	global_load_lds_dwordx4 v[226:227], off
	s_mov_b32 m0, s75
	v_lshl_add_u64 v[226:227], s[52:53], 0, v[150:151]
	global_load_lds_dwordx4 v[226:227], off
	s_waitcnt vmcnt(8)
	s_waitcnt lgkmcnt(0)
	s_setprio 1
	s_barrier
	v_mfma_f32_16x16x32_bf16 v[140:143], v[112:115], v[186:189], v[140:143]
	v_mfma_f32_16x16x32_bf16 v[136:139], v[120:123], v[186:189], v[136:139]
	v_mfma_f32_16x16x32_bf16 v[108:111], v[112:115], v[194:197], v[108:111]
	v_mfma_f32_16x16x32_bf16 v[104:107], v[120:123], v[194:197], v[104:107]
	v_mfma_f32_16x16x32_bf16 v[92:95], v[112:115], v[202:205], v[92:95]
	v_mfma_f32_16x16x32_bf16 v[88:91], v[120:123], v[202:205], v[88:91]
	v_mfma_f32_16x16x32_bf16 v[76:79], v[112:115], v[210:213], v[76:79]
	v_mfma_f32_16x16x32_bf16 v[72:75], v[120:123], v[210:213], v[72:75]
	v_mfma_f32_16x16x32_bf16 v[140:143], v[116:119], v[190:193], v[140:143]
	v_mfma_f32_16x16x32_bf16 v[136:139], v[124:127], v[190:193], v[136:139]
	v_mfma_f32_16x16x32_bf16 v[108:111], v[116:119], v[198:201], v[108:111]
	v_mfma_f32_16x16x32_bf16 v[104:107], v[124:127], v[198:201], v[104:107]
	v_mfma_f32_16x16x32_bf16 v[92:95], v[116:119], v[206:209], v[92:95]
	v_mfma_f32_16x16x32_bf16 v[88:91], v[124:127], v[206:209], v[88:91]
	v_mfma_f32_16x16x32_bf16 v[76:79], v[116:119], v[214:217], v[76:79]
	v_mfma_f32_16x16x32_bf16 v[72:75], v[124:127], v[214:217], v[72:75]
	s_setprio 0
	s_setprio 1
	v_mfma_f32_16x16x32_bf16 v[132:135], v[164:167], v[186:189], v[132:135]
	v_mfma_f32_16x16x32_bf16 v[128:131], v[178:181], v[186:189], v[128:131]
	v_mfma_f32_16x16x32_bf16 v[100:103], v[164:167], v[194:197], v[100:103]
	v_mfma_f32_16x16x32_bf16 v[96:99], v[178:181], v[194:197], v[96:99]
	v_mfma_f32_16x16x32_bf16 v[84:87], v[164:167], v[202:205], v[84:87]
	v_mfma_f32_16x16x32_bf16 v[80:83], v[178:181], v[202:205], v[80:83]
	v_mfma_f32_16x16x32_bf16 v[68:71], v[164:167], v[210:213], v[68:71]
	v_mfma_f32_16x16x32_bf16 v[64:67], v[178:181], v[210:213], v[64:67]
	v_mfma_f32_16x16x32_bf16 v[132:135], v[168:171], v[190:193], v[132:135]
	v_mfma_f32_16x16x32_bf16 v[128:131], v[182:185], v[190:193], v[128:131]
	v_mfma_f32_16x16x32_bf16 v[100:103], v[168:171], v[198:201], v[100:103]
	v_mfma_f32_16x16x32_bf16 v[96:99], v[182:185], v[198:201], v[96:99]
	v_mfma_f32_16x16x32_bf16 v[84:87], v[168:171], v[206:209], v[84:87]
	s_setprio 2
	s_barrier
; #define PG8_STAGE(bufoff, gbase, voff) do { _Pragma("unroll") for (int _i = 0; _i < 2; ++_i) \
;         __builtin_amdgcn_global_load_lds((const unsigned*)((const char*)(gbase) + (voff)[_i]), (PG8_LAS unsigned*)(lds + (bufoff) + ldsw + _i * 8192), 16, 0, 0); } while (0)
; #define PG8_LDA(dst, b, h) do { _Pragma("unroll") for (int m = 0; m < 4; ++m) _Pragma("unroll") for (int k = 0; k < 2; ++k) dst[m][k] = *(const PG8_LAS bf16x8*)(lds + PG8_SA(b, h) + aoff + m * 2048 + k * 1024); } while (0)
; #define PG8_MMA(ai, bj, At, Bt) do { __builtin_amdgcn_s_setprio(1); _Pragma("unroll") for (int m = 0; m < 4; ++m) _Pragma("unroll") for (int n = 0; n < 2; ++n) _Pragma("unroll") for (int k = 0; k < 2; ++k) \
;         acc[ai][bj][m][n] = __builtin_amdgcn_mfma_f32_16x16x32_bf16(Bt[n][k], At[m][k], acc[ai][bj][m][n], 0, 0, 0); __builtin_amdgcn_s_setprio(0); } while (0)
; #define PG8_WAIT_V(n) asm volatile("s_waitcnt vmcnt(" #n ")" ::: "memory")
; #define PG8_WAIT_L(n) asm volatile("s_waitcnt lgkmcnt(" #n ")" ::: "memory")
; #define PG8_BAR __builtin_amdgcn_s_barrier()
; #define PG8_SCHED __builtin_amdgcn_sched_barrier(0)
; template <class Epi, class Sched, bool ALIGN_EPI = false, bool SP2 = false>
; __device__ __forceinline__ void gemm_phase(PG8_LAS unsigned char* lds, const Gemm g, const Sched& S, const Epi& E) {
;     ...
;             PG8_WAIT_V(8); PG8_WAIT_L(0); PG8_BAR; PG8_MMA(0, 0, At, B0); PG8_MMA(0, 1, At, B1); PG8_BAR; PG8_SCHED;
;             PG8_LDA(At, 1, 1); PG8_STAGE(PG8_SB(1, 0), b3, voffB); PG8_STAGE(PG8_SB(1, 1), b3 + hstep, voffB); PG8_STAGE(PG8_SA(1, 0), a3, voffA);
;             PG8_WAIT_V(8); PG8_WAIT_L(0); PG8_BAR; PG8_MMA(1, 0, At, B0); PG8_MMA(1, 1, At, B1); PG8_BAR; PG8_SCHED;
	v_mfma_f32_16x16x32_bf16 v[80:83], v[182:185], v[206:209], v[80:83]
	v_mfma_f32_16x16x32_bf16 v[68:71], v[168:171], v[214:217], v[68:71]
	v_mfma_f32_16x16x32_bf16 v[64:67], v[182:185], v[214:217], v[64:67]
	s_setprio 0
	s_add_i32 s52, s56, s29
	v_lshl_add_u64 v[218:219], v[218:219], 0, s[12:13]
	s_mov_b32 m0, s52
	ds_read_b128 v[186:189], v176 offset:49152
	ds_read_b128 v[190:193], v176 offset:50176
	ds_read_b128 v[194:197], v176 offset:51200
	ds_read_b128 v[198:201], v176 offset:52224
	ds_read_b128 v[202:205], v176 offset:53248
	ds_read_b128 v[206:209], v176 offset:54272
	ds_read_b128 v[210:213], v176 offset:55296
	ds_read_b128 v[214:217], v176 offset:56320
	global_load_lds_dwordx4 v[218:219], off
	s_add_i32 m0, s52, 0x2000
	s_add_u32 s52, s70, 0x80080
	v_lshl_add_u64 v[218:219], v[220:221], 0, s[12:13]
	s_addc_u32 s53, s71, 0
	s_add_i32 s56, s57, s29
	global_load_lds_dwordx4 v[218:219], off
	s_mov_b32 m0, s56
	v_lshl_add_u64 v[218:219], s[52:53], 0, v[152:153]
	global_load_lds_dwordx4 v[218:219], off
	s_add_i32 m0, s56, 0x2000
	v_lshl_add_u64 v[218:219], s[52:53], 0, v[148:149]
	global_load_lds_dwordx4 v[218:219], off
	s_mov_b32 m0, s77
	v_lshl_add_u64 v[218:219], v[222:223], 0, s[12:13]
	global_load_lds_dwordx4 v[218:219], off
	s_mov_b32 m0, s78
	v_lshl_add_u64 v[218:219], v[224:225], 0, s[12:13]
	global_load_lds_dwordx4 v[218:219], off
	s_waitcnt vmcnt(8)
	s_waitcnt lgkmcnt(0)
	s_setprio 1
	s_barrier
	v_mfma_f32_16x16x32_bf16 v[60:63], v[112:115], v[186:189], v[60:63]
	v_mfma_f32_16x16x32_bf16 v[56:59], v[120:123], v[186:189], v[56:59]
	v_mfma_f32_16x16x32_bf16 v[44:47], v[112:115], v[194:197], v[44:47]
	v_mfma_f32_16x16x32_bf16 v[40:43], v[120:123], v[194:197], v[40:43]
	v_mfma_f32_16x16x32_bf16 v[28:31], v[112:115], v[202:205], v[28:31]
	v_mfma_f32_16x16x32_bf16 v[24:27], v[120:123], v[202:205], v[24:27]
	v_mfma_f32_16x16x32_bf16 v[12:15], v[112:115], v[210:213], v[12:15]
	v_mfma_f32_16x16x32_bf16 v[8:11], v[120:123], v[210:213], v[8:11]
	v_mfma_f32_16x16x32_bf16 v[60:63], v[116:119], v[190:193], v[60:63]
	v_mfma_f32_16x16x32_bf16 v[56:59], v[124:127], v[190:193], v[56:59]
	v_mfma_f32_16x16x32_bf16 v[44:47], v[116:119], v[198:201], v[44:47]
	v_mfma_f32_16x16x32_bf16 v[40:43], v[124:127], v[198:201], v[40:43]
	v_mfma_f32_16x16x32_bf16 v[28:31], v[116:119], v[206:209], v[28:31]
	v_mfma_f32_16x16x32_bf16 v[24:27], v[124:127], v[206:209], v[24:27]
	v_mfma_f32_16x16x32_bf16 v[12:15], v[116:119], v[214:217], v[12:15]
	v_mfma_f32_16x16x32_bf16 v[8:11], v[124:127], v[214:217], v[8:11]
	s_setprio 0
	s_setprio 1
	v_mfma_f32_16x16x32_bf16 v[52:55], v[164:167], v[186:189], v[52:55]
	v_mfma_f32_16x16x32_bf16 v[48:51], v[178:181], v[186:189], v[48:51]
	v_mfma_f32_16x16x32_bf16 v[36:39], v[164:167], v[194:197], v[36:39]
	v_mfma_f32_16x16x32_bf16 v[32:35], v[178:181], v[194:197], v[32:35]
	v_mfma_f32_16x16x32_bf16 v[20:23], v[164:167], v[202:205], v[20:23]
	v_mfma_f32_16x16x32_bf16 v[16:19], v[178:181], v[202:205], v[16:19]
	v_mfma_f32_16x16x32_bf16 v[4:7], v[164:167], v[210:213], v[4:7]
	v_mfma_f32_16x16x32_bf16 v[0:3], v[178:181], v[210:213], v[0:3]
	v_mfma_f32_16x16x32_bf16 v[52:55], v[168:171], v[190:193], v[52:55]
	v_mfma_f32_16x16x32_bf16 v[48:51], v[182:185], v[190:193], v[48:51]
	v_mfma_f32_16x16x32_bf16 v[36:39], v[168:171], v[198:201], v[36:39]
	v_mfma_f32_16x16x32_bf16 v[32:35], v[182:185], v[198:201], v[32:35]
	v_mfma_f32_16x16x32_bf16 v[20:23], v[168:171], v[206:209], v[20:23]
	s_setprio 2
	s_barrier
	v_mfma_f32_16x16x32_bf16 v[16:19], v[182:185], v[206:209], v[16:19]
	v_mfma_f32_16x16x32_bf16 v[4:7], v[168:171], v[214:217], v[4:7]
	v_mfma_f32_16x16x32_bf16 v[0:3], v[182:185], v[214:217], v[0:3]
	s_setprio 0
	s_add_i32 s88, s88, 2
	s_add_u32 s68, s68, 0x100
	s_addc_u32 s69, s69, 0
	s_add_u32 s86, s86, 0x100
	s_addc_u32 s87, s87, 0
	s_cmp_gt_u32 s88, 29
	s_cbranch_scc0 .LBB0_545
	s_and_b64 vcc, exec, s[14:15]
	s_cbranch_vccz .LBB0_548
	s_barrier

; #define PG8_STAGE(bufoff, gbase, voff) do { _Pragma("unroll") for (int _i = 0; _i < 2; ++_i) \
;         __builtin_amdgcn_global_load_lds((const unsigned*)((const char*)(gbase) + (voff)[_i]), (PG8_LAS unsigned*)(lds + (bufoff) + ldsw + _i * 8192), 16, 0, 0); } while (0)
; #define PG8_LDA(dst, b, h) do { _Pragma("unroll") for (int m = 0; m < 4; ++m) _Pragma("unroll") for (int k = 0; k < 2; ++k) dst[m][k] = *(const PG8_LAS bf16x8*)(lds + PG8_SA(b, h) + aoff + m * 2048 + k * 1024); } while (0)
; #define PG8_LDB(dst, b, h) do { _Pragma("unroll") for (int n = 0; n < 2; ++n) _Pragma("unroll") for (int k = 0; k < 2; ++k) dst[n][k] = *(const PG8_LAS bf16x8*)(lds + PG8_SB(b, h) + boff + n * 2048 + k * 1024); } while (0)
; #define PG8_MMA(ai, bj, At, Bt) do { __builtin_amdgcn_s_setprio(1); _Pragma("unroll") for (int m = 0; m < 4; ++m) _Pragma("unroll") for (int n = 0; n < 2; ++n) _Pragma("unroll") for (int k = 0; k < 2; ++k) \
;         acc[ai][bj][m][n] = __builtin_amdgcn_mfma_f32_16x16x32_bf16(Bt[n][k], At[m][k], acc[ai][bj][m][n], 0, 0, 0); __builtin_amdgcn_s_setprio(0); } while (0)
; #define PG8_WAIT_V(n) asm volatile("s_waitcnt vmcnt(" #n ")" ::: "memory")
; #define PG8_WAIT_L(n) asm volatile("s_waitcnt lgkmcnt(" #n ")" ::: "memory")
; #define PG8_BAR __builtin_amdgcn_s_barrier()
; template <class Epi, class Sched, bool ALIGN_EPI = false, bool SP2 = false>
; __device__ __forceinline__ void gemm_phase(PG8_LAS unsigned char* lds, const Gemm g, const Sched& S, const Epi& E) {
;     ...
;             const bool last = (t == nt - 2);
;             const char* a1 = cA + (size_t)(t + 1) * kstep;
;             const char* a2 = last ? nA : cA + (size_t)(t + 2) * kstep; const char* b2 = last ? nB : cB + (size_t)(t + 2) * kstep;
;             const char* a3 = a2 + kstep; const char* b3 = b2 + kstep;
;             if constexpr (SP2) {
;             PG8_LDB(B0, 0, 0); PG8_LDB(B1, 0, 1); PG8_SCHED; PG8_LDA(At, 0, 0); PG8_STAGE(PG8_SA(1, 1), a1 + hstep, voffA);
;             PG8_WAIT_V(8); PG8_WAIT_L(0); PG8_BAR; PG8_MMA(0, 0, At, B0); PG8_MMA(0, 1, At, B1); PG8_BAR; PG8_SCHED;
;             PG8_LDA(At, 0, 1); PG8_STAGE(PG8_SB(0, 0), b2, voffB); PG8_STAGE(PG8_SB(0, 1), b2 + hstep, voffB); PG8_STAGE(PG8_SA(0, 0), a2, voffA);
;             PG8_WAIT_V(8); PG8_WAIT_L(0); PG8_BAR; PG8_MMA(1, 0, At, B0); PG8_MMA(1, 1, At, B1); PG8_BAR; PG8_SCHED;
.LBB0_624:
	ds_read_b128 v[128:131], v214
	ds_read_b128 v[132:135], v214 offset:1024
	ds_read_b128 v[158:161], v214 offset:2048
	ds_read_b128 v[162:165], v214 offset:3072
	ds_read_b128 v[166:169], v215
	ds_read_b128 v[170:173], v215 offset:1024
	ds_read_b128 v[174:177], v215 offset:2048
	ds_read_b128 v[178:181], v215 offset:3072
	s_add_u32 s52, s74, 0xffe00080
	s_addc_u32 s53, s75, -1
	s_cmpk_eq_i32 vcc_hi, 0x7c
	s_cselect_b32 s79, s51, s53
	s_cselect_b32 s78, s71, s52
	s_cselect_b32 s77, s49, vcc_lo
	s_cselect_b32 s76, s73, s93
	v_lshl_add_u64 v[226:227], s[74:75], 0, v[150:151]
	s_add_i32 m0, s83, 0xc000
	ds_read_b128 v[182:185], v216
	ds_read_b128 v[186:189], v216 offset:1024
	ds_read_b128 v[190:193], v216 offset:2048
	ds_read_b128 v[194:197], v216 offset:3072
	ds_read_b128 v[198:201], v216 offset:4096
	ds_read_b128 v[202:205], v216 offset:5120
	ds_read_b128 v[218:221], v216 offset:6144
	ds_read_b128 v[222:225], v216 offset:7168
	global_load_lds_dwordx4 v[226:227], off
	s_add_i32 m0, s83, 0xe000
	v_lshl_add_u64 v[226:227], s[74:75], 0, v[152:153]
	global_load_lds_dwordx4 v[226:227], off
	s_waitcnt vmcnt(8)
	s_waitcnt lgkmcnt(0)
	s_setprio 1
	s_barrier
	v_mfma_f32_16x16x32_bf16 v[124:127], v[128:131], v[182:185], v[124:127]
	v_mfma_f32_16x16x32_bf16 v[120:123], v[158:161], v[182:185], v[120:123]
	v_mfma_f32_16x16x32_bf16 v[116:119], v[128:131], v[190:193], v[116:119]
	v_mfma_f32_16x16x32_bf16 v[112:115], v[158:161], v[190:193], v[112:115]
	v_mfma_f32_16x16x32_bf16 v[108:111], v[128:131], v[198:201], v[108:111]
	v_mfma_f32_16x16x32_bf16 v[104:107], v[158:161], v[198:201], v[104:107]
	v_mfma_f32_16x16x32_bf16 v[100:103], v[128:131], v[218:221], v[100:103]
	v_mfma_f32_16x16x32_bf16 v[96:99], v[158:161], v[218:221], v[96:99]
	v_mfma_f32_16x16x32_bf16 v[124:127], v[132:135], v[186:189], v[124:127]
	v_mfma_f32_16x16x32_bf16 v[120:123], v[162:165], v[186:189], v[120:123]
	v_mfma_f32_16x16x32_bf16 v[116:119], v[132:135], v[194:197], v[116:119]
	v_mfma_f32_16x16x32_bf16 v[112:115], v[162:165], v[194:197], v[112:115]
	v_mfma_f32_16x16x32_bf16 v[108:111], v[132:135], v[202:205], v[108:111]
	v_mfma_f32_16x16x32_bf16 v[104:107], v[162:165], v[202:205], v[104:107]
	v_mfma_f32_16x16x32_bf16 v[100:103], v[132:135], v[222:225], v[100:103]
	v_mfma_f32_16x16x32_bf16 v[96:99], v[162:165], v[222:225], v[96:99]
	s_setprio 0
	s_setprio 1
	v_mfma_f32_16x16x32_bf16 v[60:63], v[166:169], v[182:185], v[60:63]
	v_mfma_f32_16x16x32_bf16 v[56:59], v[174:177], v[182:185], v[56:59]
	v_mfma_f32_16x16x32_bf16 v[52:55], v[166:169], v[190:193], v[52:55]
	v_mfma_f32_16x16x32_bf16 v[48:51], v[174:177], v[190:193], v[48:51]
	v_mfma_f32_16x16x32_bf16 v[44:47], v[166:169], v[198:201], v[44:47]
	v_mfma_f32_16x16x32_bf16 v[40:43], v[174:177], v[198:201], v[40:43]
	v_mfma_f32_16x16x32_bf16 v[36:39], v[166:169], v[218:221], v[36:39]
	v_mfma_f32_16x16x32_bf16 v[32:35], v[174:177], v[218:221], v[32:35]
	v_mfma_f32_16x16x32_bf16 v[60:63], v[170:173], v[186:189], v[60:63]
	v_mfma_f32_16x16x32_bf16 v[56:59], v[178:181], v[186:189], v[56:59]
	v_mfma_f32_16x16x32_bf16 v[52:55], v[170:173], v[194:197], v[52:55]
	v_mfma_f32_16x16x32_bf16 v[48:51], v[178:181], v[194:197], v[48:51]
	v_mfma_f32_16x16x32_bf16 v[44:47], v[170:173], v[202:205], v[44:47]
	s_setprio 2
	s_barrier
	v_mfma_f32_16x16x32_bf16 v[40:43], v[178:181], v[202:205], v[40:43]
	v_mfma_f32_16x16x32_bf16 v[36:39], v[170:173], v[222:225], v[36:39]
	v_mfma_f32_16x16x32_bf16 v[32:35], v[178:181], v[222:225], v[32:35]
	s_setprio 0
	s_add_i32 s52, s33, s82
	v_lshl_add_u64 v[226:227], s[76:77], 0, v[138:139]
	s_mov_b32 m0, s52
	ds_read_b128 v[182:185], v216 offset:16384
	ds_read_b128 v[186:189], v216 offset:17408
	ds_read_b128 v[190:193], v216 offset:18432
	ds_read_b128 v[194:197], v216 offset:19456
	ds_read_b128 v[198:201], v216 offset:20480
	ds_read_b128 v[202:205], v216 offset:21504
	ds_read_b128 v[218:221], v216 offset:22528
	ds_read_b128 v[222:225], v216 offset:23552
	global_load_lds_dwordx4 v[226:227], off
	s_add_i32 m0, s52, 0x2000
	s_add_u32 s52, s76, 0x200000
	v_lshl_add_u64 v[228:229], s[76:77], 0, v[142:143]
	s_addc_u32 s53, s77, 0
	s_add_i32 s56, s92, s82
	global_load_lds_dwordx4 v[228:229], off
	v_lshl_add_u64 v[230:231], s[52:53], 0, v[138:139]
	s_mov_b32 m0, s56
	v_lshl_add_u64 v[232:233], s[78:79], 0, v[140:141]
	global_load_lds_dwordx4 v[230:231], off
	s_add_i32 m0, s56, 0x2000
	v_lshl_add_u64 v[230:231], s[52:53], 0, v[142:143]
	global_load_lds_dwordx4 v[230:231], off
	s_mov_b32 m0, s83
	v_lshl_add_u64 v[230:231], s[78:79], 0, v[136:137]
	global_load_lds_dwordx4 v[230:231], off
	s_mov_b32 m0, s84
	s_nop 0
	global_load_lds_dwordx4 v[232:233], off
	s_waitcnt vmcnt(8)
	s_waitcnt lgkmcnt(0)
	s_setprio 1
	s_barrier
; #define PG8_STAGE(bufoff, gbase, voff) do { _Pragma("unroll") for (int _i = 0; _i < 2; ++_i) \
;         __builtin_amdgcn_global_load_lds((const unsigned*)((const char*)(gbase) + (voff)[_i]), (PG8_LAS unsigned*)(lds + (bufoff) + ldsw + _i * 8192), 16, 0, 0); } while (0)
; #define PG8_LDA(dst, b, h) do { _Pragma("unroll") for (int m = 0; m < 4; ++m) _Pragma("unroll") for (int k = 0; k < 2; ++k) dst[m][k] = *(const PG8_LAS bf16x8*)(lds + PG8_SA(b, h) + aoff + m * 2048 + k * 1024); } while (0)
; #define PG8_LDB(dst, b, h) do { _Pragma("unroll") for (int n = 0; n < 2; ++n) _Pragma("unroll") for (int k = 0; k < 2; ++k) dst[n][k] = *(const PG8_LAS bf16x8*)(lds + PG8_SB(b, h) + boff + n * 2048 + k * 1024); } while (0)
; #define PG8_MMA(ai, bj, At, Bt) do { __builtin_amdgcn_s_setprio(1); _Pragma("unroll") for (int m = 0; m < 4; ++m) _Pragma("unroll") for (int n = 0; n < 2; ++n) _Pragma("unroll") for (int k = 0; k < 2; ++k) \
;         acc[ai][bj][m][n] = __builtin_amdgcn_mfma_f32_16x16x32_bf16(Bt[n][k], At[m][k], acc[ai][bj][m][n], 0, 0, 0); __builtin_amdgcn_s_setprio(0); } while (0)
; #define PG8_WAIT_V(n) asm volatile("s_waitcnt vmcnt(" #n ")" ::: "memory")
; #define PG8_WAIT_L(n) asm volatile("s_waitcnt lgkmcnt(" #n ")" ::: "memory")
; #define PG8_BAR __builtin_amdgcn_s_barrier()
; #define PG8_SCHED __builtin_amdgcn_sched_barrier(0)
; template <class Epi, class Sched, bool ALIGN_EPI = false, bool SP2 = false>
; __device__ __forceinline__ void gemm_phase(PG8_LAS unsigned char* lds, const Gemm g, const Sched& S, const Epi& E) {
;     ...
;             PG8_WAIT_V(8); PG8_WAIT_L(0); PG8_BAR; PG8_MMA(1, 0, At, B0); PG8_MMA(1, 1, At, B1); PG8_BAR; PG8_SCHED;
;             PG8_LDB(B0, 1, 0); PG8_LDB(B1, 1, 1); PG8_SCHED; PG8_LDA(At, 1, 0); PG8_STAGE(PG8_SA(0, 1), a2 + hstep, voffA);
;             PG8_WAIT_V(8); PG8_WAIT_L(0); PG8_BAR; PG8_MMA(0, 0, At, B0); PG8_MMA(0, 1, At, B1); PG8_BAR; PG8_SCHED;
	v_mfma_f32_16x16x32_bf16 v[92:95], v[128:131], v[182:185], v[92:95]
	v_mfma_f32_16x16x32_bf16 v[88:91], v[158:161], v[182:185], v[88:91]
	v_mfma_f32_16x16x32_bf16 v[84:87], v[128:131], v[190:193], v[84:87]
	v_mfma_f32_16x16x32_bf16 v[80:83], v[158:161], v[190:193], v[80:83]
	v_mfma_f32_16x16x32_bf16 v[76:79], v[128:131], v[198:201], v[76:79]
	v_mfma_f32_16x16x32_bf16 v[72:75], v[158:161], v[198:201], v[72:75]
	v_mfma_f32_16x16x32_bf16 v[68:71], v[128:131], v[218:221], v[68:71]
	v_mfma_f32_16x16x32_bf16 v[64:67], v[158:161], v[218:221], v[64:67]
	v_mfma_f32_16x16x32_bf16 v[92:95], v[132:135], v[186:189], v[92:95]
	v_mfma_f32_16x16x32_bf16 v[88:91], v[162:165], v[186:189], v[88:91]
	v_mfma_f32_16x16x32_bf16 v[84:87], v[132:135], v[194:197], v[84:87]
	v_mfma_f32_16x16x32_bf16 v[80:83], v[162:165], v[194:197], v[80:83]
	v_mfma_f32_16x16x32_bf16 v[76:79], v[132:135], v[202:205], v[76:79]
	v_mfma_f32_16x16x32_bf16 v[72:75], v[162:165], v[202:205], v[72:75]
	v_mfma_f32_16x16x32_bf16 v[68:71], v[132:135], v[222:225], v[68:71]
	v_mfma_f32_16x16x32_bf16 v[64:67], v[162:165], v[222:225], v[64:67]
	s_setprio 0
	s_setprio 1
	v_mfma_f32_16x16x32_bf16 v[28:31], v[166:169], v[182:185], v[28:31]
	v_mfma_f32_16x16x32_bf16 v[24:27], v[174:177], v[182:185], v[24:27]
	v_mfma_f32_16x16x32_bf16 v[20:23], v[166:169], v[190:193], v[20:23]
	v_mfma_f32_16x16x32_bf16 v[16:19], v[174:177], v[190:193], v[16:19]
	v_mfma_f32_16x16x32_bf16 v[12:15], v[166:169], v[198:201], v[12:15]
	v_mfma_f32_16x16x32_bf16 v[8:11], v[174:177], v[198:201], v[8:11]
	v_mfma_f32_16x16x32_bf16 v[4:7], v[166:169], v[218:221], v[4:7]
	v_mfma_f32_16x16x32_bf16 v[0:3], v[174:177], v[218:221], v[0:3]
	v_mfma_f32_16x16x32_bf16 v[28:31], v[170:173], v[186:189], v[28:31]
	v_mfma_f32_16x16x32_bf16 v[24:27], v[178:181], v[186:189], v[24:27]
	v_mfma_f32_16x16x32_bf16 v[20:23], v[170:173], v[194:197], v[20:23]
	v_mfma_f32_16x16x32_bf16 v[16:19], v[178:181], v[194:197], v[16:19]
	v_mfma_f32_16x16x32_bf16 v[12:15], v[170:173], v[202:205], v[12:15]
	s_setprio 2
	s_barrier
	v_mfma_f32_16x16x32_bf16 v[8:11], v[178:181], v[202:205], v[8:11]
	v_mfma_f32_16x16x32_bf16 v[4:7], v[170:173], v[222:225], v[4:7]
	v_mfma_f32_16x16x32_bf16 v[0:3], v[178:181], v[222:225], v[0:3]
	s_setprio 0
	s_add_i32 s56, 0, 0x18000
	s_add_i32 s57, 0, 0x1c000
	v_add_u32_e32 v162, s56, v212
	v_add_u32_e32 v178, s57, v212
	ds_read_b128 v[128:131], v162
	ds_read_b128 v[132:135], v162 offset:1024
	ds_read_b128 v[158:161], v162 offset:2048
	ds_read_b128 v[162:165], v162 offset:3072
	ds_read_b128 v[166:169], v178
	ds_read_b128 v[170:173], v178 offset:1024
	ds_read_b128 v[174:177], v178 offset:2048
	ds_read_b128 v[178:181], v178 offset:3072
	s_add_u32 s52, s78, 0x200000
	s_addc_u32 s53, s79, 0
	s_mov_b32 m0, s85
	v_lshl_add_u64 v[234:235], s[52:53], 0, v[136:137]
	ds_read_b128 v[182:185], v216 offset:32768
	ds_read_b128 v[186:189], v216 offset:33792
	ds_read_b128 v[190:193], v216 offset:34816
	ds_read_b128 v[194:197], v216 offset:35840
	ds_read_b128 v[198:201], v216 offset:36864
	ds_read_b128 v[202:205], v216 offset:37888
	ds_read_b128 v[218:221], v216 offset:38912
	ds_read_b128 v[222:225], v216 offset:39936
	global_load_lds_dwordx4 v[234:235], off
	s_mov_b32 m0, s86
	v_lshl_add_u64 v[234:235], s[52:53], 0, v[140:141]
	global_load_lds_dwordx4 v[234:235], off
	s_waitcnt vmcnt(8)
	s_waitcnt lgkmcnt(0)
	s_setprio 1
	s_barrier
	v_mfma_f32_16x16x32_bf16 v[124:127], v[128:131], v[182:185], v[124:127]
	v_mfma_f32_16x16x32_bf16 v[120:123], v[158:161], v[182:185], v[120:123]
	v_mfma_f32_16x16x32_bf16 v[116:119], v[128:131], v[190:193], v[116:119]
	v_mfma_f32_16x16x32_bf16 v[112:115], v[158:161], v[190:193], v[112:115]
	v_mfma_f32_16x16x32_bf16 v[108:111], v[128:131], v[198:201], v[108:111]
	v_mfma_f32_16x16x32_bf16 v[104:107], v[158:161], v[198:201], v[104:107]
	v_mfma_f32_16x16x32_bf16 v[100:103], v[128:131], v[218:221], v[100:103]
	v_mfma_f32_16x16x32_bf16 v[96:99], v[158:161], v[218:221], v[96:99]
	v_mfma_f32_16x16x32_bf16 v[124:127], v[132:135], v[186:189], v[124:127]
	v_mfma_f32_16x16x32_bf16 v[120:123], v[162:165], v[186:189], v[120:123]
	v_mfma_f32_16x16x32_bf16 v[116:119], v[132:135], v[194:197], v[116:119]
	v_mfma_f32_16x16x32_bf16 v[112:115], v[162:165], v[194:197], v[112:115]
	v_mfma_f32_16x16x32_bf16 v[108:111], v[132:135], v[202:205], v[108:111]
	v_mfma_f32_16x16x32_bf16 v[104:107], v[162:165], v[202:205], v[104:107]
	v_mfma_f32_16x16x32_bf16 v[100:103], v[132:135], v[222:225], v[100:103]
	v_mfma_f32_16x16x32_bf16 v[96:99], v[162:165], v[222:225], v[96:99]
	s_setprio 0
	s_setprio 1
	v_mfma_f32_16x16x32_bf16 v[60:63], v[166:169], v[182:185], v[60:63]
	v_mfma_f32_16x16x32_bf16 v[56:59], v[174:177], v[182:185], v[56:59]
	v_mfma_f32_16x16x32_bf16 v[52:55], v[166:169], v[190:193], v[52:55]
	v_mfma_f32_16x16x32_bf16 v[48:51], v[174:177], v[190:193], v[48:51]
	v_mfma_f32_16x16x32_bf16 v[44:47], v[166:169], v[198:201], v[44:47]
	v_mfma_f32_16x16x32_bf16 v[40:43], v[174:177], v[198:201], v[40:43]
	v_mfma_f32_16x16x32_bf16 v[36:39], v[166:169], v[218:221], v[36:39]
	v_mfma_f32_16x16x32_bf16 v[32:35], v[174:177], v[218:221], v[32:35]
	v_mfma_f32_16x16x32_bf16 v[60:63], v[170:173], v[186:189], v[60:63]
	v_mfma_f32_16x16x32_bf16 v[56:59], v[178:181], v[186:189], v[56:59]
	v_mfma_f32_16x16x32_bf16 v[52:55], v[170:173], v[194:197], v[52:55]
	v_mfma_f32_16x16x32_bf16 v[48:51], v[178:181], v[194:197], v[48:51]
	v_mfma_f32_16x16x32_bf16 v[44:47], v[170:173], v[202:205], v[44:47]
	s_setprio 2
	s_barrier
; #define PG8_STAGE(bufoff, gbase, voff) do { _Pragma("unroll") for (int _i = 0; _i < 2; ++_i) \
;         __builtin_amdgcn_global_load_lds((const unsigned*)((const char*)(gbase) + (voff)[_i]), (PG8_LAS unsigned*)(lds + (bufoff) + ldsw + _i * 8192), 16, 0, 0); } while (0)
; #define PG8_LDA(dst, b, h) do { _Pragma("unroll") for (int m = 0; m < 4; ++m) _Pragma("unroll") for (int k = 0; k < 2; ++k) dst[m][k] = *(const PG8_LAS bf16x8*)(lds + PG8_SA(b, h) + aoff + m * 2048 + k * 1024); } while (0)
; #define PG8_MMA(ai, bj, At, Bt) do { __builtin_amdgcn_s_setprio(1); _Pragma("unroll") for (int m = 0; m < 4; ++m) _Pragma("unroll") for (int n = 0; n < 2; ++n) _Pragma("unroll") for (int k = 0; k < 2; ++k) \
;         acc[ai][bj][m][n] = __builtin_amdgcn_mfma_f32_16x16x32_bf16(Bt[n][k], At[m][k], acc[ai][bj][m][n], 0, 0, 0); __builtin_amdgcn_s_setprio(0); } while (0)
; #define PG8_WAIT_V(n) asm volatile("s_waitcnt vmcnt(" #n ")" ::: "memory")
; #define PG8_WAIT_L(n) asm volatile("s_waitcnt lgkmcnt(" #n ")" ::: "memory")
; #define PG8_BAR __builtin_amdgcn_s_barrier()
; #define PG8_SCHED __builtin_amdgcn_sched_barrier(0)
; template <class Epi, class Sched, bool ALIGN_EPI = false, bool SP2 = false>
; __device__ __forceinline__ void gemm_phase(PG8_LAS unsigned char* lds, const Gemm g, const Sched& S, const Epi& E) {
;     ...
;         for (int t = 0; t < nt; t += 2) {
;             const bool last = (t == nt - 2);
;     ...
;             PG8_WAIT_V(8); PG8_WAIT_L(0); PG8_BAR; PG8_MMA(0, 0, At, B0); PG8_MMA(0, 1, At, B1); PG8_BAR; PG8_SCHED;
;             PG8_LDA(At, 1, 1); PG8_STAGE(PG8_SB(1, 0), b3, voffB); PG8_STAGE(PG8_SB(1, 1), b3 + hstep, voffB); PG8_STAGE(PG8_SA(1, 0), a3, voffA);
;             PG8_WAIT_V(8); PG8_WAIT_L(0); PG8_BAR; PG8_MMA(1, 0, At, B0); PG8_MMA(1, 1, At, B1); PG8_BAR; PG8_SCHED;
	v_mfma_f32_16x16x32_bf16 v[40:43], v[178:181], v[202:205], v[40:43]
	v_mfma_f32_16x16x32_bf16 v[36:39], v[170:173], v[222:225], v[36:39]
	v_mfma_f32_16x16x32_bf16 v[32:35], v[178:181], v[222:225], v[32:35]
	s_setprio 0
	s_add_i32 s52, s56, s82
	v_lshl_add_u64 v[226:227], v[226:227], 0, s[36:37]
	s_mov_b32 m0, s52
	ds_read_b128 v[182:185], v216 offset:49152
	ds_read_b128 v[186:189], v216 offset:50176
	ds_read_b128 v[190:193], v216 offset:51200
	ds_read_b128 v[194:197], v216 offset:52224
	ds_read_b128 v[198:201], v216 offset:53248
	ds_read_b128 v[202:205], v216 offset:54272
	ds_read_b128 v[218:221], v216 offset:55296
	ds_read_b128 v[222:225], v216 offset:56320
	global_load_lds_dwordx4 v[226:227], off
	s_add_i32 m0, s52, 0x2000
	s_add_u32 s52, s76, 0x200080
	v_lshl_add_u64 v[226:227], v[228:229], 0, s[36:37]
	s_addc_u32 s53, s77, 0
	s_add_i32 s56, s57, s82
	global_load_lds_dwordx4 v[226:227], off
	s_mov_b32 m0, s56
	v_lshl_add_u64 v[226:227], s[52:53], 0, v[138:139]
	global_load_lds_dwordx4 v[226:227], off
	s_add_i32 m0, s56, 0x2000
	v_lshl_add_u64 v[226:227], s[52:53], 0, v[142:143]
	global_load_lds_dwordx4 v[226:227], off
	s_mov_b32 m0, s94
	v_lshl_add_u64 v[226:227], v[230:231], 0, s[36:37]
	global_load_lds_dwordx4 v[226:227], off
	s_mov_b32 m0, s95
	v_lshl_add_u64 v[226:227], v[232:233], 0, s[36:37]
	global_load_lds_dwordx4 v[226:227], off
	s_waitcnt vmcnt(8)
	s_waitcnt lgkmcnt(0)
	s_setprio 1
	s_barrier
	v_mfma_f32_16x16x32_bf16 v[92:95], v[128:131], v[182:185], v[92:95]
	v_mfma_f32_16x16x32_bf16 v[88:91], v[158:161], v[182:185], v[88:91]
	v_mfma_f32_16x16x32_bf16 v[84:87], v[128:131], v[190:193], v[84:87]
	v_mfma_f32_16x16x32_bf16 v[80:83], v[158:161], v[190:193], v[80:83]
	v_mfma_f32_16x16x32_bf16 v[76:79], v[128:131], v[198:201], v[76:79]
	v_mfma_f32_16x16x32_bf16 v[72:75], v[158:161], v[198:201], v[72:75]
	v_mfma_f32_16x16x32_bf16 v[68:71], v[128:131], v[218:221], v[68:71]
	v_mfma_f32_16x16x32_bf16 v[64:67], v[158:161], v[218:221], v[64:67]
	v_mfma_f32_16x16x32_bf16 v[92:95], v[132:135], v[186:189], v[92:95]
	v_mfma_f32_16x16x32_bf16 v[88:91], v[162:165], v[186:189], v[88:91]
	v_mfma_f32_16x16x32_bf16 v[84:87], v[132:135], v[194:197], v[84:87]
	v_mfma_f32_16x16x32_bf16 v[80:83], v[162:165], v[194:197], v[80:83]
	v_mfma_f32_16x16x32_bf16 v[76:79], v[132:135], v[202:205], v[76:79]
	v_mfma_f32_16x16x32_bf16 v[72:75], v[162:165], v[202:205], v[72:75]
	v_mfma_f32_16x16x32_bf16 v[68:71], v[132:135], v[222:225], v[68:71]
	v_mfma_f32_16x16x32_bf16 v[64:67], v[162:165], v[222:225], v[64:67]
	s_setprio 0
	s_setprio 1
	v_mfma_f32_16x16x32_bf16 v[28:31], v[166:169], v[182:185], v[28:31]
	v_mfma_f32_16x16x32_bf16 v[24:27], v[174:177], v[182:185], v[24:27]
	v_mfma_f32_16x16x32_bf16 v[20:23], v[166:169], v[190:193], v[20:23]
	v_mfma_f32_16x16x32_bf16 v[16:19], v[174:177], v[190:193], v[16:19]
	v_mfma_f32_16x16x32_bf16 v[12:15], v[166:169], v[198:201], v[12:15]
	v_mfma_f32_16x16x32_bf16 v[8:11], v[174:177], v[198:201], v[8:11]
	v_mfma_f32_16x16x32_bf16 v[4:7], v[166:169], v[218:221], v[4:7]
	v_mfma_f32_16x16x32_bf16 v[0:3], v[174:177], v[218:221], v[0:3]
	v_mfma_f32_16x16x32_bf16 v[28:31], v[170:173], v[186:189], v[28:31]
	v_mfma_f32_16x16x32_bf16 v[24:27], v[178:181], v[186:189], v[24:27]
	v_mfma_f32_16x16x32_bf16 v[20:23], v[170:173], v[194:197], v[20:23]
	v_mfma_f32_16x16x32_bf16 v[16:19], v[178:181], v[194:197], v[16:19]
	v_mfma_f32_16x16x32_bf16 v[12:15], v[170:173], v[202:205], v[12:15]
	s_setprio 2
	s_barrier
	v_mfma_f32_16x16x32_bf16 v[8:11], v[178:181], v[202:205], v[8:11]
	v_mfma_f32_16x16x32_bf16 v[4:7], v[170:173], v[222:225], v[4:7]
	v_mfma_f32_16x16x32_bf16 v[0:3], v[178:181], v[222:225], v[0:3]
	s_setprio 0
	s_add_i32 vcc_hi, vcc_hi, 2
	s_add_u32 s74, s74, 0x100
	s_addc_u32 s75, s75, 0
	s_add_u32 s93, s93, 0x100
	s_addc_u32 vcc_lo, vcc_lo, 0
	s_cmpk_gt_u32 vcc_hi, 0x7d
	s_cbranch_scc0 .LBB0_624
	s_and_b64 vcc, exec, s[40:41]
	s_cbranch_vccz .LBB0_627
	s_barrier

; #define PG8_STAGE(bufoff, gbase, voff) do { _Pragma("unroll") for (int _i = 0; _i < 2; ++_i) \
;         __builtin_amdgcn_global_load_lds((const unsigned*)((const char*)(gbase) + (voff)[_i]), (PG8_LAS unsigned*)(lds + (bufoff) + ldsw + _i * 8192), 16, 0, 0); } while (0)
; #define PG8_LDA(dst, b, h) do { _Pragma("unroll") for (int m = 0; m < 4; ++m) _Pragma("unroll") for (int k = 0; k < 2; ++k) dst[m][k] = *(const PG8_LAS bf16x8*)(lds + PG8_SA(b, h) + aoff + m * 2048 + k * 1024); } while (0)
; #define PG8_LDB(dst, b, h) do { _Pragma("unroll") for (int n = 0; n < 2; ++n) _Pragma("unroll") for (int k = 0; k < 2; ++k) dst[n][k] = *(const PG8_LAS bf16x8*)(lds + PG8_SB(b, h) + boff + n * 2048 + k * 1024); } while (0)
; #define PG8_MMA(ai, bj, At, Bt) do { __builtin_amdgcn_s_setprio(1); _Pragma("unroll") for (int m = 0; m < 4; ++m) _Pragma("unroll") for (int n = 0; n < 2; ++n) _Pragma("unroll") for (int k = 0; k < 2; ++k) \
;         acc[ai][bj][m][n] = __builtin_amdgcn_mfma_f32_16x16x32_bf16(Bt[n][k], At[m][k], acc[ai][bj][m][n], 0, 0, 0); __builtin_amdgcn_s_setprio(0); } while (0)
; #define PG8_WAIT_V(n) asm volatile("s_waitcnt vmcnt(" #n ")" ::: "memory")
; #define PG8_WAIT_L(n) asm volatile("s_waitcnt lgkmcnt(" #n ")" ::: "memory")
; #define PG8_BAR __builtin_amdgcn_s_barrier()
; #define PG8_SCHED __builtin_amdgcn_sched_barrier(0)
; template <class Epi, class Sched, bool ALIGN_EPI = false, bool SP2 = false>
; __device__ __forceinline__ void gemm_phase(PG8_LAS unsigned char* lds, const Gemm g, const Sched& S, const Epi& E) {
;     ...
;         for (int t = 0; t < nt; t += 2) {
;             const bool last = (t == nt - 2);
;             const char* a1 = cA + (size_t)(t + 1) * kstep;
;             const char* a2 = last ? nA : cA + (size_t)(t + 2) * kstep; const char* b2 = last ? nB : cB + (size_t)(t + 2) * kstep;
;             const char* a3 = a2 + kstep; const char* b3 = b2 + kstep;
;             if constexpr (SP2) {
;             PG8_LDB(B0, 0, 0); PG8_LDB(B1, 0, 1); PG8_SCHED; PG8_LDA(At, 0, 0); PG8_STAGE(PG8_SA(1, 1), a1 + hstep, voffA);
;             PG8_WAIT_V(8); PG8_WAIT_L(0); PG8_BAR; PG8_MMA(0, 0, At, B0); PG8_MMA(0, 1, At, B1); PG8_BAR; PG8_SCHED;
;             PG8_LDA(At, 0, 1); PG8_STAGE(PG8_SB(0, 0), b2, voffB); PG8_STAGE(PG8_SB(0, 1), b2 + hstep, voffB); PG8_STAGE(PG8_SA(0, 0), a2, voffA);
.LBB0_660:
	ds_read_b128 v[166:169], v145
	ds_read_b128 v[170:173], v145 offset:1024
	ds_read_b128 v[174:177], v145 offset:2048
	ds_read_b128 v[178:181], v145 offset:3072
	ds_read_b128 v[182:185], v149
	ds_read_b128 v[186:189], v149 offset:1024
	ds_read_b128 v[190:193], v149 offset:2048
	ds_read_b128 v[194:197], v149 offset:3072
	s_add_u32 s52, s72, 0xffe00080
	s_addc_u32 s53, s73, -1
	s_cmp_eq_u32 s49, 28
	s_cselect_b32 s77, s51, s53
	s_cselect_b32 s76, s50, s52
	s_cselect_b32 s75, s55, s41
	s_cselect_b32 s74, s54, s37
	s_mov_b32 m0, s82
	v_lshl_add_u64 v[230:231], s[72:73], 0, v[160:161]
	ds_read_b128 v[198:201], v164
	ds_read_b128 v[202:205], v164 offset:1024
	ds_read_b128 v[206:209], v164 offset:2048
	ds_read_b128 v[210:213], v164 offset:3072
	ds_read_b128 v[214:217], v164 offset:4096
	ds_read_b128 v[218:221], v164 offset:5120
	ds_read_b128 v[222:225], v164 offset:6144
	ds_read_b128 v[226:229], v164 offset:7168
	global_load_lds_dwordx4 v[230:231], off
	s_mov_b32 m0, s83
	v_lshl_add_u64 v[230:231], s[72:73], 0, v[162:163]
	global_load_lds_dwordx4 v[230:231], off
	s_waitcnt vmcnt(8)
	s_waitcnt lgkmcnt(0)
	s_setprio 1
	s_barrier
	v_mfma_f32_16x16x32_bf16 v[124:127], v[166:169], v[198:201], v[124:127]
	v_mfma_f32_16x16x32_bf16 v[120:123], v[174:177], v[198:201], v[120:123]
	v_mfma_f32_16x16x32_bf16 v[116:119], v[166:169], v[206:209], v[116:119]
	v_mfma_f32_16x16x32_bf16 v[108:111], v[174:177], v[206:209], v[108:111]
	v_mfma_f32_16x16x32_bf16 v[100:103], v[166:169], v[214:217], v[100:103]
	v_mfma_f32_16x16x32_bf16 v[92:95], v[174:177], v[214:217], v[92:95]
	v_mfma_f32_16x16x32_bf16 v[84:87], v[166:169], v[222:225], v[84:87]
	v_mfma_f32_16x16x32_bf16 v[76:79], v[174:177], v[222:225], v[76:79]
	v_mfma_f32_16x16x32_bf16 v[124:127], v[170:173], v[202:205], v[124:127]
	v_mfma_f32_16x16x32_bf16 v[120:123], v[178:181], v[202:205], v[120:123]
	v_mfma_f32_16x16x32_bf16 v[116:119], v[170:173], v[210:213], v[116:119]
	v_mfma_f32_16x16x32_bf16 v[108:111], v[178:181], v[210:213], v[108:111]
	v_mfma_f32_16x16x32_bf16 v[100:103], v[170:173], v[218:221], v[100:103]
	v_mfma_f32_16x16x32_bf16 v[92:95], v[178:181], v[218:221], v[92:95]
	v_mfma_f32_16x16x32_bf16 v[84:87], v[170:173], v[226:229], v[84:87]
	v_mfma_f32_16x16x32_bf16 v[76:79], v[178:181], v[226:229], v[76:79]
	s_setprio 0
	s_setprio 1
	v_mfma_f32_16x16x32_bf16 v[112:115], v[182:185], v[198:201], v[112:115]
	v_mfma_f32_16x16x32_bf16 v[104:107], v[190:193], v[198:201], v[104:107]
	v_mfma_f32_16x16x32_bf16 v[96:99], v[182:185], v[206:209], v[96:99]
	v_mfma_f32_16x16x32_bf16 v[88:91], v[190:193], v[206:209], v[88:91]
	v_mfma_f32_16x16x32_bf16 v[80:83], v[182:185], v[214:217], v[80:83]
	v_mfma_f32_16x16x32_bf16 v[72:75], v[190:193], v[214:217], v[72:75]
	v_mfma_f32_16x16x32_bf16 v[68:71], v[182:185], v[222:225], v[68:71]
	v_mfma_f32_16x16x32_bf16 v[64:67], v[190:193], v[222:225], v[64:67]
	v_mfma_f32_16x16x32_bf16 v[112:115], v[186:189], v[202:205], v[112:115]
	v_mfma_f32_16x16x32_bf16 v[104:107], v[194:197], v[202:205], v[104:107]
	v_mfma_f32_16x16x32_bf16 v[96:99], v[186:189], v[210:213], v[96:99]
	v_mfma_f32_16x16x32_bf16 v[88:91], v[194:197], v[210:213], v[88:91]
	v_mfma_f32_16x16x32_bf16 v[80:83], v[186:189], v[218:221], v[80:83]
	s_setprio 2
	s_barrier
	v_mfma_f32_16x16x32_bf16 v[72:75], v[194:197], v[218:221], v[72:75]
	v_mfma_f32_16x16x32_bf16 v[68:71], v[186:189], v[226:229], v[68:71]
	v_mfma_f32_16x16x32_bf16 v[64:67], v[194:197], v[226:229], v[64:67]
	s_setprio 0
	s_mov_b32 m0, s84
	v_lshl_add_u64 v[230:231], s[74:75], 0, v[138:139]
	s_add_u32 s52, s74, 0x200000
	ds_read_b128 v[198:201], v164 offset:16384
	ds_read_b128 v[202:205], v164 offset:17408
	ds_read_b128 v[206:209], v164 offset:18432
	ds_read_b128 v[210:213], v164 offset:19456
	ds_read_b128 v[214:217], v164 offset:20480
	ds_read_b128 v[218:221], v164 offset:21504
	ds_read_b128 v[222:225], v164 offset:22528
	ds_read_b128 v[226:229], v164 offset:23552
	global_load_lds_dwordx4 v[230:231], off
	v_lshl_add_u64 v[232:233], s[74:75], 0, v[142:143]
	s_mov_b32 m0, s85
	s_addc_u32 s53, s75, 0
	global_load_lds_dwordx4 v[232:233], off
	v_lshl_add_u64 v[234:235], s[52:53], 0, v[138:139]
	s_mov_b32 m0, s86
	v_lshl_add_u64 v[236:237], s[76:77], 0, v[140:141]
	global_load_lds_dwordx4 v[234:235], off
	s_mov_b32 m0, s87
	v_lshl_add_u64 v[234:235], s[52:53], 0, v[142:143]
	global_load_lds_dwordx4 v[234:235], off
	s_mov_b32 m0, s28
	v_lshl_add_u64 v[234:235], s[76:77], 0, v[136:137]
	global_load_lds_dwordx4 v[234:235], off
	s_mov_b32 m0, s29
	s_nop 0
	global_load_lds_dwordx4 v[236:237], off
	s_waitcnt vmcnt(8)
	s_waitcnt lgkmcnt(0)
	s_setprio 1
	s_barrier
; #define PG8_STAGE(bufoff, gbase, voff) do { _Pragma("unroll") for (int _i = 0; _i < 2; ++_i) \
;         __builtin_amdgcn_global_load_lds((const unsigned*)((const char*)(gbase) + (voff)[_i]), (PG8_LAS unsigned*)(lds + (bufoff) + ldsw + _i * 8192), 16, 0, 0); } while (0)
; #define PG8_LDA(dst, b, h) do { _Pragma("unroll") for (int m = 0; m < 4; ++m) _Pragma("unroll") for (int k = 0; k < 2; ++k) dst[m][k] = *(const PG8_LAS bf16x8*)(lds + PG8_SA(b, h) + aoff + m * 2048 + k * 1024); } while (0)
; #define PG8_LDB(dst, b, h) do { _Pragma("unroll") for (int n = 0; n < 2; ++n) _Pragma("unroll") for (int k = 0; k < 2; ++k) dst[n][k] = *(const PG8_LAS bf16x8*)(lds + PG8_SB(b, h) + boff + n * 2048 + k * 1024); } while (0)
; #define PG8_MMA(ai, bj, At, Bt) do { __builtin_amdgcn_s_setprio(1); _Pragma("unroll") for (int m = 0; m < 4; ++m) _Pragma("unroll") for (int n = 0; n < 2; ++n) _Pragma("unroll") for (int k = 0; k < 2; ++k) \
;         acc[ai][bj][m][n] = __builtin_amdgcn_mfma_f32_16x16x32_bf16(Bt[n][k], At[m][k], acc[ai][bj][m][n], 0, 0, 0); __builtin_amdgcn_s_setprio(0); } while (0)
; #define PG8_WAIT_V(n) asm volatile("s_waitcnt vmcnt(" #n ")" ::: "memory")
; #define PG8_WAIT_L(n) asm volatile("s_waitcnt lgkmcnt(" #n ")" ::: "memory")
; #define PG8_BAR __builtin_amdgcn_s_barrier()
; #define PG8_SCHED __builtin_amdgcn_sched_barrier(0)
; template <class Epi, class Sched, bool ALIGN_EPI = false, bool SP2 = false>
; __device__ __forceinline__ void gemm_phase(PG8_LAS unsigned char* lds, const Gemm g, const Sched& S, const Epi& E) {
;     ...
;             PG8_WAIT_V(8); PG8_WAIT_L(0); PG8_BAR; PG8_MMA(1, 0, At, B0); PG8_MMA(1, 1, At, B1); PG8_BAR; PG8_SCHED;
;             PG8_LDB(B0, 1, 0); PG8_LDB(B1, 1, 1); PG8_SCHED; PG8_LDA(At, 1, 0); PG8_STAGE(PG8_SA(0, 1), a2 + hstep, voffA);
;             PG8_WAIT_V(8); PG8_WAIT_L(0); PG8_BAR; PG8_MMA(0, 0, At, B0); PG8_MMA(0, 1, At, B1); PG8_BAR; PG8_SCHED;
	v_mfma_f32_16x16x32_bf16 v[60:63], v[166:169], v[198:201], v[60:63]
	v_mfma_f32_16x16x32_bf16 v[56:59], v[174:177], v[198:201], v[56:59]
	v_mfma_f32_16x16x32_bf16 v[52:55], v[166:169], v[206:209], v[52:55]
	v_mfma_f32_16x16x32_bf16 v[44:47], v[174:177], v[206:209], v[44:47]
	v_mfma_f32_16x16x32_bf16 v[36:39], v[166:169], v[214:217], v[36:39]
	v_mfma_f32_16x16x32_bf16 v[28:31], v[174:177], v[214:217], v[28:31]
	v_mfma_f32_16x16x32_bf16 v[20:23], v[166:169], v[222:225], v[20:23]
	v_mfma_f32_16x16x32_bf16 v[12:15], v[174:177], v[222:225], v[12:15]
	v_mfma_f32_16x16x32_bf16 v[60:63], v[170:173], v[202:205], v[60:63]
	v_mfma_f32_16x16x32_bf16 v[56:59], v[178:181], v[202:205], v[56:59]
	v_mfma_f32_16x16x32_bf16 v[52:55], v[170:173], v[210:213], v[52:55]
	v_mfma_f32_16x16x32_bf16 v[44:47], v[178:181], v[210:213], v[44:47]
	v_mfma_f32_16x16x32_bf16 v[36:39], v[170:173], v[218:221], v[36:39]
	v_mfma_f32_16x16x32_bf16 v[28:31], v[178:181], v[218:221], v[28:31]
	v_mfma_f32_16x16x32_bf16 v[20:23], v[170:173], v[226:229], v[20:23]
	v_mfma_f32_16x16x32_bf16 v[12:15], v[178:181], v[226:229], v[12:15]
	s_setprio 0
	s_setprio 1
	v_mfma_f32_16x16x32_bf16 v[48:51], v[182:185], v[198:201], v[48:51]
	v_mfma_f32_16x16x32_bf16 v[40:43], v[190:193], v[198:201], v[40:43]
	v_mfma_f32_16x16x32_bf16 v[32:35], v[182:185], v[206:209], v[32:35]
	v_mfma_f32_16x16x32_bf16 v[24:27], v[190:193], v[206:209], v[24:27]
	v_mfma_f32_16x16x32_bf16 v[16:19], v[182:185], v[214:217], v[16:19]
	v_mfma_f32_16x16x32_bf16 v[8:11], v[190:193], v[214:217], v[8:11]
	v_mfma_f32_16x16x32_bf16 v[4:7], v[182:185], v[222:225], v[4:7]
	v_mfma_f32_16x16x32_bf16 v[0:3], v[190:193], v[222:225], v[0:3]
	v_mfma_f32_16x16x32_bf16 v[48:51], v[186:189], v[202:205], v[48:51]
	v_mfma_f32_16x16x32_bf16 v[40:43], v[194:197], v[202:205], v[40:43]
	v_mfma_f32_16x16x32_bf16 v[32:35], v[186:189], v[210:213], v[32:35]
	v_mfma_f32_16x16x32_bf16 v[24:27], v[194:197], v[210:213], v[24:27]
	v_mfma_f32_16x16x32_bf16 v[16:19], v[186:189], v[218:221], v[16:19]
	s_setprio 2
	s_barrier
	v_mfma_f32_16x16x32_bf16 v[8:11], v[194:197], v[218:221], v[8:11]
	v_mfma_f32_16x16x32_bf16 v[4:7], v[186:189], v[226:229], v[4:7]
	v_mfma_f32_16x16x32_bf16 v[0:3], v[194:197], v[226:229], v[0:3]
	s_setprio 0
	ds_read_b128 v[166:169], v148
	ds_read_b128 v[170:173], v148 offset:1024
	ds_read_b128 v[174:177], v148 offset:2048
	ds_read_b128 v[178:181], v148 offset:3072
	ds_read_b128 v[182:185], v165
	ds_read_b128 v[186:189], v165 offset:1024
	ds_read_b128 v[190:193], v165 offset:2048
	ds_read_b128 v[194:197], v165 offset:3072
	s_add_u32 s52, s76, 0x200000
	s_addc_u32 s53, s77, 0
	s_mov_b32 m0, s33
	v_lshl_add_u64 v[238:239], s[52:53], 0, v[136:137]
	ds_read_b128 v[198:201], v164 offset:32768
	ds_read_b128 v[202:205], v164 offset:33792
	ds_read_b128 v[206:209], v164 offset:34816
	ds_read_b128 v[210:213], v164 offset:35840
	ds_read_b128 v[214:217], v164 offset:36864
	ds_read_b128 v[218:221], v164 offset:37888
	ds_read_b128 v[222:225], v164 offset:38912
	ds_read_b128 v[226:229], v164 offset:39936
	global_load_lds_dwordx4 v[238:239], off
	s_mov_b32 m0, s38
	v_lshl_add_u64 v[238:239], s[52:53], 0, v[140:141]
	global_load_lds_dwordx4 v[238:239], off
	s_waitcnt vmcnt(8)
	s_waitcnt lgkmcnt(0)
	s_setprio 1
	s_barrier
	v_mfma_f32_16x16x32_bf16 v[124:127], v[166:169], v[198:201], v[124:127]
	v_mfma_f32_16x16x32_bf16 v[120:123], v[174:177], v[198:201], v[120:123]
	v_mfma_f32_16x16x32_bf16 v[116:119], v[166:169], v[206:209], v[116:119]
	v_mfma_f32_16x16x32_bf16 v[108:111], v[174:177], v[206:209], v[108:111]
	v_mfma_f32_16x16x32_bf16 v[100:103], v[166:169], v[214:217], v[100:103]
	v_mfma_f32_16x16x32_bf16 v[92:95], v[174:177], v[214:217], v[92:95]
	v_mfma_f32_16x16x32_bf16 v[84:87], v[166:169], v[222:225], v[84:87]
	v_mfma_f32_16x16x32_bf16 v[76:79], v[174:177], v[222:225], v[76:79]
	v_mfma_f32_16x16x32_bf16 v[124:127], v[170:173], v[202:205], v[124:127]
	v_mfma_f32_16x16x32_bf16 v[120:123], v[178:181], v[202:205], v[120:123]
	v_mfma_f32_16x16x32_bf16 v[116:119], v[170:173], v[210:213], v[116:119]
	v_mfma_f32_16x16x32_bf16 v[108:111], v[178:181], v[210:213], v[108:111]
	v_mfma_f32_16x16x32_bf16 v[100:103], v[170:173], v[218:221], v[100:103]
	v_mfma_f32_16x16x32_bf16 v[92:95], v[178:181], v[218:221], v[92:95]
	v_mfma_f32_16x16x32_bf16 v[84:87], v[170:173], v[226:229], v[84:87]
	v_mfma_f32_16x16x32_bf16 v[76:79], v[178:181], v[226:229], v[76:79]
	s_setprio 0
	s_setprio 1
	v_mfma_f32_16x16x32_bf16 v[112:115], v[182:185], v[198:201], v[112:115]
	v_mfma_f32_16x16x32_bf16 v[104:107], v[190:193], v[198:201], v[104:107]
	v_mfma_f32_16x16x32_bf16 v[96:99], v[182:185], v[206:209], v[96:99]
	v_mfma_f32_16x16x32_bf16 v[88:91], v[190:193], v[206:209], v[88:91]
	v_mfma_f32_16x16x32_bf16 v[80:83], v[182:185], v[214:217], v[80:83]
	v_mfma_f32_16x16x32_bf16 v[72:75], v[190:193], v[214:217], v[72:75]
	v_mfma_f32_16x16x32_bf16 v[68:71], v[182:185], v[222:225], v[68:71]
	v_mfma_f32_16x16x32_bf16 v[64:67], v[190:193], v[222:225], v[64:67]
	v_mfma_f32_16x16x32_bf16 v[112:115], v[186:189], v[202:205], v[112:115]
	v_mfma_f32_16x16x32_bf16 v[104:107], v[194:197], v[202:205], v[104:107]
	v_mfma_f32_16x16x32_bf16 v[96:99], v[186:189], v[210:213], v[96:99]
	v_mfma_f32_16x16x32_bf16 v[88:91], v[194:197], v[210:213], v[88:91]
	v_mfma_f32_16x16x32_bf16 v[80:83], v[186:189], v[218:221], v[80:83]
	s_setprio 2
	s_barrier
; #define PG8_STAGE(bufoff, gbase, voff) do { _Pragma("unroll") for (int _i = 0; _i < 2; ++_i) \
;         __builtin_amdgcn_global_load_lds((const unsigned*)((const char*)(gbase) + (voff)[_i]), (PG8_LAS unsigned*)(lds + (bufoff) + ldsw + _i * 8192), 16, 0, 0); } while (0)
; #define PG8_LDA(dst, b, h) do { _Pragma("unroll") for (int m = 0; m < 4; ++m) _Pragma("unroll") for (int k = 0; k < 2; ++k) dst[m][k] = *(const PG8_LAS bf16x8*)(lds + PG8_SA(b, h) + aoff + m * 2048 + k * 1024); } while (0)
; #define PG8_MMA(ai, bj, At, Bt) do { __builtin_amdgcn_s_setprio(1); _Pragma("unroll") for (int m = 0; m < 4; ++m) _Pragma("unroll") for (int n = 0; n < 2; ++n) _Pragma("unroll") for (int k = 0; k < 2; ++k) \
;         acc[ai][bj][m][n] = __builtin_amdgcn_mfma_f32_16x16x32_bf16(Bt[n][k], At[m][k], acc[ai][bj][m][n], 0, 0, 0); __builtin_amdgcn_s_setprio(0); } while (0)
; #define PG8_WAIT_V(n) asm volatile("s_waitcnt vmcnt(" #n ")" ::: "memory")
; #define PG8_WAIT_L(n) asm volatile("s_waitcnt lgkmcnt(" #n ")" ::: "memory")
; #define PG8_BAR __builtin_amdgcn_s_barrier()
; #define PG8_SCHED __builtin_amdgcn_sched_barrier(0)
; template <class Epi, class Sched, bool ALIGN_EPI = false, bool SP2 = false>
; __device__ __forceinline__ void gemm_phase(PG8_LAS unsigned char* lds, const Gemm g, const Sched& S, const Epi& E) {
;     ...
;         for (int t = 0; t < nt; t += 2) {
;             const bool last = (t == nt - 2);
;     ...
;             PG8_WAIT_V(8); PG8_WAIT_L(0); PG8_BAR; PG8_MMA(0, 0, At, B0); PG8_MMA(0, 1, At, B1); PG8_BAR; PG8_SCHED;
;             PG8_LDA(At, 1, 1); PG8_STAGE(PG8_SB(1, 0), b3, voffB); PG8_STAGE(PG8_SB(1, 1), b3 + hstep, voffB); PG8_STAGE(PG8_SA(1, 0), a3, voffA);
;             PG8_WAIT_V(8); PG8_WAIT_L(0); PG8_BAR; PG8_MMA(1, 0, At, B0); PG8_MMA(1, 1, At, B1); PG8_BAR; PG8_SCHED;
	v_mfma_f32_16x16x32_bf16 v[72:75], v[194:197], v[218:221], v[72:75]
	v_mfma_f32_16x16x32_bf16 v[68:71], v[186:189], v[226:229], v[68:71]
	v_mfma_f32_16x16x32_bf16 v[64:67], v[194:197], v[226:229], v[64:67]
	s_setprio 0
	s_mov_b32 m0, s89
	v_lshl_add_u64 v[230:231], v[230:231], 0, s[12:13]
	ds_read_b128 v[198:201], v164 offset:49152
	ds_read_b128 v[202:205], v164 offset:50176
	ds_read_b128 v[206:209], v164 offset:51200
	ds_read_b128 v[210:213], v164 offset:52224
	ds_read_b128 v[214:217], v164 offset:53248
	ds_read_b128 v[218:221], v164 offset:54272
	ds_read_b128 v[222:225], v164 offset:55296
	ds_read_b128 v[226:229], v164 offset:56320
	global_load_lds_dwordx4 v[230:231], off
	s_add_i32 m0, s89, 0x2000
	s_add_u32 s52, s74, 0x200080
	v_lshl_add_u64 v[230:231], v[232:233], 0, s[12:13]
	s_addc_u32 s53, s75, 0
	s_add_i32 s56, s88, s3
	global_load_lds_dwordx4 v[230:231], off
	s_mov_b32 m0, s56
	v_lshl_add_u64 v[230:231], s[52:53], 0, v[138:139]
	global_load_lds_dwordx4 v[230:231], off
	s_add_i32 m0, s56, 0x2000
	v_lshl_add_u64 v[230:231], s[52:53], 0, v[142:143]
	global_load_lds_dwordx4 v[230:231], off
	s_mov_b32 m0, s71
	v_lshl_add_u64 v[230:231], v[234:235], 0, s[12:13]
	global_load_lds_dwordx4 v[230:231], off
	s_mov_b32 m0, s78
	v_lshl_add_u64 v[230:231], v[236:237], 0, s[12:13]
	global_load_lds_dwordx4 v[230:231], off
	s_waitcnt vmcnt(8)
	s_waitcnt lgkmcnt(0)
	s_setprio 1
	s_barrier
	v_mfma_f32_16x16x32_bf16 v[60:63], v[166:169], v[198:201], v[60:63]
	v_mfma_f32_16x16x32_bf16 v[56:59], v[174:177], v[198:201], v[56:59]
	v_mfma_f32_16x16x32_bf16 v[52:55], v[166:169], v[206:209], v[52:55]
	v_mfma_f32_16x16x32_bf16 v[44:47], v[174:177], v[206:209], v[44:47]
	v_mfma_f32_16x16x32_bf16 v[36:39], v[166:169], v[214:217], v[36:39]
	v_mfma_f32_16x16x32_bf16 v[28:31], v[174:177], v[214:217], v[28:31]
	v_mfma_f32_16x16x32_bf16 v[20:23], v[166:169], v[222:225], v[20:23]
	v_mfma_f32_16x16x32_bf16 v[12:15], v[174:177], v[222:225], v[12:15]
	v_mfma_f32_16x16x32_bf16 v[60:63], v[170:173], v[202:205], v[60:63]
	v_mfma_f32_16x16x32_bf16 v[56:59], v[178:181], v[202:205], v[56:59]
	v_mfma_f32_16x16x32_bf16 v[52:55], v[170:173], v[210:213], v[52:55]
	v_mfma_f32_16x16x32_bf16 v[44:47], v[178:181], v[210:213], v[44:47]
	v_mfma_f32_16x16x32_bf16 v[36:39], v[170:173], v[218:221], v[36:39]
	v_mfma_f32_16x16x32_bf16 v[28:31], v[178:181], v[218:221], v[28:31]
	v_mfma_f32_16x16x32_bf16 v[20:23], v[170:173], v[226:229], v[20:23]
	v_mfma_f32_16x16x32_bf16 v[12:15], v[178:181], v[226:229], v[12:15]
	s_setprio 0
	s_setprio 1
	v_mfma_f32_16x16x32_bf16 v[48:51], v[182:185], v[198:201], v[48:51]
	v_mfma_f32_16x16x32_bf16 v[40:43], v[190:193], v[198:201], v[40:43]
	v_mfma_f32_16x16x32_bf16 v[32:35], v[182:185], v[206:209], v[32:35]
	v_mfma_f32_16x16x32_bf16 v[24:27], v[190:193], v[206:209], v[24:27]
	v_mfma_f32_16x16x32_bf16 v[16:19], v[182:185], v[214:217], v[16:19]
	v_mfma_f32_16x16x32_bf16 v[8:11], v[190:193], v[214:217], v[8:11]
	v_mfma_f32_16x16x32_bf16 v[4:7], v[182:185], v[222:225], v[4:7]
	v_mfma_f32_16x16x32_bf16 v[0:3], v[190:193], v[222:225], v[0:3]
	v_mfma_f32_16x16x32_bf16 v[48:51], v[186:189], v[202:205], v[48:51]
	v_mfma_f32_16x16x32_bf16 v[40:43], v[194:197], v[202:205], v[40:43]
	v_mfma_f32_16x16x32_bf16 v[32:35], v[186:189], v[210:213], v[32:35]
	v_mfma_f32_16x16x32_bf16 v[24:27], v[194:197], v[210:213], v[24:27]
	v_mfma_f32_16x16x32_bf16 v[16:19], v[186:189], v[218:221], v[16:19]
	s_setprio 2
	s_barrier
	v_mfma_f32_16x16x32_bf16 v[8:11], v[194:197], v[218:221], v[8:11]
	v_mfma_f32_16x16x32_bf16 v[4:7], v[186:189], v[226:229], v[4:7]
	v_mfma_f32_16x16x32_bf16 v[0:3], v[194:197], v[226:229], v[0:3]
	s_setprio 0
	s_add_i32 s49, s49, 2
	s_add_u32 s72, s72, 0x100
	s_addc_u32 s73, s73, 0
	s_add_u32 s37, s37, 0x100
	s_addc_u32 s41, s41, 0
	s_cmp_gt_u32 s49, 29
	s_cbranch_scc0 .LBB0_660
	s_and_b64 vcc, exec, s[14:15]
	s_cbranch_vccz .LBB0_663
	s_barrier

; #define PG8_STAGE(bufoff, gbase, voff) do { _Pragma("unroll") for (int _i = 0; _i < 2; ++_i) \
;         __builtin_amdgcn_global_load_lds((const unsigned*)((const char*)(gbase) + (voff)[_i]), (PG8_LAS unsigned*)(lds + (bufoff) + ldsw + _i * 8192), 16, 0, 0); } while (0)
; #define PG8_LDA(dst, b, h) do { _Pragma("unroll") for (int m = 0; m < 4; ++m) _Pragma("unroll") for (int k = 0; k < 2; ++k) dst[m][k] = *(const PG8_LAS bf16x8*)(lds + PG8_SA(b, h) + aoff + m * 2048 + k * 1024); } while (0)
; #define PG8_LDB(dst, b, h) do { _Pragma("unroll") for (int n = 0; n < 2; ++n) _Pragma("unroll") for (int k = 0; k < 2; ++k) dst[n][k] = *(const PG8_LAS bf16x8*)(lds + PG8_SB(b, h) + boff + n * 2048 + k * 1024); } while (0)
; #define PG8_MMA(ai, bj, At, Bt) do { __builtin_amdgcn_s_setprio(1); _Pragma("unroll") for (int m = 0; m < 4; ++m) _Pragma("unroll") for (int n = 0; n < 2; ++n) _Pragma("unroll") for (int k = 0; k < 2; ++k) \
;         acc[ai][bj][m][n] = __builtin_amdgcn_mfma_f32_16x16x32_bf16(Bt[n][k], At[m][k], acc[ai][bj][m][n], 0, 0, 0); __builtin_amdgcn_s_setprio(0); } while (0)
; #define PG8_WAIT_V(n) asm volatile("s_waitcnt vmcnt(" #n ")" ::: "memory")
; #define PG8_WAIT_L(n) asm volatile("s_waitcnt lgkmcnt(" #n ")" ::: "memory")
; #define PG8_BAR __builtin_amdgcn_s_barrier()
; #define PG8_SCHED __builtin_amdgcn_sched_barrier(0)
; template <class Epi, class Sched, bool ALIGN_EPI = false, bool SP2 = false>
; __device__ __forceinline__ void gemm_phase(PG8_LAS unsigned char* lds, const Gemm g, const Sched& S, const Epi& E) {
;     ...
;         for (int t = 0; t < nt; t += 2) {
;             const bool last = (t == nt - 2);
;             const char* a1 = cA + (size_t)(t + 1) * kstep;
;             const char* a2 = last ? nA : cA + (size_t)(t + 2) * kstep; const char* b2 = last ? nB : cB + (size_t)(t + 2) * kstep;
;             const char* a3 = a2 + kstep; const char* b3 = b2 + kstep;
;             if constexpr (SP2) {
;             PG8_LDB(B0, 0, 0); PG8_LDB(B1, 0, 1); PG8_SCHED; PG8_LDA(At, 0, 0); PG8_STAGE(PG8_SA(1, 1), a1 + hstep, voffA);
;             PG8_WAIT_V(8); PG8_WAIT_L(0); PG8_BAR; PG8_MMA(0, 0, At, B0); PG8_MMA(0, 1, At, B1); PG8_BAR; PG8_SCHED;
;             PG8_LDA(At, 0, 1); PG8_STAGE(PG8_SB(0, 0), b2, voffB); PG8_STAGE(PG8_SB(0, 1), b2 + hstep, voffB); PG8_STAGE(PG8_SA(0, 0), a2, voffA);
.LBB0_809:
	ds_read_b128 v[128:131], v180
	ds_read_b128 v[132:135], v180 offset:1024
	ds_read_b128 v[136:139], v180 offset:2048
	ds_read_b128 v[140:143], v180 offset:3072
	ds_read_b128 v[160:163], v181
	ds_read_b128 v[164:167], v181 offset:1024
	ds_read_b128 v[184:187], v181 offset:2048
	ds_read_b128 v[188:191], v181 offset:3072
	s_add_u32 s52, s72, 0xfff80080
	s_addc_u32 s53, s73, -1
	s_cmp_eq_u32 s92, 28
	s_cselect_b32 s77, s5, s53
	s_cselect_b32 s76, s49, s52
	s_cselect_b32 s75, s45, s91
	s_cselect_b32 s74, s89, s90
	v_lshl_add_u64 v[168:169], s[72:73], 0, v[154:155]
	s_add_i32 m0, s71, 0xc000
	ds_read_b128 v[192:195], v182
	ds_read_b128 v[196:199], v182 offset:1024
	ds_read_b128 v[200:203], v182 offset:2048
	ds_read_b128 v[204:207], v182 offset:3072
	ds_read_b128 v[208:211], v182 offset:4096
	ds_read_b128 v[212:215], v182 offset:5120
	ds_read_b128 v[216:219], v182 offset:6144
	ds_read_b128 v[220:223], v182 offset:7168
	global_load_lds_dwordx4 v[168:169], off
	s_add_i32 m0, s71, 0xe000
	v_lshl_add_u64 v[168:169], s[72:73], 0, v[156:157]
	global_load_lds_dwordx4 v[168:169], off
	s_waitcnt vmcnt(8)
	s_waitcnt lgkmcnt(0)
	s_setprio 1
	s_barrier
	v_mfma_f32_16x16x32_bf16 v[124:127], v[128:131], v[192:195], v[124:127]
	v_mfma_f32_16x16x32_bf16 v[120:123], v[136:139], v[192:195], v[120:123]
	v_mfma_f32_16x16x32_bf16 v[108:111], v[128:131], v[200:203], v[108:111]
	v_mfma_f32_16x16x32_bf16 v[104:107], v[136:139], v[200:203], v[104:107]
	v_mfma_f32_16x16x32_bf16 v[92:95], v[128:131], v[208:211], v[92:95]
	v_mfma_f32_16x16x32_bf16 v[88:91], v[136:139], v[208:211], v[88:91]
	v_mfma_f32_16x16x32_bf16 v[76:79], v[128:131], v[216:219], v[76:79]
	v_mfma_f32_16x16x32_bf16 v[72:75], v[136:139], v[216:219], v[72:75]
	v_mfma_f32_16x16x32_bf16 v[124:127], v[132:135], v[196:199], v[124:127]
	v_mfma_f32_16x16x32_bf16 v[120:123], v[140:143], v[196:199], v[120:123]
	v_mfma_f32_16x16x32_bf16 v[108:111], v[132:135], v[204:207], v[108:111]
	v_mfma_f32_16x16x32_bf16 v[104:107], v[140:143], v[204:207], v[104:107]
	v_mfma_f32_16x16x32_bf16 v[92:95], v[132:135], v[212:215], v[92:95]
	v_mfma_f32_16x16x32_bf16 v[88:91], v[140:143], v[212:215], v[88:91]
	v_mfma_f32_16x16x32_bf16 v[76:79], v[132:135], v[220:223], v[76:79]
	v_mfma_f32_16x16x32_bf16 v[72:75], v[140:143], v[220:223], v[72:75]
	s_setprio 0
	s_setprio 1
	v_mfma_f32_16x16x32_bf16 v[116:119], v[160:163], v[192:195], v[116:119]
	v_mfma_f32_16x16x32_bf16 v[112:115], v[184:187], v[192:195], v[112:115]
	v_mfma_f32_16x16x32_bf16 v[100:103], v[160:163], v[200:203], v[100:103]
	v_mfma_f32_16x16x32_bf16 v[96:99], v[184:187], v[200:203], v[96:99]
	v_mfma_f32_16x16x32_bf16 v[84:87], v[160:163], v[208:211], v[84:87]
	v_mfma_f32_16x16x32_bf16 v[80:83], v[184:187], v[208:211], v[80:83]
	v_mfma_f32_16x16x32_bf16 v[68:71], v[160:163], v[216:219], v[68:71]
	v_mfma_f32_16x16x32_bf16 v[64:67], v[184:187], v[216:219], v[64:67]
	v_mfma_f32_16x16x32_bf16 v[116:119], v[164:167], v[196:199], v[116:119]
	v_mfma_f32_16x16x32_bf16 v[112:115], v[188:191], v[196:199], v[112:115]
	v_mfma_f32_16x16x32_bf16 v[100:103], v[164:167], v[204:207], v[100:103]
	v_mfma_f32_16x16x32_bf16 v[96:99], v[188:191], v[204:207], v[96:99]
	v_mfma_f32_16x16x32_bf16 v[84:87], v[164:167], v[212:215], v[84:87]
	s_setprio 2
	s_barrier
	v_mfma_f32_16x16x32_bf16 v[80:83], v[188:191], v[212:215], v[80:83]
	v_mfma_f32_16x16x32_bf16 v[68:71], v[164:167], v[220:223], v[68:71]
	v_mfma_f32_16x16x32_bf16 v[64:67], v[188:191], v[220:223], v[64:67]
	s_setprio 0
	s_add_i32 s52, s83, s78
	v_lshl_add_u64 v[168:169], s[74:75], 0, v[148:149]
	s_mov_b32 m0, s52
	ds_read_b128 v[192:195], v182 offset:16384
	ds_read_b128 v[196:199], v182 offset:17408
	ds_read_b128 v[200:203], v182 offset:18432
	ds_read_b128 v[204:207], v182 offset:19456
	ds_read_b128 v[208:211], v182 offset:20480
	ds_read_b128 v[212:215], v182 offset:21504
	ds_read_b128 v[216:219], v182 offset:22528
	ds_read_b128 v[220:223], v182 offset:23552
	global_load_lds_dwordx4 v[168:169], off
	s_add_i32 m0, s52, 0x2000
	s_add_u32 s52, s74, 0x80000
	v_lshl_add_u64 v[224:225], s[74:75], 0, v[152:153]
	s_addc_u32 s53, s75, 0
	s_add_i32 s56, s84, s78
	global_load_lds_dwordx4 v[224:225], off
	v_lshl_add_u64 v[226:227], s[52:53], 0, v[148:149]
	s_mov_b32 m0, s56
	v_lshl_add_u64 v[228:229], s[76:77], 0, v[150:151]
	global_load_lds_dwordx4 v[226:227], off
	s_add_i32 m0, s56, 0x2000
	v_lshl_add_u64 v[226:227], s[52:53], 0, v[152:153]
	global_load_lds_dwordx4 v[226:227], off
	s_mov_b32 m0, s71
	v_lshl_add_u64 v[226:227], s[76:77], 0, v[144:145]
	global_load_lds_dwordx4 v[226:227], off
	s_mov_b32 m0, s79
	s_nop 0
	global_load_lds_dwordx4 v[228:229], off
	s_waitcnt vmcnt(8)
	s_waitcnt lgkmcnt(0)
	s_setprio 1
	s_barrier
; #define PG8_STAGE(bufoff, gbase, voff) do { _Pragma("unroll") for (int _i = 0; _i < 2; ++_i) \
;         __builtin_amdgcn_global_load_lds((const unsigned*)((const char*)(gbase) + (voff)[_i]), (PG8_LAS unsigned*)(lds + (bufoff) + ldsw + _i * 8192), 16, 0, 0); } while (0)
; #define PG8_LDA(dst, b, h) do { _Pragma("unroll") for (int m = 0; m < 4; ++m) _Pragma("unroll") for (int k = 0; k < 2; ++k) dst[m][k] = *(const PG8_LAS bf16x8*)(lds + PG8_SA(b, h) + aoff + m * 2048 + k * 1024); } while (0)
; #define PG8_LDB(dst, b, h) do { _Pragma("unroll") for (int n = 0; n < 2; ++n) _Pragma("unroll") for (int k = 0; k < 2; ++k) dst[n][k] = *(const PG8_LAS bf16x8*)(lds + PG8_SB(b, h) + boff + n * 2048 + k * 1024); } while (0)
; #define PG8_MMA(ai, bj, At, Bt) do { __builtin_amdgcn_s_setprio(1); _Pragma("unroll") for (int m = 0; m < 4; ++m) _Pragma("unroll") for (int n = 0; n < 2; ++n) _Pragma("unroll") for (int k = 0; k < 2; ++k) \
;         acc[ai][bj][m][n] = __builtin_amdgcn_mfma_f32_16x16x32_bf16(Bt[n][k], At[m][k], acc[ai][bj][m][n], 0, 0, 0); __builtin_amdgcn_s_setprio(0); } while (0)
; #define PG8_WAIT_V(n) asm volatile("s_waitcnt vmcnt(" #n ")" ::: "memory")
; #define PG8_WAIT_L(n) asm volatile("s_waitcnt lgkmcnt(" #n ")" ::: "memory")
; #define PG8_BAR __builtin_amdgcn_s_barrier()
; #define PG8_SCHED __builtin_amdgcn_sched_barrier(0)
; template <class Epi, class Sched, bool ALIGN_EPI = false, bool SP2 = false>
; __device__ __forceinline__ void gemm_phase(PG8_LAS unsigned char* lds, const Gemm g, const Sched& S, const Epi& E) {
;     ...
;             PG8_WAIT_V(8); PG8_WAIT_L(0); PG8_BAR; PG8_MMA(1, 0, At, B0); PG8_MMA(1, 1, At, B1); PG8_BAR; PG8_SCHED;
;             PG8_LDB(B0, 1, 0); PG8_LDB(B1, 1, 1); PG8_SCHED; PG8_LDA(At, 1, 0); PG8_STAGE(PG8_SA(0, 1), a2 + hstep, voffA);
;             PG8_WAIT_V(8); PG8_WAIT_L(0); PG8_BAR; PG8_MMA(0, 0, At, B0); PG8_MMA(0, 1, At, B1); PG8_BAR; PG8_SCHED;
	v_mfma_f32_16x16x32_bf16 v[60:63], v[128:131], v[192:195], v[60:63]
	v_mfma_f32_16x16x32_bf16 v[56:59], v[136:139], v[192:195], v[56:59]
	v_mfma_f32_16x16x32_bf16 v[44:47], v[128:131], v[200:203], v[44:47]
	v_mfma_f32_16x16x32_bf16 v[40:43], v[136:139], v[200:203], v[40:43]
	v_mfma_f32_16x16x32_bf16 v[28:31], v[128:131], v[208:211], v[28:31]
	v_mfma_f32_16x16x32_bf16 v[24:27], v[136:139], v[208:211], v[24:27]
	v_mfma_f32_16x16x32_bf16 v[12:15], v[128:131], v[216:219], v[12:15]
	v_mfma_f32_16x16x32_bf16 v[8:11], v[136:139], v[216:219], v[8:11]
	v_mfma_f32_16x16x32_bf16 v[60:63], v[132:135], v[196:199], v[60:63]
	v_mfma_f32_16x16x32_bf16 v[56:59], v[140:143], v[196:199], v[56:59]
	v_mfma_f32_16x16x32_bf16 v[44:47], v[132:135], v[204:207], v[44:47]
	v_mfma_f32_16x16x32_bf16 v[40:43], v[140:143], v[204:207], v[40:43]
	v_mfma_f32_16x16x32_bf16 v[28:31], v[132:135], v[212:215], v[28:31]
	v_mfma_f32_16x16x32_bf16 v[24:27], v[140:143], v[212:215], v[24:27]
	v_mfma_f32_16x16x32_bf16 v[12:15], v[132:135], v[220:223], v[12:15]
	v_mfma_f32_16x16x32_bf16 v[8:11], v[140:143], v[220:223], v[8:11]
	s_setprio 0
	s_setprio 1
	v_mfma_f32_16x16x32_bf16 v[52:55], v[160:163], v[192:195], v[52:55]
	v_mfma_f32_16x16x32_bf16 v[48:51], v[184:187], v[192:195], v[48:51]
	v_mfma_f32_16x16x32_bf16 v[36:39], v[160:163], v[200:203], v[36:39]
	v_mfma_f32_16x16x32_bf16 v[32:35], v[184:187], v[200:203], v[32:35]
	v_mfma_f32_16x16x32_bf16 v[20:23], v[160:163], v[208:211], v[20:23]
	v_mfma_f32_16x16x32_bf16 v[16:19], v[184:187], v[208:211], v[16:19]
	v_mfma_f32_16x16x32_bf16 v[4:7], v[160:163], v[216:219], v[4:7]
	v_mfma_f32_16x16x32_bf16 v[0:3], v[184:187], v[216:219], v[0:3]
	v_mfma_f32_16x16x32_bf16 v[52:55], v[164:167], v[196:199], v[52:55]
	v_mfma_f32_16x16x32_bf16 v[48:51], v[188:191], v[196:199], v[48:51]
	v_mfma_f32_16x16x32_bf16 v[36:39], v[164:167], v[204:207], v[36:39]
	v_mfma_f32_16x16x32_bf16 v[32:35], v[188:191], v[204:207], v[32:35]
	v_mfma_f32_16x16x32_bf16 v[20:23], v[164:167], v[212:215], v[20:23]
	s_setprio 2
	s_barrier
	v_mfma_f32_16x16x32_bf16 v[16:19], v[188:191], v[212:215], v[16:19]
	v_mfma_f32_16x16x32_bf16 v[4:7], v[164:167], v[220:223], v[4:7]
	v_mfma_f32_16x16x32_bf16 v[0:3], v[188:191], v[220:223], v[0:3]
	s_setprio 0
	s_add_i32 s56, 0, 0x18000
	s_add_i32 s57, 0, 0x1c000
	v_add_u32_e32 v140, s56, v171
	v_add_u32_e32 v188, s57, v171
	ds_read_b128 v[128:131], v140
	ds_read_b128 v[132:135], v140 offset:1024
	ds_read_b128 v[136:139], v140 offset:2048
	ds_read_b128 v[140:143], v140 offset:3072
	ds_read_b128 v[160:163], v188
	ds_read_b128 v[164:167], v188 offset:1024
	ds_read_b128 v[184:187], v188 offset:2048
	ds_read_b128 v[188:191], v188 offset:3072
	s_add_u32 s52, s76, 0x80000
	s_addc_u32 s53, s77, 0
	s_mov_b32 m0, s80
	v_lshl_add_u64 v[230:231], s[52:53], 0, v[144:145]
	ds_read_b128 v[192:195], v182 offset:32768
	ds_read_b128 v[196:199], v182 offset:33792
	ds_read_b128 v[200:203], v182 offset:34816
	ds_read_b128 v[204:207], v182 offset:35840
	ds_read_b128 v[208:211], v182 offset:36864
	ds_read_b128 v[212:215], v182 offset:37888
	ds_read_b128 v[216:219], v182 offset:38912
	ds_read_b128 v[220:223], v182 offset:39936
	global_load_lds_dwordx4 v[230:231], off
	s_mov_b32 m0, s81
	v_lshl_add_u64 v[230:231], s[52:53], 0, v[150:151]
	global_load_lds_dwordx4 v[230:231], off
	s_waitcnt vmcnt(8)
	s_waitcnt lgkmcnt(0)
	s_setprio 1
	s_barrier
	v_mfma_f32_16x16x32_bf16 v[124:127], v[128:131], v[192:195], v[124:127]
	v_mfma_f32_16x16x32_bf16 v[120:123], v[136:139], v[192:195], v[120:123]
	v_mfma_f32_16x16x32_bf16 v[108:111], v[128:131], v[200:203], v[108:111]
	v_mfma_f32_16x16x32_bf16 v[104:107], v[136:139], v[200:203], v[104:107]
	v_mfma_f32_16x16x32_bf16 v[92:95], v[128:131], v[208:211], v[92:95]
	v_mfma_f32_16x16x32_bf16 v[88:91], v[136:139], v[208:211], v[88:91]
	v_mfma_f32_16x16x32_bf16 v[76:79], v[128:131], v[216:219], v[76:79]
	v_mfma_f32_16x16x32_bf16 v[72:75], v[136:139], v[216:219], v[72:75]
	v_mfma_f32_16x16x32_bf16 v[124:127], v[132:135], v[196:199], v[124:127]
	v_mfma_f32_16x16x32_bf16 v[120:123], v[140:143], v[196:199], v[120:123]
	v_mfma_f32_16x16x32_bf16 v[108:111], v[132:135], v[204:207], v[108:111]
	v_mfma_f32_16x16x32_bf16 v[104:107], v[140:143], v[204:207], v[104:107]
	v_mfma_f32_16x16x32_bf16 v[92:95], v[132:135], v[212:215], v[92:95]
	v_mfma_f32_16x16x32_bf16 v[88:91], v[140:143], v[212:215], v[88:91]
	v_mfma_f32_16x16x32_bf16 v[76:79], v[132:135], v[220:223], v[76:79]
	v_mfma_f32_16x16x32_bf16 v[72:75], v[140:143], v[220:223], v[72:75]
	s_setprio 0
	s_setprio 1
	v_mfma_f32_16x16x32_bf16 v[116:119], v[160:163], v[192:195], v[116:119]
	v_mfma_f32_16x16x32_bf16 v[112:115], v[184:187], v[192:195], v[112:115]
	v_mfma_f32_16x16x32_bf16 v[100:103], v[160:163], v[200:203], v[100:103]
	v_mfma_f32_16x16x32_bf16 v[96:99], v[184:187], v[200:203], v[96:99]
	v_mfma_f32_16x16x32_bf16 v[84:87], v[160:163], v[208:211], v[84:87]
	v_mfma_f32_16x16x32_bf16 v[80:83], v[184:187], v[208:211], v[80:83]
	v_mfma_f32_16x16x32_bf16 v[68:71], v[160:163], v[216:219], v[68:71]
	v_mfma_f32_16x16x32_bf16 v[64:67], v[184:187], v[216:219], v[64:67]
	v_mfma_f32_16x16x32_bf16 v[116:119], v[164:167], v[196:199], v[116:119]
	v_mfma_f32_16x16x32_bf16 v[112:115], v[188:191], v[196:199], v[112:115]
	v_mfma_f32_16x16x32_bf16 v[100:103], v[164:167], v[204:207], v[100:103]
	v_mfma_f32_16x16x32_bf16 v[96:99], v[188:191], v[204:207], v[96:99]
	v_mfma_f32_16x16x32_bf16 v[84:87], v[164:167], v[212:215], v[84:87]
	s_setprio 2
	s_barrier
; #define PG8_STAGE(bufoff, gbase, voff) do { _Pragma("unroll") for (int _i = 0; _i < 2; ++_i) \
;         __builtin_amdgcn_global_load_lds((const unsigned*)((const char*)(gbase) + (voff)[_i]), (PG8_LAS unsigned*)(lds + (bufoff) + ldsw + _i * 8192), 16, 0, 0); } while (0)
; #define PG8_LDA(dst, b, h) do { _Pragma("unroll") for (int m = 0; m < 4; ++m) _Pragma("unroll") for (int k = 0; k < 2; ++k) dst[m][k] = *(const PG8_LAS bf16x8*)(lds + PG8_SA(b, h) + aoff + m * 2048 + k * 1024); } while (0)
; #define PG8_MMA(ai, bj, At, Bt) do { __builtin_amdgcn_s_setprio(1); _Pragma("unroll") for (int m = 0; m < 4; ++m) _Pragma("unroll") for (int n = 0; n < 2; ++n) _Pragma("unroll") for (int k = 0; k < 2; ++k) \
;         acc[ai][bj][m][n] = __builtin_amdgcn_mfma_f32_16x16x32_bf16(Bt[n][k], At[m][k], acc[ai][bj][m][n], 0, 0, 0); __builtin_amdgcn_s_setprio(0); } while (0)
; #define PG8_WAIT_V(n) asm volatile("s_waitcnt vmcnt(" #n ")" ::: "memory")
; #define PG8_WAIT_L(n) asm volatile("s_waitcnt lgkmcnt(" #n ")" ::: "memory")
; #define PG8_BAR __builtin_amdgcn_s_barrier()
; #define PG8_SCHED __builtin_amdgcn_sched_barrier(0)
; template <class Epi, class Sched, bool ALIGN_EPI = false, bool SP2 = false>
; __device__ __forceinline__ void gemm_phase(PG8_LAS unsigned char* lds, const Gemm g, const Sched& S, const Epi& E) {
;     ...
;         for (int t = 0; t < nt; t += 2) {
;             const bool last = (t == nt - 2);
;     ...
;             PG8_WAIT_V(8); PG8_WAIT_L(0); PG8_BAR; PG8_MMA(0, 0, At, B0); PG8_MMA(0, 1, At, B1); PG8_BAR; PG8_SCHED;
;             PG8_LDA(At, 1, 1); PG8_STAGE(PG8_SB(1, 0), b3, voffB); PG8_STAGE(PG8_SB(1, 1), b3 + hstep, voffB); PG8_STAGE(PG8_SA(1, 0), a3, voffA);
;             PG8_WAIT_V(8); PG8_WAIT_L(0); PG8_BAR; PG8_MMA(1, 0, At, B0); PG8_MMA(1, 1, At, B1); PG8_BAR; PG8_SCHED;
	v_mfma_f32_16x16x32_bf16 v[80:83], v[188:191], v[212:215], v[80:83]
	v_mfma_f32_16x16x32_bf16 v[68:71], v[164:167], v[220:223], v[68:71]
	v_mfma_f32_16x16x32_bf16 v[64:67], v[188:191], v[220:223], v[64:67]
	s_setprio 0
	s_add_i32 s52, s56, s78
	v_lshl_add_u64 v[168:169], v[168:169], 0, s[40:41]
	s_mov_b32 m0, s52
	ds_read_b128 v[192:195], v182 offset:49152
	ds_read_b128 v[196:199], v182 offset:50176
	ds_read_b128 v[200:203], v182 offset:51200
	ds_read_b128 v[204:207], v182 offset:52224
	ds_read_b128 v[208:211], v182 offset:53248
	ds_read_b128 v[212:215], v182 offset:54272
	ds_read_b128 v[216:219], v182 offset:55296
	ds_read_b128 v[220:223], v182 offset:56320
	global_load_lds_dwordx4 v[168:169], off
	s_add_i32 m0, s52, 0x2000
	s_add_u32 s52, s74, 0x80080
	v_lshl_add_u64 v[168:169], v[224:225], 0, s[40:41]
	s_addc_u32 s53, s75, 0
	s_add_i32 s56, s57, s78
	global_load_lds_dwordx4 v[168:169], off
	s_mov_b32 m0, s56
	v_lshl_add_u64 v[168:169], s[52:53], 0, v[148:149]
	global_load_lds_dwordx4 v[168:169], off
	s_add_i32 m0, s56, 0x2000
	v_lshl_add_u64 v[168:169], s[52:53], 0, v[152:153]
	global_load_lds_dwordx4 v[168:169], off
	s_mov_b32 m0, s3
	v_lshl_add_u64 v[168:169], v[226:227], 0, s[40:41]
	global_load_lds_dwordx4 v[168:169], off
	s_mov_b32 m0, s28
	v_lshl_add_u64 v[168:169], v[228:229], 0, s[40:41]
	global_load_lds_dwordx4 v[168:169], off
	s_waitcnt vmcnt(8)
	s_waitcnt lgkmcnt(0)
	s_setprio 1
	s_barrier
	v_mfma_f32_16x16x32_bf16 v[60:63], v[128:131], v[192:195], v[60:63]
	v_mfma_f32_16x16x32_bf16 v[56:59], v[136:139], v[192:195], v[56:59]
	v_mfma_f32_16x16x32_bf16 v[44:47], v[128:131], v[200:203], v[44:47]
	v_mfma_f32_16x16x32_bf16 v[40:43], v[136:139], v[200:203], v[40:43]
	v_mfma_f32_16x16x32_bf16 v[28:31], v[128:131], v[208:211], v[28:31]
	v_mfma_f32_16x16x32_bf16 v[24:27], v[136:139], v[208:211], v[24:27]
	v_mfma_f32_16x16x32_bf16 v[12:15], v[128:131], v[216:219], v[12:15]
	v_mfma_f32_16x16x32_bf16 v[8:11], v[136:139], v[216:219], v[8:11]
	v_mfma_f32_16x16x32_bf16 v[60:63], v[132:135], v[196:199], v[60:63]
	v_mfma_f32_16x16x32_bf16 v[56:59], v[140:143], v[196:199], v[56:59]
	v_mfma_f32_16x16x32_bf16 v[44:47], v[132:135], v[204:207], v[44:47]
	v_mfma_f32_16x16x32_bf16 v[40:43], v[140:143], v[204:207], v[40:43]
	v_mfma_f32_16x16x32_bf16 v[28:31], v[132:135], v[212:215], v[28:31]
	v_mfma_f32_16x16x32_bf16 v[24:27], v[140:143], v[212:215], v[24:27]
	v_mfma_f32_16x16x32_bf16 v[12:15], v[132:135], v[220:223], v[12:15]
	v_mfma_f32_16x16x32_bf16 v[8:11], v[140:143], v[220:223], v[8:11]
	s_setprio 0
	s_setprio 1
	v_mfma_f32_16x16x32_bf16 v[52:55], v[160:163], v[192:195], v[52:55]
	v_mfma_f32_16x16x32_bf16 v[48:51], v[184:187], v[192:195], v[48:51]
	v_mfma_f32_16x16x32_bf16 v[36:39], v[160:163], v[200:203], v[36:39]
	v_mfma_f32_16x16x32_bf16 v[32:35], v[184:187], v[200:203], v[32:35]
	v_mfma_f32_16x16x32_bf16 v[20:23], v[160:163], v[208:211], v[20:23]
	v_mfma_f32_16x16x32_bf16 v[16:19], v[184:187], v[208:211], v[16:19]
	v_mfma_f32_16x16x32_bf16 v[4:7], v[160:163], v[216:219], v[4:7]
	v_mfma_f32_16x16x32_bf16 v[0:3], v[184:187], v[216:219], v[0:3]
	v_mfma_f32_16x16x32_bf16 v[52:55], v[164:167], v[196:199], v[52:55]
	v_mfma_f32_16x16x32_bf16 v[48:51], v[188:191], v[196:199], v[48:51]
	v_mfma_f32_16x16x32_bf16 v[36:39], v[164:167], v[204:207], v[36:39]
	v_mfma_f32_16x16x32_bf16 v[32:35], v[188:191], v[204:207], v[32:35]
	v_mfma_f32_16x16x32_bf16 v[20:23], v[164:167], v[212:215], v[20:23]
	s_setprio 2
	s_barrier
	v_mfma_f32_16x16x32_bf16 v[16:19], v[188:191], v[212:215], v[16:19]
	v_mfma_f32_16x16x32_bf16 v[4:7], v[164:167], v[220:223], v[4:7]
	v_mfma_f32_16x16x32_bf16 v[0:3], v[188:191], v[220:223], v[0:3]
	s_setprio 0
	s_add_i32 s92, s92, 2
	s_add_u32 s72, s72, 0x100
	s_addc_u32 s73, s73, 0
	s_add_u32 s90, s90, 0x100
	s_addc_u32 s91, s91, 0
	s_cmp_gt_u32 s92, 29
	s_cbranch_scc0 .LBB0_809
	s_and_b64 vcc, exec, s[42:43]
	s_cbranch_vccz .LBB0_812
	s_barrier

; #define PG8_STAGE(bufoff, gbase, voff) do { _Pragma("unroll") for (int _i = 0; _i < 2; ++_i) \
;         __builtin_amdgcn_global_load_lds((const unsigned*)((const char*)(gbase) + (voff)[_i]), (PG8_LAS unsigned*)(lds + (bufoff) + ldsw + _i * 8192), 16, 0, 0); } while (0)
; #define PG8_LDA(dst, b, h) do { _Pragma("unroll") for (int m = 0; m < 4; ++m) _Pragma("unroll") for (int k = 0; k < 2; ++k) dst[m][k] = *(const PG8_LAS bf16x8*)(lds + PG8_SA(b, h) + aoff + m * 2048 + k * 1024); } while (0)
; #define PG8_LDB(dst, b, h) do { _Pragma("unroll") for (int n = 0; n < 2; ++n) _Pragma("unroll") for (int k = 0; k < 2; ++k) dst[n][k] = *(const PG8_LAS bf16x8*)(lds + PG8_SB(b, h) + boff + n * 2048 + k * 1024); } while (0)
; #define PG8_MMA(ai, bj, At, Bt) do { __builtin_amdgcn_s_setprio(1); _Pragma("unroll") for (int m = 0; m < 4; ++m) _Pragma("unroll") for (int n = 0; n < 2; ++n) _Pragma("unroll") for (int k = 0; k < 2; ++k) \
;         acc[ai][bj][m][n] = __builtin_amdgcn_mfma_f32_16x16x32_bf16(Bt[n][k], At[m][k], acc[ai][bj][m][n], 0, 0, 0); __builtin_amdgcn_s_setprio(0); } while (0)
; #define PG8_WAIT_V(n) asm volatile("s_waitcnt vmcnt(" #n ")" ::: "memory")
; #define PG8_WAIT_L(n) asm volatile("s_waitcnt lgkmcnt(" #n ")" ::: "memory")
; #define PG8_BAR __builtin_amdgcn_s_barrier()
; #define PG8_SCHED __builtin_amdgcn_sched_barrier(0)
; template <class Epi, class Sched, bool ALIGN_EPI = false, bool SP2 = false>
; __device__ __forceinline__ void gemm_phase(PG8_LAS unsigned char* lds, const Gemm g, const Sched& S, const Epi& E) {
;     ...
;         for (int t = 0; t < nt; t += 2) {
;             const bool last = (t == nt - 2);
;             const char* a1 = cA + (size_t)(t + 1) * kstep;
;             const char* a2 = last ? nA : cA + (size_t)(t + 2) * kstep; const char* b2 = last ? nB : cB + (size_t)(t + 2) * kstep;
;             const char* a3 = a2 + kstep; const char* b3 = b2 + kstep;
;             if constexpr (SP2) {
;             PG8_LDB(B0, 0, 0); PG8_LDB(B1, 0, 1); PG8_SCHED; PG8_LDA(At, 0, 0); PG8_STAGE(PG8_SA(1, 1), a1 + hstep, voffA);
;             PG8_WAIT_V(8); PG8_WAIT_L(0); PG8_BAR; PG8_MMA(0, 0, At, B0); PG8_MMA(0, 1, At, B1); PG8_BAR; PG8_SCHED;
;             PG8_LDA(At, 0, 1); PG8_STAGE(PG8_SB(0, 0), b2, voffB); PG8_STAGE(PG8_SB(0, 1), b2 + hstep, voffB); PG8_STAGE(PG8_SA(0, 0), a2, voffA);
.LBB0_1051:
	ds_read_b128 v[128:131], v205
	ds_read_b128 v[132:135], v205 offset:1024
	ds_read_b128 v[154:157], v205 offset:2048
	ds_read_b128 v[158:161], v205 offset:3072
	ds_read_b128 v[162:165], v206
	ds_read_b128 v[166:169], v206 offset:1024
	ds_read_b128 v[170:173], v206 offset:2048
	ds_read_b128 v[174:177], v206 offset:3072
	s_add_u32 s54, s52, 0xfff80080
	s_addc_u32 s55, s53, -1
	s_cmp_eq_u32 s77, 28
	s_cselect_b32 s57, s43, s55
	s_cselect_b32 s56, s49, s54
	s_cselect_b32 s55, s37, s76
	s_cselect_b32 s54, s51, s75
	v_lshl_add_u64 v[218:219], s[52:53], 0, v[144:145]
	s_add_i32 m0, s61, 0xc000
	ds_read_b128 v[178:181], v207
	ds_read_b128 v[182:185], v207 offset:1024
	ds_read_b128 v[186:189], v207 offset:2048
	ds_read_b128 v[190:193], v207 offset:3072
	ds_read_b128 v[194:197], v207 offset:4096
	ds_read_b128 v[198:201], v207 offset:5120
	ds_read_b128 v[210:213], v207 offset:6144
	ds_read_b128 v[214:217], v207 offset:7168
	global_load_lds_dwordx4 v[218:219], off
	s_add_i32 m0, s61, 0xe000
	v_lshl_add_u64 v[218:219], s[52:53], 0, v[148:149]
	global_load_lds_dwordx4 v[218:219], off
	s_waitcnt vmcnt(8)
	s_waitcnt lgkmcnt(0)
	s_setprio 1
	s_barrier
	v_mfma_f32_16x16x32_bf16 v[124:127], v[128:131], v[178:181], v[124:127]
	v_mfma_f32_16x16x32_bf16 v[120:123], v[154:157], v[178:181], v[120:123]
	v_mfma_f32_16x16x32_bf16 v[116:119], v[128:131], v[186:189], v[116:119]
	v_mfma_f32_16x16x32_bf16 v[112:115], v[154:157], v[186:189], v[112:115]
	v_mfma_f32_16x16x32_bf16 v[108:111], v[128:131], v[194:197], v[108:111]
	v_mfma_f32_16x16x32_bf16 v[104:107], v[154:157], v[194:197], v[104:107]
	v_mfma_f32_16x16x32_bf16 v[100:103], v[128:131], v[210:213], v[100:103]
	v_mfma_f32_16x16x32_bf16 v[96:99], v[154:157], v[210:213], v[96:99]
	v_mfma_f32_16x16x32_bf16 v[124:127], v[132:135], v[182:185], v[124:127]
	v_mfma_f32_16x16x32_bf16 v[120:123], v[158:161], v[182:185], v[120:123]
	v_mfma_f32_16x16x32_bf16 v[116:119], v[132:135], v[190:193], v[116:119]
	v_mfma_f32_16x16x32_bf16 v[112:115], v[158:161], v[190:193], v[112:115]
	v_mfma_f32_16x16x32_bf16 v[108:111], v[132:135], v[198:201], v[108:111]
	v_mfma_f32_16x16x32_bf16 v[104:107], v[158:161], v[198:201], v[104:107]
	v_mfma_f32_16x16x32_bf16 v[100:103], v[132:135], v[214:217], v[100:103]
	v_mfma_f32_16x16x32_bf16 v[96:99], v[158:161], v[214:217], v[96:99]
	s_setprio 0
	s_setprio 1
	v_mfma_f32_16x16x32_bf16 v[60:63], v[162:165], v[178:181], v[60:63]
	v_mfma_f32_16x16x32_bf16 v[56:59], v[170:173], v[178:181], v[56:59]
	v_mfma_f32_16x16x32_bf16 v[52:55], v[162:165], v[186:189], v[52:55]
	v_mfma_f32_16x16x32_bf16 v[48:51], v[170:173], v[186:189], v[48:51]
	v_mfma_f32_16x16x32_bf16 v[44:47], v[162:165], v[194:197], v[44:47]
	v_mfma_f32_16x16x32_bf16 v[40:43], v[170:173], v[194:197], v[40:43]
	v_mfma_f32_16x16x32_bf16 v[36:39], v[162:165], v[210:213], v[36:39]
	v_mfma_f32_16x16x32_bf16 v[32:35], v[170:173], v[210:213], v[32:35]
	v_mfma_f32_16x16x32_bf16 v[60:63], v[166:169], v[182:185], v[60:63]
	v_mfma_f32_16x16x32_bf16 v[56:59], v[174:177], v[182:185], v[56:59]
	v_mfma_f32_16x16x32_bf16 v[52:55], v[166:169], v[190:193], v[52:55]
	v_mfma_f32_16x16x32_bf16 v[48:51], v[174:177], v[190:193], v[48:51]
	v_mfma_f32_16x16x32_bf16 v[44:47], v[166:169], v[198:201], v[44:47]
	s_setprio 2
	s_barrier
	v_mfma_f32_16x16x32_bf16 v[40:43], v[174:177], v[198:201], v[40:43]
	v_mfma_f32_16x16x32_bf16 v[36:39], v[166:169], v[214:217], v[36:39]
	v_mfma_f32_16x16x32_bf16 v[32:35], v[174:177], v[214:217], v[32:35]
	s_setprio 0
	s_add_i32 s78, s33, s60
	v_lshl_add_u64 v[218:219], s[54:55], 0, v[138:139]
	s_mov_b32 m0, s78
	ds_read_b128 v[178:181], v207 offset:16384
	ds_read_b128 v[182:185], v207 offset:17408
	ds_read_b128 v[186:189], v207 offset:18432
	ds_read_b128 v[190:193], v207 offset:19456
	ds_read_b128 v[194:197], v207 offset:20480
	ds_read_b128 v[198:201], v207 offset:21504
	ds_read_b128 v[210:213], v207 offset:22528
	ds_read_b128 v[214:217], v207 offset:23552
	global_load_lds_dwordx4 v[218:219], off
	s_add_i32 m0, s78, 0x2000
	s_add_u32 s78, s54, 0x80000
	v_lshl_add_u64 v[220:221], s[54:55], 0, v[142:143]
	s_addc_u32 s79, s55, 0
	s_add_i32 s80, s74, s60
	global_load_lds_dwordx4 v[220:221], off
	v_lshl_add_u64 v[222:223], s[78:79], 0, v[138:139]
	s_mov_b32 m0, s80
	v_lshl_add_u64 v[224:225], s[56:57], 0, v[140:141]
	global_load_lds_dwordx4 v[222:223], off
	s_add_i32 m0, s80, 0x2000
	v_lshl_add_u64 v[222:223], s[78:79], 0, v[142:143]
	global_load_lds_dwordx4 v[222:223], off
	s_mov_b32 m0, s61
	v_lshl_add_u64 v[222:223], s[56:57], 0, v[136:137]
	global_load_lds_dwordx4 v[222:223], off
	s_mov_b32 m0, s62
	s_nop 0
	global_load_lds_dwordx4 v[224:225], off
	s_waitcnt vmcnt(8)
	s_waitcnt lgkmcnt(0)
	s_setprio 1
	s_barrier
; #define PG8_STAGE(bufoff, gbase, voff) do { _Pragma("unroll") for (int _i = 0; _i < 2; ++_i) \
;         __builtin_amdgcn_global_load_lds((const unsigned*)((const char*)(gbase) + (voff)[_i]), (PG8_LAS unsigned*)(lds + (bufoff) + ldsw + _i * 8192), 16, 0, 0); } while (0)
; #define PG8_LDA(dst, b, h) do { _Pragma("unroll") for (int m = 0; m < 4; ++m) _Pragma("unroll") for (int k = 0; k < 2; ++k) dst[m][k] = *(const PG8_LAS bf16x8*)(lds + PG8_SA(b, h) + aoff + m * 2048 + k * 1024); } while (0)
; #define PG8_LDB(dst, b, h) do { _Pragma("unroll") for (int n = 0; n < 2; ++n) _Pragma("unroll") for (int k = 0; k < 2; ++k) dst[n][k] = *(const PG8_LAS bf16x8*)(lds + PG8_SB(b, h) + boff + n * 2048 + k * 1024); } while (0)
; #define PG8_MMA(ai, bj, At, Bt) do { __builtin_amdgcn_s_setprio(1); _Pragma("unroll") for (int m = 0; m < 4; ++m) _Pragma("unroll") for (int n = 0; n < 2; ++n) _Pragma("unroll") for (int k = 0; k < 2; ++k) \
;         acc[ai][bj][m][n] = __builtin_amdgcn_mfma_f32_16x16x32_bf16(Bt[n][k], At[m][k], acc[ai][bj][m][n], 0, 0, 0); __builtin_amdgcn_s_setprio(0); } while (0)
; #define PG8_WAIT_V(n) asm volatile("s_waitcnt vmcnt(" #n ")" ::: "memory")
; #define PG8_WAIT_L(n) asm volatile("s_waitcnt lgkmcnt(" #n ")" ::: "memory")
; #define PG8_BAR __builtin_amdgcn_s_barrier()
; #define PG8_SCHED __builtin_amdgcn_sched_barrier(0)
; template <class Epi, class Sched, bool ALIGN_EPI = false, bool SP2 = false>
; __device__ __forceinline__ void gemm_phase(PG8_LAS unsigned char* lds, const Gemm g, const Sched& S, const Epi& E) {
;     ...
;             PG8_WAIT_V(8); PG8_WAIT_L(0); PG8_BAR; PG8_MMA(1, 0, At, B0); PG8_MMA(1, 1, At, B1); PG8_BAR; PG8_SCHED;
;             PG8_LDB(B0, 1, 0); PG8_LDB(B1, 1, 1); PG8_SCHED; PG8_LDA(At, 1, 0); PG8_STAGE(PG8_SA(0, 1), a2 + hstep, voffA);
;             PG8_WAIT_V(8); PG8_WAIT_L(0); PG8_BAR; PG8_MMA(0, 0, At, B0); PG8_MMA(0, 1, At, B1); PG8_BAR; PG8_SCHED;
	v_mfma_f32_16x16x32_bf16 v[92:95], v[128:131], v[178:181], v[92:95]
	v_mfma_f32_16x16x32_bf16 v[88:91], v[154:157], v[178:181], v[88:91]
	v_mfma_f32_16x16x32_bf16 v[84:87], v[128:131], v[186:189], v[84:87]
	v_mfma_f32_16x16x32_bf16 v[80:83], v[154:157], v[186:189], v[80:83]
	v_mfma_f32_16x16x32_bf16 v[76:79], v[128:131], v[194:197], v[76:79]
	v_mfma_f32_16x16x32_bf16 v[72:75], v[154:157], v[194:197], v[72:75]
	v_mfma_f32_16x16x32_bf16 v[68:71], v[128:131], v[210:213], v[68:71]
	v_mfma_f32_16x16x32_bf16 v[64:67], v[154:157], v[210:213], v[64:67]
	v_mfma_f32_16x16x32_bf16 v[92:95], v[132:135], v[182:185], v[92:95]
	v_mfma_f32_16x16x32_bf16 v[88:91], v[158:161], v[182:185], v[88:91]
	v_mfma_f32_16x16x32_bf16 v[84:87], v[132:135], v[190:193], v[84:87]
	v_mfma_f32_16x16x32_bf16 v[80:83], v[158:161], v[190:193], v[80:83]
	v_mfma_f32_16x16x32_bf16 v[76:79], v[132:135], v[198:201], v[76:79]
	v_mfma_f32_16x16x32_bf16 v[72:75], v[158:161], v[198:201], v[72:75]
	v_mfma_f32_16x16x32_bf16 v[68:71], v[132:135], v[214:217], v[68:71]
	v_mfma_f32_16x16x32_bf16 v[64:67], v[158:161], v[214:217], v[64:67]
	s_setprio 0
	s_setprio 1
	v_mfma_f32_16x16x32_bf16 v[28:31], v[162:165], v[178:181], v[28:31]
	v_mfma_f32_16x16x32_bf16 v[24:27], v[170:173], v[178:181], v[24:27]
	v_mfma_f32_16x16x32_bf16 v[20:23], v[162:165], v[186:189], v[20:23]
	v_mfma_f32_16x16x32_bf16 v[16:19], v[170:173], v[186:189], v[16:19]
	v_mfma_f32_16x16x32_bf16 v[12:15], v[162:165], v[194:197], v[12:15]
	v_mfma_f32_16x16x32_bf16 v[8:11], v[170:173], v[194:197], v[8:11]
	v_mfma_f32_16x16x32_bf16 v[4:7], v[162:165], v[210:213], v[4:7]
	v_mfma_f32_16x16x32_bf16 v[0:3], v[170:173], v[210:213], v[0:3]
	v_mfma_f32_16x16x32_bf16 v[28:31], v[166:169], v[182:185], v[28:31]
	v_mfma_f32_16x16x32_bf16 v[24:27], v[174:177], v[182:185], v[24:27]
	v_mfma_f32_16x16x32_bf16 v[20:23], v[166:169], v[190:193], v[20:23]
	v_mfma_f32_16x16x32_bf16 v[16:19], v[174:177], v[190:193], v[16:19]
	v_mfma_f32_16x16x32_bf16 v[12:15], v[166:169], v[198:201], v[12:15]
	s_setprio 2
	s_barrier
	v_mfma_f32_16x16x32_bf16 v[8:11], v[174:177], v[198:201], v[8:11]
	v_mfma_f32_16x16x32_bf16 v[4:7], v[166:169], v[214:217], v[4:7]
	v_mfma_f32_16x16x32_bf16 v[0:3], v[174:177], v[214:217], v[0:3]
	s_setprio 0
	s_add_i32 s78, 0, 0x18000
	s_add_i32 s79, 0, 0x1c000
	v_add_u32_e32 v158, s78, v203
	v_add_u32_e32 v174, s79, v203
	ds_read_b128 v[128:131], v158
	ds_read_b128 v[132:135], v158 offset:1024
	ds_read_b128 v[154:157], v158 offset:2048
	ds_read_b128 v[158:161], v158 offset:3072
	ds_read_b128 v[162:165], v174
	ds_read_b128 v[166:169], v174 offset:1024
	ds_read_b128 v[170:173], v174 offset:2048
	ds_read_b128 v[174:177], v174 offset:3072
	s_add_u32 s56, s56, 0x80000
	s_addc_u32 s57, s57, 0
	s_mov_b32 m0, s63
	v_lshl_add_u64 v[226:227], s[56:57], 0, v[136:137]
	ds_read_b128 v[178:181], v207 offset:32768
	ds_read_b128 v[182:185], v207 offset:33792
	ds_read_b128 v[186:189], v207 offset:34816
	ds_read_b128 v[190:193], v207 offset:35840
	ds_read_b128 v[194:197], v207 offset:36864
	ds_read_b128 v[198:201], v207 offset:37888
	ds_read_b128 v[210:213], v207 offset:38912
	ds_read_b128 v[214:217], v207 offset:39936
	global_load_lds_dwordx4 v[226:227], off
	s_mov_b32 m0, s64
	v_lshl_add_u64 v[226:227], s[56:57], 0, v[140:141]
	global_load_lds_dwordx4 v[226:227], off
	s_waitcnt vmcnt(8)
	s_waitcnt lgkmcnt(0)
	s_setprio 1
	s_barrier
	v_mfma_f32_16x16x32_bf16 v[124:127], v[128:131], v[178:181], v[124:127]
	v_mfma_f32_16x16x32_bf16 v[120:123], v[154:157], v[178:181], v[120:123]
	v_mfma_f32_16x16x32_bf16 v[116:119], v[128:131], v[186:189], v[116:119]
	v_mfma_f32_16x16x32_bf16 v[112:115], v[154:157], v[186:189], v[112:115]
	v_mfma_f32_16x16x32_bf16 v[108:111], v[128:131], v[194:197], v[108:111]
	v_mfma_f32_16x16x32_bf16 v[104:107], v[154:157], v[194:197], v[104:107]
	v_mfma_f32_16x16x32_bf16 v[100:103], v[128:131], v[210:213], v[100:103]
	v_mfma_f32_16x16x32_bf16 v[96:99], v[154:157], v[210:213], v[96:99]
	v_mfma_f32_16x16x32_bf16 v[124:127], v[132:135], v[182:185], v[124:127]
	v_mfma_f32_16x16x32_bf16 v[120:123], v[158:161], v[182:185], v[120:123]
	v_mfma_f32_16x16x32_bf16 v[116:119], v[132:135], v[190:193], v[116:119]
	v_mfma_f32_16x16x32_bf16 v[112:115], v[158:161], v[190:193], v[112:115]
	v_mfma_f32_16x16x32_bf16 v[108:111], v[132:135], v[198:201], v[108:111]
	v_mfma_f32_16x16x32_bf16 v[104:107], v[158:161], v[198:201], v[104:107]
	v_mfma_f32_16x16x32_bf16 v[100:103], v[132:135], v[214:217], v[100:103]
	v_mfma_f32_16x16x32_bf16 v[96:99], v[158:161], v[214:217], v[96:99]
	s_setprio 0
	s_setprio 1
	v_mfma_f32_16x16x32_bf16 v[60:63], v[162:165], v[178:181], v[60:63]
	v_mfma_f32_16x16x32_bf16 v[56:59], v[170:173], v[178:181], v[56:59]
	v_mfma_f32_16x16x32_bf16 v[52:55], v[162:165], v[186:189], v[52:55]
	v_mfma_f32_16x16x32_bf16 v[48:51], v[170:173], v[186:189], v[48:51]
	v_mfma_f32_16x16x32_bf16 v[44:47], v[162:165], v[194:197], v[44:47]
	v_mfma_f32_16x16x32_bf16 v[40:43], v[170:173], v[194:197], v[40:43]
	v_mfma_f32_16x16x32_bf16 v[36:39], v[162:165], v[210:213], v[36:39]
	v_mfma_f32_16x16x32_bf16 v[32:35], v[170:173], v[210:213], v[32:35]
	v_mfma_f32_16x16x32_bf16 v[60:63], v[166:169], v[182:185], v[60:63]
	v_mfma_f32_16x16x32_bf16 v[56:59], v[174:177], v[182:185], v[56:59]
	v_mfma_f32_16x16x32_bf16 v[52:55], v[166:169], v[190:193], v[52:55]
	v_mfma_f32_16x16x32_bf16 v[48:51], v[174:177], v[190:193], v[48:51]
	v_mfma_f32_16x16x32_bf16 v[44:47], v[166:169], v[198:201], v[44:47]
	s_setprio 2
	s_barrier
; #define PG8_STAGE(bufoff, gbase, voff) do { _Pragma("unroll") for (int _i = 0; _i < 2; ++_i) \
;         __builtin_amdgcn_global_load_lds((const unsigned*)((const char*)(gbase) + (voff)[_i]), (PG8_LAS unsigned*)(lds + (bufoff) + ldsw + _i * 8192), 16, 0, 0); } while (0)
; #define PG8_LDA(dst, b, h) do { _Pragma("unroll") for (int m = 0; m < 4; ++m) _Pragma("unroll") for (int k = 0; k < 2; ++k) dst[m][k] = *(const PG8_LAS bf16x8*)(lds + PG8_SA(b, h) + aoff + m * 2048 + k * 1024); } while (0)
; #define PG8_MMA(ai, bj, At, Bt) do { __builtin_amdgcn_s_setprio(1); _Pragma("unroll") for (int m = 0; m < 4; ++m) _Pragma("unroll") for (int n = 0; n < 2; ++n) _Pragma("unroll") for (int k = 0; k < 2; ++k) \
;         acc[ai][bj][m][n] = __builtin_amdgcn_mfma_f32_16x16x32_bf16(Bt[n][k], At[m][k], acc[ai][bj][m][n], 0, 0, 0); __builtin_amdgcn_s_setprio(0); } while (0)
; #define PG8_WAIT_V(n) asm volatile("s_waitcnt vmcnt(" #n ")" ::: "memory")
; #define PG8_WAIT_L(n) asm volatile("s_waitcnt lgkmcnt(" #n ")" ::: "memory")
; #define PG8_BAR __builtin_amdgcn_s_barrier()
; #define PG8_SCHED __builtin_amdgcn_sched_barrier(0)
; template <class Epi, class Sched, bool ALIGN_EPI = false, bool SP2 = false>
; __device__ __forceinline__ void gemm_phase(PG8_LAS unsigned char* lds, const Gemm g, const Sched& S, const Epi& E) {
;     ...
;         for (int t = 0; t < nt; t += 2) {
;             const bool last = (t == nt - 2);
;     ...
;             PG8_WAIT_V(8); PG8_WAIT_L(0); PG8_BAR; PG8_MMA(0, 0, At, B0); PG8_MMA(0, 1, At, B1); PG8_BAR; PG8_SCHED;
;             PG8_LDA(At, 1, 1); PG8_STAGE(PG8_SB(1, 0), b3, voffB); PG8_STAGE(PG8_SB(1, 1), b3 + hstep, voffB); PG8_STAGE(PG8_SA(1, 0), a3, voffA);
;             PG8_WAIT_V(8); PG8_WAIT_L(0); PG8_BAR; PG8_MMA(1, 0, At, B0); PG8_MMA(1, 1, At, B1); PG8_BAR; PG8_SCHED;
	v_mfma_f32_16x16x32_bf16 v[40:43], v[174:177], v[198:201], v[40:43]
	v_mfma_f32_16x16x32_bf16 v[36:39], v[166:169], v[214:217], v[36:39]
	v_mfma_f32_16x16x32_bf16 v[32:35], v[174:177], v[214:217], v[32:35]
	s_setprio 0
	s_add_i32 s56, s78, s60
	v_lshl_add_u64 v[218:219], v[218:219], 0, s[12:13]
	s_mov_b32 m0, s56
	ds_read_b128 v[178:181], v207 offset:49152
	ds_read_b128 v[182:185], v207 offset:50176
	ds_read_b128 v[186:189], v207 offset:51200
	ds_read_b128 v[190:193], v207 offset:52224
	ds_read_b128 v[194:197], v207 offset:53248
	ds_read_b128 v[198:201], v207 offset:54272
	ds_read_b128 v[210:213], v207 offset:55296
	ds_read_b128 v[214:217], v207 offset:56320
	global_load_lds_dwordx4 v[218:219], off
	s_add_i32 m0, s56, 0x2000
	s_add_u32 s54, s54, 0x80080
	v_lshl_add_u64 v[218:219], v[220:221], 0, s[12:13]
	s_addc_u32 s55, s55, 0
	s_add_i32 s56, s79, s60
	global_load_lds_dwordx4 v[218:219], off
	s_mov_b32 m0, s56
	v_lshl_add_u64 v[218:219], s[54:55], 0, v[138:139]
	global_load_lds_dwordx4 v[218:219], off
	s_add_i32 m0, s56, 0x2000
	v_lshl_add_u64 v[218:219], s[54:55], 0, v[142:143]
	global_load_lds_dwordx4 v[218:219], off
	s_mov_b32 m0, s70
	v_lshl_add_u64 v[218:219], v[222:223], 0, s[12:13]
	global_load_lds_dwordx4 v[218:219], off
	s_mov_b32 m0, s71
	v_lshl_add_u64 v[218:219], v[224:225], 0, s[12:13]
	global_load_lds_dwordx4 v[218:219], off
	s_waitcnt vmcnt(8)
	s_waitcnt lgkmcnt(0)
	s_setprio 1
	s_barrier
	v_mfma_f32_16x16x32_bf16 v[92:95], v[128:131], v[178:181], v[92:95]
	v_mfma_f32_16x16x32_bf16 v[88:91], v[154:157], v[178:181], v[88:91]
	v_mfma_f32_16x16x32_bf16 v[84:87], v[128:131], v[186:189], v[84:87]
	v_mfma_f32_16x16x32_bf16 v[80:83], v[154:157], v[186:189], v[80:83]
	v_mfma_f32_16x16x32_bf16 v[76:79], v[128:131], v[194:197], v[76:79]
	v_mfma_f32_16x16x32_bf16 v[72:75], v[154:157], v[194:197], v[72:75]
	v_mfma_f32_16x16x32_bf16 v[68:71], v[128:131], v[210:213], v[68:71]
	v_mfma_f32_16x16x32_bf16 v[64:67], v[154:157], v[210:213], v[64:67]
	v_mfma_f32_16x16x32_bf16 v[92:95], v[132:135], v[182:185], v[92:95]
	v_mfma_f32_16x16x32_bf16 v[88:91], v[158:161], v[182:185], v[88:91]
	v_mfma_f32_16x16x32_bf16 v[84:87], v[132:135], v[190:193], v[84:87]
	v_mfma_f32_16x16x32_bf16 v[80:83], v[158:161], v[190:193], v[80:83]
	v_mfma_f32_16x16x32_bf16 v[76:79], v[132:135], v[198:201], v[76:79]
	v_mfma_f32_16x16x32_bf16 v[72:75], v[158:161], v[198:201], v[72:75]
	v_mfma_f32_16x16x32_bf16 v[68:71], v[132:135], v[214:217], v[68:71]
	v_mfma_f32_16x16x32_bf16 v[64:67], v[158:161], v[214:217], v[64:67]
	s_setprio 0
	s_setprio 1
	v_mfma_f32_16x16x32_bf16 v[28:31], v[162:165], v[178:181], v[28:31]
	v_mfma_f32_16x16x32_bf16 v[24:27], v[170:173], v[178:181], v[24:27]
	v_mfma_f32_16x16x32_bf16 v[20:23], v[162:165], v[186:189], v[20:23]
	v_mfma_f32_16x16x32_bf16 v[16:19], v[170:173], v[186:189], v[16:19]
	v_mfma_f32_16x16x32_bf16 v[12:15], v[162:165], v[194:197], v[12:15]
	v_mfma_f32_16x16x32_bf16 v[8:11], v[170:173], v[194:197], v[8:11]
	v_mfma_f32_16x16x32_bf16 v[4:7], v[162:165], v[210:213], v[4:7]
	v_mfma_f32_16x16x32_bf16 v[0:3], v[170:173], v[210:213], v[0:3]
	v_mfma_f32_16x16x32_bf16 v[28:31], v[166:169], v[182:185], v[28:31]
	v_mfma_f32_16x16x32_bf16 v[24:27], v[174:177], v[182:185], v[24:27]
	v_mfma_f32_16x16x32_bf16 v[20:23], v[166:169], v[190:193], v[20:23]
	v_mfma_f32_16x16x32_bf16 v[16:19], v[174:177], v[190:193], v[16:19]
	v_mfma_f32_16x16x32_bf16 v[12:15], v[166:169], v[198:201], v[12:15]
	s_setprio 2
	s_barrier
	v_mfma_f32_16x16x32_bf16 v[8:11], v[174:177], v[198:201], v[8:11]
	v_mfma_f32_16x16x32_bf16 v[4:7], v[166:169], v[214:217], v[4:7]
	v_mfma_f32_16x16x32_bf16 v[0:3], v[174:177], v[214:217], v[0:3]
	s_setprio 0
	s_add_i32 s77, s77, 2
	s_add_u32 s52, s52, 0x100
	s_addc_u32 s53, s53, 0
	s_add_u32 s75, s75, 0x100
	s_addc_u32 s76, s76, 0
	s_cmp_gt_u32 s77, 29
	s_cbranch_scc0 .LBB0_1051
	s_and_b64 vcc, exec, s[14:15]
	s_cbranch_vccz .LBB0_1054
	s_barrier

; #define PG8_STAGE(bufoff, gbase, voff) do { _Pragma("unroll") for (int _i = 0; _i < 2; ++_i) \
;         __builtin_amdgcn_global_load_lds((const unsigned*)((const char*)(gbase) + (voff)[_i]), (PG8_LAS unsigned*)(lds + (bufoff) + ldsw + _i * 8192), 16, 0, 0); } while (0)
; #define PG8_LDA(dst, b, h) do { _Pragma("unroll") for (int m = 0; m < 4; ++m) _Pragma("unroll") for (int k = 0; k < 2; ++k) dst[m][k] = *(const PG8_LAS bf16x8*)(lds + PG8_SA(b, h) + aoff + m * 2048 + k * 1024); } while (0)
; #define PG8_LDB(dst, b, h) do { _Pragma("unroll") for (int n = 0; n < 2; ++n) _Pragma("unroll") for (int k = 0; k < 2; ++k) dst[n][k] = *(const PG8_LAS bf16x8*)(lds + PG8_SB(b, h) + boff + n * 2048 + k * 1024); } while (0)
; #define PG8_MMA(ai, bj, At, Bt) do { __builtin_amdgcn_s_setprio(1); _Pragma("unroll") for (int m = 0; m < 4; ++m) _Pragma("unroll") for (int n = 0; n < 2; ++n) _Pragma("unroll") for (int k = 0; k < 2; ++k) \
;         acc[ai][bj][m][n] = __builtin_amdgcn_mfma_f32_16x16x32_bf16(Bt[n][k], At[m][k], acc[ai][bj][m][n], 0, 0, 0); __builtin_amdgcn_s_setprio(0); } while (0)
; #define PG8_WAIT_V(n) asm volatile("s_waitcnt vmcnt(" #n ")" ::: "memory")
; #define PG8_WAIT_L(n) asm volatile("s_waitcnt lgkmcnt(" #n ")" ::: "memory")
; #define PG8_BAR __builtin_amdgcn_s_barrier()
; #define PG8_SCHED __builtin_amdgcn_sched_barrier(0)
; template <class Epi, class Sched, bool ALIGN_EPI = false, bool SP2 = false>
; __device__ __forceinline__ void gemm_phase(PG8_LAS unsigned char* lds, const Gemm g, const Sched& S, const Epi& E) {
;     ...
;         for (int t = 0; t < nt; t += 2) {
;             const bool last = (t == nt - 2);
;             const char* a1 = cA + (size_t)(t + 1) * kstep;
;             const char* a2 = last ? nA : cA + (size_t)(t + 2) * kstep; const char* b2 = last ? nB : cB + (size_t)(t + 2) * kstep;
;             const char* a3 = a2 + kstep; const char* b3 = b2 + kstep;
;             if constexpr (SP2) {
;             PG8_LDB(B0, 0, 0); PG8_LDB(B1, 0, 1); PG8_SCHED; PG8_LDA(At, 0, 0); PG8_STAGE(PG8_SA(1, 1), a1 + hstep, voffA);
;             PG8_WAIT_V(8); PG8_WAIT_L(0); PG8_BAR; PG8_MMA(0, 0, At, B0); PG8_MMA(0, 1, At, B1); PG8_BAR; PG8_SCHED;
;             PG8_LDA(At, 0, 1); PG8_STAGE(PG8_SB(0, 0), b2, voffB); PG8_STAGE(PG8_SB(0, 1), b2 + hstep, voffB); PG8_STAGE(PG8_SA(0, 0), a2, voffA);
.LBB0_1142:
	ds_read_b128 v[80:83], v171
	ds_read_b128 v[84:87], v171 offset:1024
	ds_read_b128 v[88:91], v171 offset:2048
	ds_read_b128 v[92:95], v171 offset:3072
	ds_read_b128 v[164:167], v172
	ds_read_b128 v[176:179], v172 offset:1024
	ds_read_b128 v[180:183], v172 offset:2048
	ds_read_b128 v[184:187], v172 offset:3072
	s_add_u32 s44, s42, 0xfff80080
	s_addc_u32 s45, s43, -1
	s_cmp_eq_u32 s64, 28
	s_cselect_b32 s47, s15, s45
	s_cselect_b32 s46, s60, s44
	s_cselect_b32 s45, s13, s63
	s_cselect_b32 s44, s61, s62
	v_lshl_add_u64 v[220:221], s[42:43], 0, v[156:157]
	s_add_i32 m0, s41, 0xc000
	ds_read_b128 v[188:191], v173
	ds_read_b128 v[192:195], v173 offset:1024
	ds_read_b128 v[196:199], v173 offset:2048
	ds_read_b128 v[200:203], v173 offset:3072
	ds_read_b128 v[204:207], v173 offset:4096
	ds_read_b128 v[208:211], v173 offset:5120
	ds_read_b128 v[212:215], v173 offset:6144
	ds_read_b128 v[216:219], v173 offset:7168
	global_load_lds_dwordx4 v[220:221], off
	s_add_i32 m0, s41, 0xe000
	v_lshl_add_u64 v[220:221], s[42:43], 0, v[158:159]
	global_load_lds_dwordx4 v[220:221], off
	s_waitcnt vmcnt(8)
	s_waitcnt lgkmcnt(0)
	s_setprio 1
	s_barrier
	v_mfma_f32_16x16x32_bf16 v[140:143], v[80:83], v[188:191], v[140:143]
	v_mfma_f32_16x16x32_bf16 v[136:139], v[88:91], v[188:191], v[136:139]
	v_mfma_f32_16x16x32_bf16 v[124:127], v[80:83], v[196:199], v[124:127]
	v_mfma_f32_16x16x32_bf16 v[120:123], v[88:91], v[196:199], v[120:123]
	v_mfma_f32_16x16x32_bf16 v[108:111], v[80:83], v[204:207], v[108:111]
	v_mfma_f32_16x16x32_bf16 v[104:107], v[88:91], v[204:207], v[104:107]
	v_mfma_f32_16x16x32_bf16 v[76:79], v[80:83], v[212:215], v[76:79]
	v_mfma_f32_16x16x32_bf16 v[72:75], v[88:91], v[212:215], v[72:75]
	v_mfma_f32_16x16x32_bf16 v[140:143], v[84:87], v[192:195], v[140:143]
	v_mfma_f32_16x16x32_bf16 v[136:139], v[92:95], v[192:195], v[136:139]
	v_mfma_f32_16x16x32_bf16 v[124:127], v[84:87], v[200:203], v[124:127]
	v_mfma_f32_16x16x32_bf16 v[120:123], v[92:95], v[200:203], v[120:123]
	v_mfma_f32_16x16x32_bf16 v[108:111], v[84:87], v[208:211], v[108:111]
	v_mfma_f32_16x16x32_bf16 v[104:107], v[92:95], v[208:211], v[104:107]
	v_mfma_f32_16x16x32_bf16 v[76:79], v[84:87], v[216:219], v[76:79]
	v_mfma_f32_16x16x32_bf16 v[72:75], v[92:95], v[216:219], v[72:75]
	s_setprio 0
	s_setprio 1
	v_mfma_f32_16x16x32_bf16 v[132:135], v[164:167], v[188:191], v[132:135]
	v_mfma_f32_16x16x32_bf16 v[128:131], v[180:183], v[188:191], v[128:131]
	v_mfma_f32_16x16x32_bf16 v[116:119], v[164:167], v[196:199], v[116:119]
	v_mfma_f32_16x16x32_bf16 v[112:115], v[180:183], v[196:199], v[112:115]
	v_mfma_f32_16x16x32_bf16 v[100:103], v[164:167], v[204:207], v[100:103]
	v_mfma_f32_16x16x32_bf16 v[96:99], v[180:183], v[204:207], v[96:99]
	v_mfma_f32_16x16x32_bf16 v[68:71], v[164:167], v[212:215], v[68:71]
	v_mfma_f32_16x16x32_bf16 v[64:67], v[180:183], v[212:215], v[64:67]
	v_mfma_f32_16x16x32_bf16 v[132:135], v[176:179], v[192:195], v[132:135]
	v_mfma_f32_16x16x32_bf16 v[128:131], v[184:187], v[192:195], v[128:131]
	v_mfma_f32_16x16x32_bf16 v[116:119], v[176:179], v[200:203], v[116:119]
	v_mfma_f32_16x16x32_bf16 v[112:115], v[184:187], v[200:203], v[112:115]
	v_mfma_f32_16x16x32_bf16 v[100:103], v[176:179], v[208:211], v[100:103]
	s_setprio 2
	s_barrier
	v_mfma_f32_16x16x32_bf16 v[96:99], v[184:187], v[208:211], v[96:99]
	v_mfma_f32_16x16x32_bf16 v[68:71], v[176:179], v[216:219], v[68:71]
	v_mfma_f32_16x16x32_bf16 v[64:67], v[184:187], v[216:219], v[64:67]
	s_setprio 0
	s_add_i32 s65, s56, s33
	v_lshl_add_u64 v[220:221], s[44:45], 0, v[148:149]
	s_mov_b32 m0, s65
	ds_read_b128 v[188:191], v173 offset:16384
	ds_read_b128 v[192:195], v173 offset:17408
	ds_read_b128 v[196:199], v173 offset:18432
	ds_read_b128 v[200:203], v173 offset:19456
	ds_read_b128 v[204:207], v173 offset:20480
	ds_read_b128 v[208:211], v173 offset:21504
	ds_read_b128 v[212:215], v173 offset:22528
	ds_read_b128 v[216:219], v173 offset:23552
	global_load_lds_dwordx4 v[220:221], off
	s_add_i32 m0, s65, 0x2000
	s_add_u32 s66, s44, 0x80000
	v_lshl_add_u64 v[222:223], s[44:45], 0, v[152:153]
	s_addc_u32 s67, s45, 0
	s_add_i32 s65, s57, s33
	global_load_lds_dwordx4 v[222:223], off
	v_lshl_add_u64 v[224:225], s[66:67], 0, v[148:149]
	s_mov_b32 m0, s65
	v_lshl_add_u64 v[226:227], s[46:47], 0, v[150:151]
	global_load_lds_dwordx4 v[224:225], off
	s_add_i32 m0, s65, 0x2000
	v_lshl_add_u64 v[224:225], s[66:67], 0, v[152:153]
	global_load_lds_dwordx4 v[224:225], off
	s_mov_b32 m0, s41
	v_lshl_add_u64 v[224:225], s[46:47], 0, v[144:145]
	global_load_lds_dwordx4 v[224:225], off
	s_mov_b32 m0, s48
	s_nop 0
	global_load_lds_dwordx4 v[226:227], off
	s_waitcnt vmcnt(8)
	s_waitcnt lgkmcnt(0)
	s_setprio 1
	s_barrier
; #define PG8_STAGE(bufoff, gbase, voff) do { _Pragma("unroll") for (int _i = 0; _i < 2; ++_i) \
;         __builtin_amdgcn_global_load_lds((const unsigned*)((const char*)(gbase) + (voff)[_i]), (PG8_LAS unsigned*)(lds + (bufoff) + ldsw + _i * 8192), 16, 0, 0); } while (0)
; #define PG8_LDA(dst, b, h) do { _Pragma("unroll") for (int m = 0; m < 4; ++m) _Pragma("unroll") for (int k = 0; k < 2; ++k) dst[m][k] = *(const PG8_LAS bf16x8*)(lds + PG8_SA(b, h) + aoff + m * 2048 + k * 1024); } while (0)
; #define PG8_LDB(dst, b, h) do { _Pragma("unroll") for (int n = 0; n < 2; ++n) _Pragma("unroll") for (int k = 0; k < 2; ++k) dst[n][k] = *(const PG8_LAS bf16x8*)(lds + PG8_SB(b, h) + boff + n * 2048 + k * 1024); } while (0)
; #define PG8_MMA(ai, bj, At, Bt) do { __builtin_amdgcn_s_setprio(1); _Pragma("unroll") for (int m = 0; m < 4; ++m) _Pragma("unroll") for (int n = 0; n < 2; ++n) _Pragma("unroll") for (int k = 0; k < 2; ++k) \
;         acc[ai][bj][m][n] = __builtin_amdgcn_mfma_f32_16x16x32_bf16(Bt[n][k], At[m][k], acc[ai][bj][m][n], 0, 0, 0); __builtin_amdgcn_s_setprio(0); } while (0)
; #define PG8_WAIT_V(n) asm volatile("s_waitcnt vmcnt(" #n ")" ::: "memory")
; #define PG8_WAIT_L(n) asm volatile("s_waitcnt lgkmcnt(" #n ")" ::: "memory")
; #define PG8_BAR __builtin_amdgcn_s_barrier()
; #define PG8_SCHED __builtin_amdgcn_sched_barrier(0)
; template <class Epi, class Sched, bool ALIGN_EPI = false, bool SP2 = false>
; __device__ __forceinline__ void gemm_phase(PG8_LAS unsigned char* lds, const Gemm g, const Sched& S, const Epi& E) {
;     ...
;             PG8_WAIT_V(8); PG8_WAIT_L(0); PG8_BAR; PG8_MMA(1, 0, At, B0); PG8_MMA(1, 1, At, B1); PG8_BAR; PG8_SCHED;
;             PG8_LDB(B0, 1, 0); PG8_LDB(B1, 1, 1); PG8_SCHED; PG8_LDA(At, 1, 0); PG8_STAGE(PG8_SA(0, 1), a2 + hstep, voffA);
;             PG8_WAIT_V(8); PG8_WAIT_L(0); PG8_BAR; PG8_MMA(0, 0, At, B0); PG8_MMA(0, 1, At, B1); PG8_BAR; PG8_SCHED;
	v_mfma_f32_16x16x32_bf16 v[60:63], v[80:83], v[188:191], v[60:63]
	v_mfma_f32_16x16x32_bf16 v[56:59], v[88:91], v[188:191], v[56:59]
	v_mfma_f32_16x16x32_bf16 v[44:47], v[80:83], v[196:199], v[44:47]
	v_mfma_f32_16x16x32_bf16 v[40:43], v[88:91], v[196:199], v[40:43]
	v_mfma_f32_16x16x32_bf16 v[28:31], v[80:83], v[204:207], v[28:31]
	v_mfma_f32_16x16x32_bf16 v[24:27], v[88:91], v[204:207], v[24:27]
	v_mfma_f32_16x16x32_bf16 v[12:15], v[80:83], v[212:215], v[12:15]
	v_mfma_f32_16x16x32_bf16 v[8:11], v[88:91], v[212:215], v[8:11]
	v_mfma_f32_16x16x32_bf16 v[60:63], v[84:87], v[192:195], v[60:63]
	v_mfma_f32_16x16x32_bf16 v[56:59], v[92:95], v[192:195], v[56:59]
	v_mfma_f32_16x16x32_bf16 v[44:47], v[84:87], v[200:203], v[44:47]
	v_mfma_f32_16x16x32_bf16 v[40:43], v[92:95], v[200:203], v[40:43]
	v_mfma_f32_16x16x32_bf16 v[28:31], v[84:87], v[208:211], v[28:31]
	v_mfma_f32_16x16x32_bf16 v[24:27], v[92:95], v[208:211], v[24:27]
	v_mfma_f32_16x16x32_bf16 v[12:15], v[84:87], v[216:219], v[12:15]
	v_mfma_f32_16x16x32_bf16 v[8:11], v[92:95], v[216:219], v[8:11]
	s_setprio 0
	s_setprio 1
	v_mfma_f32_16x16x32_bf16 v[52:55], v[164:167], v[188:191], v[52:55]
	v_mfma_f32_16x16x32_bf16 v[48:51], v[180:183], v[188:191], v[48:51]
	v_mfma_f32_16x16x32_bf16 v[36:39], v[164:167], v[196:199], v[36:39]
	v_mfma_f32_16x16x32_bf16 v[32:35], v[180:183], v[196:199], v[32:35]
	v_mfma_f32_16x16x32_bf16 v[20:23], v[164:167], v[204:207], v[20:23]
	v_mfma_f32_16x16x32_bf16 v[16:19], v[180:183], v[204:207], v[16:19]
	v_mfma_f32_16x16x32_bf16 v[4:7], v[164:167], v[212:215], v[4:7]
	v_mfma_f32_16x16x32_bf16 v[0:3], v[180:183], v[212:215], v[0:3]
	v_mfma_f32_16x16x32_bf16 v[52:55], v[176:179], v[192:195], v[52:55]
	v_mfma_f32_16x16x32_bf16 v[48:51], v[184:187], v[192:195], v[48:51]
	v_mfma_f32_16x16x32_bf16 v[36:39], v[176:179], v[200:203], v[36:39]
	v_mfma_f32_16x16x32_bf16 v[32:35], v[184:187], v[200:203], v[32:35]
	v_mfma_f32_16x16x32_bf16 v[20:23], v[176:179], v[208:211], v[20:23]
	s_setprio 2
	s_barrier
	v_mfma_f32_16x16x32_bf16 v[16:19], v[184:187], v[208:211], v[16:19]
	v_mfma_f32_16x16x32_bf16 v[4:7], v[176:179], v[216:219], v[4:7]
	v_mfma_f32_16x16x32_bf16 v[0:3], v[184:187], v[216:219], v[0:3]
	s_setprio 0
	s_add_i32 s65, 0, 0x18000
	s_add_i32 s66, 0, 0x1c000
	v_add_u32_e32 v92, s65, v169
	v_add_u32_e32 v184, s66, v169
	ds_read_b128 v[80:83], v92
	ds_read_b128 v[84:87], v92 offset:1024
	ds_read_b128 v[88:91], v92 offset:2048
	ds_read_b128 v[92:95], v92 offset:3072
	ds_read_b128 v[164:167], v184
	ds_read_b128 v[176:179], v184 offset:1024
	ds_read_b128 v[180:183], v184 offset:2048
	ds_read_b128 v[184:187], v184 offset:3072
	s_add_u32 s46, s46, 0x80000
	s_addc_u32 s47, s47, 0
	s_mov_b32 m0, s49
	v_lshl_add_u64 v[228:229], s[46:47], 0, v[144:145]
	ds_read_b128 v[188:191], v173 offset:32768
	ds_read_b128 v[192:195], v173 offset:33792
	ds_read_b128 v[196:199], v173 offset:34816
	ds_read_b128 v[200:203], v173 offset:35840
	ds_read_b128 v[204:207], v173 offset:36864
	ds_read_b128 v[208:211], v173 offset:37888
	ds_read_b128 v[212:215], v173 offset:38912
	ds_read_b128 v[216:219], v173 offset:39936
	global_load_lds_dwordx4 v[228:229], off
	s_mov_b32 m0, s50
	v_lshl_add_u64 v[228:229], s[46:47], 0, v[150:151]
	global_load_lds_dwordx4 v[228:229], off
	s_waitcnt vmcnt(8)
	s_waitcnt lgkmcnt(0)
	s_setprio 1
	s_barrier
	v_mfma_f32_16x16x32_bf16 v[140:143], v[80:83], v[188:191], v[140:143]
	v_mfma_f32_16x16x32_bf16 v[136:139], v[88:91], v[188:191], v[136:139]
	v_mfma_f32_16x16x32_bf16 v[124:127], v[80:83], v[196:199], v[124:127]
	v_mfma_f32_16x16x32_bf16 v[120:123], v[88:91], v[196:199], v[120:123]
	v_mfma_f32_16x16x32_bf16 v[108:111], v[80:83], v[204:207], v[108:111]
	v_mfma_f32_16x16x32_bf16 v[104:107], v[88:91], v[204:207], v[104:107]
	v_mfma_f32_16x16x32_bf16 v[76:79], v[80:83], v[212:215], v[76:79]
	v_mfma_f32_16x16x32_bf16 v[72:75], v[88:91], v[212:215], v[72:75]
	v_mfma_f32_16x16x32_bf16 v[140:143], v[84:87], v[192:195], v[140:143]
	v_mfma_f32_16x16x32_bf16 v[136:139], v[92:95], v[192:195], v[136:139]
	v_mfma_f32_16x16x32_bf16 v[124:127], v[84:87], v[200:203], v[124:127]
	v_mfma_f32_16x16x32_bf16 v[120:123], v[92:95], v[200:203], v[120:123]
	v_mfma_f32_16x16x32_bf16 v[108:111], v[84:87], v[208:211], v[108:111]
	v_mfma_f32_16x16x32_bf16 v[104:107], v[92:95], v[208:211], v[104:107]
	v_mfma_f32_16x16x32_bf16 v[76:79], v[84:87], v[216:219], v[76:79]
	v_mfma_f32_16x16x32_bf16 v[72:75], v[92:95], v[216:219], v[72:75]
	s_setprio 0
	s_setprio 1
	v_mfma_f32_16x16x32_bf16 v[132:135], v[164:167], v[188:191], v[132:135]
	v_mfma_f32_16x16x32_bf16 v[128:131], v[180:183], v[188:191], v[128:131]
	v_mfma_f32_16x16x32_bf16 v[116:119], v[164:167], v[196:199], v[116:119]
	v_mfma_f32_16x16x32_bf16 v[112:115], v[180:183], v[196:199], v[112:115]
	v_mfma_f32_16x16x32_bf16 v[100:103], v[164:167], v[204:207], v[100:103]
	v_mfma_f32_16x16x32_bf16 v[96:99], v[180:183], v[204:207], v[96:99]
	v_mfma_f32_16x16x32_bf16 v[68:71], v[164:167], v[212:215], v[68:71]
	v_mfma_f32_16x16x32_bf16 v[64:67], v[180:183], v[212:215], v[64:67]
	v_mfma_f32_16x16x32_bf16 v[132:135], v[176:179], v[192:195], v[132:135]
	v_mfma_f32_16x16x32_bf16 v[128:131], v[184:187], v[192:195], v[128:131]
	v_mfma_f32_16x16x32_bf16 v[116:119], v[176:179], v[200:203], v[116:119]
	v_mfma_f32_16x16x32_bf16 v[112:115], v[184:187], v[200:203], v[112:115]
	v_mfma_f32_16x16x32_bf16 v[100:103], v[176:179], v[208:211], v[100:103]
	s_setprio 2
	s_barrier
; #define PG8_STAGE(bufoff, gbase, voff) do { _Pragma("unroll") for (int _i = 0; _i < 2; ++_i) \
;         __builtin_amdgcn_global_load_lds((const unsigned*)((const char*)(gbase) + (voff)[_i]), (PG8_LAS unsigned*)(lds + (bufoff) + ldsw + _i * 8192), 16, 0, 0); } while (0)
; #define PG8_LDA(dst, b, h) do { _Pragma("unroll") for (int m = 0; m < 4; ++m) _Pragma("unroll") for (int k = 0; k < 2; ++k) dst[m][k] = *(const PG8_LAS bf16x8*)(lds + PG8_SA(b, h) + aoff + m * 2048 + k * 1024); } while (0)
; #define PG8_MMA(ai, bj, At, Bt) do { __builtin_amdgcn_s_setprio(1); _Pragma("unroll") for (int m = 0; m < 4; ++m) _Pragma("unroll") for (int n = 0; n < 2; ++n) _Pragma("unroll") for (int k = 0; k < 2; ++k) \
;         acc[ai][bj][m][n] = __builtin_amdgcn_mfma_f32_16x16x32_bf16(Bt[n][k], At[m][k], acc[ai][bj][m][n], 0, 0, 0); __builtin_amdgcn_s_setprio(0); } while (0)
; #define PG8_WAIT_V(n) asm volatile("s_waitcnt vmcnt(" #n ")" ::: "memory")
; #define PG8_WAIT_L(n) asm volatile("s_waitcnt lgkmcnt(" #n ")" ::: "memory")
; #define PG8_BAR __builtin_amdgcn_s_barrier()
; #define PG8_SCHED __builtin_amdgcn_sched_barrier(0)
; template <class Epi, class Sched, bool ALIGN_EPI = false, bool SP2 = false>
; __device__ __forceinline__ void gemm_phase(PG8_LAS unsigned char* lds, const Gemm g, const Sched& S, const Epi& E) {
;     ...
;         for (int t = 0; t < nt; t += 2) {
;             const bool last = (t == nt - 2);
;     ...
;             PG8_WAIT_V(8); PG8_WAIT_L(0); PG8_BAR; PG8_MMA(0, 0, At, B0); PG8_MMA(0, 1, At, B1); PG8_BAR; PG8_SCHED;
;             PG8_LDA(At, 1, 1); PG8_STAGE(PG8_SB(1, 0), b3, voffB); PG8_STAGE(PG8_SB(1, 1), b3 + hstep, voffB); PG8_STAGE(PG8_SA(1, 0), a3, voffA);
;             PG8_WAIT_V(8); PG8_WAIT_L(0); PG8_BAR; PG8_MMA(1, 0, At, B0); PG8_MMA(1, 1, At, B1); PG8_BAR; PG8_SCHED;
	v_mfma_f32_16x16x32_bf16 v[96:99], v[184:187], v[208:211], v[96:99]
	v_mfma_f32_16x16x32_bf16 v[68:71], v[176:179], v[216:219], v[68:71]
	v_mfma_f32_16x16x32_bf16 v[64:67], v[184:187], v[216:219], v[64:67]
	s_setprio 0
	s_add_i32 s46, s65, s33
	v_lshl_add_u64 v[220:221], v[220:221], 0, s[8:9]
	s_mov_b32 m0, s46
	ds_read_b128 v[188:191], v173 offset:49152
	ds_read_b128 v[192:195], v173 offset:50176
	ds_read_b128 v[196:199], v173 offset:51200
	ds_read_b128 v[200:203], v173 offset:52224
	ds_read_b128 v[204:207], v173 offset:53248
	ds_read_b128 v[208:211], v173 offset:54272
	ds_read_b128 v[212:215], v173 offset:55296
	ds_read_b128 v[216:219], v173 offset:56320
	global_load_lds_dwordx4 v[220:221], off
	s_add_i32 m0, s46, 0x2000
	s_add_u32 s44, s44, 0x80080
	v_lshl_add_u64 v[220:221], v[222:223], 0, s[8:9]
	s_addc_u32 s45, s45, 0
	s_add_i32 s46, s66, s33
	global_load_lds_dwordx4 v[220:221], off
	s_mov_b32 m0, s46
	v_lshl_add_u64 v[220:221], s[44:45], 0, v[148:149]
	global_load_lds_dwordx4 v[220:221], off
	s_add_i32 m0, s46, 0x2000
	v_lshl_add_u64 v[220:221], s[44:45], 0, v[152:153]
	global_load_lds_dwordx4 v[220:221], off
	s_mov_b32 m0, s52
	v_lshl_add_u64 v[220:221], v[224:225], 0, s[8:9]
	global_load_lds_dwordx4 v[220:221], off
	s_mov_b32 m0, s53
	v_lshl_add_u64 v[220:221], v[226:227], 0, s[8:9]
	global_load_lds_dwordx4 v[220:221], off
	s_waitcnt vmcnt(8)
	s_waitcnt lgkmcnt(0)
	s_setprio 1
	s_barrier
	v_mfma_f32_16x16x32_bf16 v[60:63], v[80:83], v[188:191], v[60:63]
	v_mfma_f32_16x16x32_bf16 v[56:59], v[88:91], v[188:191], v[56:59]
	v_mfma_f32_16x16x32_bf16 v[44:47], v[80:83], v[196:199], v[44:47]
	v_mfma_f32_16x16x32_bf16 v[40:43], v[88:91], v[196:199], v[40:43]
	v_mfma_f32_16x16x32_bf16 v[28:31], v[80:83], v[204:207], v[28:31]
	v_mfma_f32_16x16x32_bf16 v[24:27], v[88:91], v[204:207], v[24:27]
	v_mfma_f32_16x16x32_bf16 v[12:15], v[80:83], v[212:215], v[12:15]
	v_mfma_f32_16x16x32_bf16 v[8:11], v[88:91], v[212:215], v[8:11]
	v_mfma_f32_16x16x32_bf16 v[60:63], v[84:87], v[192:195], v[60:63]
	v_mfma_f32_16x16x32_bf16 v[56:59], v[92:95], v[192:195], v[56:59]
	v_mfma_f32_16x16x32_bf16 v[44:47], v[84:87], v[200:203], v[44:47]
	v_mfma_f32_16x16x32_bf16 v[40:43], v[92:95], v[200:203], v[40:43]
	v_mfma_f32_16x16x32_bf16 v[28:31], v[84:87], v[208:211], v[28:31]
	v_mfma_f32_16x16x32_bf16 v[24:27], v[92:95], v[208:211], v[24:27]
	v_mfma_f32_16x16x32_bf16 v[12:15], v[84:87], v[216:219], v[12:15]
	v_mfma_f32_16x16x32_bf16 v[8:11], v[92:95], v[216:219], v[8:11]
	s_setprio 0
	s_setprio 1
	v_mfma_f32_16x16x32_bf16 v[52:55], v[164:167], v[188:191], v[52:55]
	v_mfma_f32_16x16x32_bf16 v[48:51], v[180:183], v[188:191], v[48:51]
	v_mfma_f32_16x16x32_bf16 v[36:39], v[164:167], v[196:199], v[36:39]
	v_mfma_f32_16x16x32_bf16 v[32:35], v[180:183], v[196:199], v[32:35]
	v_mfma_f32_16x16x32_bf16 v[20:23], v[164:167], v[204:207], v[20:23]
	v_mfma_f32_16x16x32_bf16 v[16:19], v[180:183], v[204:207], v[16:19]
	v_mfma_f32_16x16x32_bf16 v[4:7], v[164:167], v[212:215], v[4:7]
	v_mfma_f32_16x16x32_bf16 v[0:3], v[180:183], v[212:215], v[0:3]
	v_mfma_f32_16x16x32_bf16 v[52:55], v[176:179], v[192:195], v[52:55]
	v_mfma_f32_16x16x32_bf16 v[48:51], v[184:187], v[192:195], v[48:51]
	v_mfma_f32_16x16x32_bf16 v[36:39], v[176:179], v[200:203], v[36:39]
	v_mfma_f32_16x16x32_bf16 v[32:35], v[184:187], v[200:203], v[32:35]
	v_mfma_f32_16x16x32_bf16 v[20:23], v[176:179], v[208:211], v[20:23]
	s_setprio 2
	s_barrier
	v_mfma_f32_16x16x32_bf16 v[16:19], v[184:187], v[208:211], v[16:19]
	v_mfma_f32_16x16x32_bf16 v[4:7], v[176:179], v[216:219], v[4:7]
	v_mfma_f32_16x16x32_bf16 v[0:3], v[184:187], v[216:219], v[0:3]
	s_setprio 0
	s_add_i32 s64, s64, 2
	s_add_u32 s42, s42, 0x100
	s_addc_u32 s43, s43, 0
	s_add_u32 s62, s62, 0x100
	s_addc_u32 s63, s63, 0
	s_cmp_gt_u32 s64, 29
	s_cbranch_scc0 .LBB0_1142
	s_and_b64 vcc, exec, s[10:11]
	s_cbranch_vccz .LBB0_1145
	s_barrier

; #define PG8_STAGE(bufoff, gbase, voff) do { _Pragma("unroll") for (int _i = 0; _i < 2; ++_i) \
;         __builtin_amdgcn_global_load_lds((const unsigned*)((const char*)(gbase) + (voff)[_i]), (PG8_LAS unsigned*)(lds + (bufoff) + ldsw + _i * 8192), 16, 0, 0); } while (0)
; #define PG8_LDA(dst, b, h) do { _Pragma("unroll") for (int m = 0; m < 4; ++m) _Pragma("unroll") for (int k = 0; k < 2; ++k) dst[m][k] = *(const PG8_LAS bf16x8*)(lds + PG8_SA(b, h) + aoff + m * 2048 + k * 1024); } while (0)
; #define PG8_LDB(dst, b, h) do { _Pragma("unroll") for (int n = 0; n < 2; ++n) _Pragma("unroll") for (int k = 0; k < 2; ++k) dst[n][k] = *(const PG8_LAS bf16x8*)(lds + PG8_SB(b, h) + boff + n * 2048 + k * 1024); } while (0)
; #define PG8_MMA(ai, bj, At, Bt) do { __builtin_amdgcn_s_setprio(1); _Pragma("unroll") for (int m = 0; m < 4; ++m) _Pragma("unroll") for (int n = 0; n < 2; ++n) _Pragma("unroll") for (int k = 0; k < 2; ++k) \
;         acc[ai][bj][m][n] = __builtin_amdgcn_mfma_f32_16x16x32_bf16(Bt[n][k], At[m][k], acc[ai][bj][m][n], 0, 0, 0); __builtin_amdgcn_s_setprio(0); } while (0)
; #define PG8_WAIT_V(n) asm volatile("s_waitcnt vmcnt(" #n ")" ::: "memory")
; #define PG8_WAIT_L(n) asm volatile("s_waitcnt lgkmcnt(" #n ")" ::: "memory")
; #define PG8_BAR __builtin_amdgcn_s_barrier()
; #define PG8_SCHED __builtin_amdgcn_sched_barrier(0)
; template <class Epi, class Sched, bool ALIGN_EPI = false, bool SP2 = false>
; __device__ __forceinline__ void gemm_phase(PG8_LAS unsigned char* lds, const Gemm g, const Sched& S, const Epi& E) {
;     ...
;         for (int t = 0; t < nt; t += 2) {
;             const bool last = (t == nt - 2);
;             const char* a1 = cA + (size_t)(t + 1) * kstep;
;             const char* a2 = last ? nA : cA + (size_t)(t + 2) * kstep; const char* b2 = last ? nB : cB + (size_t)(t + 2) * kstep;
;             const char* a3 = a2 + kstep; const char* b3 = b2 + kstep;
;             if constexpr (SP2) {
;             PG8_LDB(B0, 0, 0); PG8_LDB(B1, 0, 1); PG8_SCHED; PG8_LDA(At, 0, 0); PG8_STAGE(PG8_SA(1, 1), a1 + hstep, voffA);
;             PG8_WAIT_V(8); PG8_WAIT_L(0); PG8_BAR; PG8_MMA(0, 0, At, B0); PG8_MMA(0, 1, At, B1); PG8_BAR; PG8_SCHED;
;             PG8_LDA(At, 0, 1); PG8_STAGE(PG8_SB(0, 0), b2, voffB); PG8_STAGE(PG8_SB(0, 1), b2 + hstep, voffB); PG8_STAGE(PG8_SA(0, 0), a2, voffA);
.LBB0_1219:
	ds_read_b128 v[128:131], v167
	ds_read_b128 v[132:135], v167 offset:1024
	ds_read_b128 v[154:157], v167 offset:2048
	ds_read_b128 v[158:161], v167 offset:3072
	ds_read_b128 v[170:173], v168
	ds_read_b128 v[174:177], v168 offset:1024
	ds_read_b128 v[178:181], v168 offset:2048
	ds_read_b128 v[182:185], v168 offset:3072
	s_add_u32 s42, s40, 0xffe00080
	s_addc_u32 s43, s41, -1
	s_cmpk_eq_i32 s63, 0x7c
	s_cselect_b32 s45, s15, s43
	s_cselect_b32 s44, s59, s42
	s_cselect_b32 s43, s13, s62
	s_cselect_b32 s42, s60, s61
	v_lshl_add_u64 v[162:163], s[40:41], 0, v[144:145]
	s_add_i32 m0, s39, 0xc000
	ds_read_b128 v[186:189], v169
	ds_read_b128 v[190:193], v169 offset:1024
	ds_read_b128 v[194:197], v169 offset:2048
	ds_read_b128 v[198:201], v169 offset:3072
	ds_read_b128 v[202:205], v169 offset:4096
	ds_read_b128 v[206:209], v169 offset:5120
	ds_read_b128 v[210:213], v169 offset:6144
	ds_read_b128 v[214:217], v169 offset:7168
	global_load_lds_dwordx4 v[162:163], off
	s_add_i32 m0, s39, 0xe000
	v_lshl_add_u64 v[162:163], s[40:41], 0, v[148:149]
	global_load_lds_dwordx4 v[162:163], off
	s_waitcnt vmcnt(8)
	s_waitcnt lgkmcnt(0)
	s_setprio 1
	s_barrier
	v_mfma_f32_16x16x32_bf16 v[124:127], v[128:131], v[186:189], v[124:127]
	v_mfma_f32_16x16x32_bf16 v[120:123], v[154:157], v[186:189], v[120:123]
	v_mfma_f32_16x16x32_bf16 v[116:119], v[128:131], v[194:197], v[116:119]
	v_mfma_f32_16x16x32_bf16 v[112:115], v[154:157], v[194:197], v[112:115]
	v_mfma_f32_16x16x32_bf16 v[108:111], v[128:131], v[202:205], v[108:111]
	v_mfma_f32_16x16x32_bf16 v[104:107], v[154:157], v[202:205], v[104:107]
	v_mfma_f32_16x16x32_bf16 v[100:103], v[128:131], v[210:213], v[100:103]
	v_mfma_f32_16x16x32_bf16 v[96:99], v[154:157], v[210:213], v[96:99]
	v_mfma_f32_16x16x32_bf16 v[124:127], v[132:135], v[190:193], v[124:127]
	v_mfma_f32_16x16x32_bf16 v[120:123], v[158:161], v[190:193], v[120:123]
	v_mfma_f32_16x16x32_bf16 v[116:119], v[132:135], v[198:201], v[116:119]
	v_mfma_f32_16x16x32_bf16 v[112:115], v[158:161], v[198:201], v[112:115]
	v_mfma_f32_16x16x32_bf16 v[108:111], v[132:135], v[206:209], v[108:111]
	v_mfma_f32_16x16x32_bf16 v[104:107], v[158:161], v[206:209], v[104:107]
	v_mfma_f32_16x16x32_bf16 v[100:103], v[132:135], v[214:217], v[100:103]
	v_mfma_f32_16x16x32_bf16 v[96:99], v[158:161], v[214:217], v[96:99]
	s_setprio 0
	s_setprio 1
	v_mfma_f32_16x16x32_bf16 v[68:71], v[170:173], v[186:189], v[68:71]
	v_mfma_f32_16x16x32_bf16 v[60:63], v[178:181], v[186:189], v[60:63]
	v_mfma_f32_16x16x32_bf16 v[52:55], v[170:173], v[194:197], v[52:55]
	v_mfma_f32_16x16x32_bf16 v[48:51], v[178:181], v[194:197], v[48:51]
	v_mfma_f32_16x16x32_bf16 v[44:47], v[170:173], v[202:205], v[44:47]
	v_mfma_f32_16x16x32_bf16 v[40:43], v[178:181], v[202:205], v[40:43]
	v_mfma_f32_16x16x32_bf16 v[36:39], v[170:173], v[210:213], v[36:39]
	v_mfma_f32_16x16x32_bf16 v[32:35], v[178:181], v[210:213], v[32:35]
	v_mfma_f32_16x16x32_bf16 v[68:71], v[174:177], v[190:193], v[68:71]
	v_mfma_f32_16x16x32_bf16 v[60:63], v[182:185], v[190:193], v[60:63]
	v_mfma_f32_16x16x32_bf16 v[52:55], v[174:177], v[198:201], v[52:55]
	v_mfma_f32_16x16x32_bf16 v[48:51], v[182:185], v[198:201], v[48:51]
	v_mfma_f32_16x16x32_bf16 v[44:47], v[174:177], v[206:209], v[44:47]
	s_setprio 2
	s_barrier
	v_mfma_f32_16x16x32_bf16 v[40:43], v[182:185], v[206:209], v[40:43]
	v_mfma_f32_16x16x32_bf16 v[36:39], v[174:177], v[214:217], v[36:39]
	v_mfma_f32_16x16x32_bf16 v[32:35], v[182:185], v[214:217], v[32:35]
	s_setprio 0
	s_add_i32 s64, s56, s33
	v_lshl_add_u64 v[162:163], s[42:43], 0, v[138:139]
	s_mov_b32 m0, s64
	ds_read_b128 v[186:189], v169 offset:16384
	ds_read_b128 v[190:193], v169 offset:17408
	ds_read_b128 v[194:197], v169 offset:18432
	ds_read_b128 v[198:201], v169 offset:19456
	ds_read_b128 v[202:205], v169 offset:20480
	ds_read_b128 v[206:209], v169 offset:21504
	ds_read_b128 v[210:213], v169 offset:22528
	ds_read_b128 v[214:217], v169 offset:23552
	global_load_lds_dwordx4 v[162:163], off
	s_add_i32 m0, s64, 0x2000
	s_add_u32 s64, s42, 0x200000
	v_lshl_add_u64 v[218:219], s[42:43], 0, v[142:143]
	s_addc_u32 s65, s43, 0
	s_add_i32 s66, s57, s33
	global_load_lds_dwordx4 v[218:219], off
	v_lshl_add_u64 v[220:221], s[64:65], 0, v[138:139]
	s_mov_b32 m0, s66
	v_lshl_add_u64 v[222:223], s[44:45], 0, v[140:141]
	global_load_lds_dwordx4 v[220:221], off
	s_add_i32 m0, s66, 0x2000
	v_lshl_add_u64 v[220:221], s[64:65], 0, v[142:143]
	global_load_lds_dwordx4 v[220:221], off
	s_mov_b32 m0, s39
	v_lshl_add_u64 v[220:221], s[44:45], 0, v[136:137]
	global_load_lds_dwordx4 v[220:221], off
	s_mov_b32 m0, s46
	s_nop 0
	global_load_lds_dwordx4 v[222:223], off
	s_waitcnt vmcnt(8)
	s_waitcnt lgkmcnt(0)
	s_setprio 1
	s_barrier
; #define PG8_STAGE(bufoff, gbase, voff) do { _Pragma("unroll") for (int _i = 0; _i < 2; ++_i) \
;         __builtin_amdgcn_global_load_lds((const unsigned*)((const char*)(gbase) + (voff)[_i]), (PG8_LAS unsigned*)(lds + (bufoff) + ldsw + _i * 8192), 16, 0, 0); } while (0)
; #define PG8_LDA(dst, b, h) do { _Pragma("unroll") for (int m = 0; m < 4; ++m) _Pragma("unroll") for (int k = 0; k < 2; ++k) dst[m][k] = *(const PG8_LAS bf16x8*)(lds + PG8_SA(b, h) + aoff + m * 2048 + k * 1024); } while (0)
; #define PG8_LDB(dst, b, h) do { _Pragma("unroll") for (int n = 0; n < 2; ++n) _Pragma("unroll") for (int k = 0; k < 2; ++k) dst[n][k] = *(const PG8_LAS bf16x8*)(lds + PG8_SB(b, h) + boff + n * 2048 + k * 1024); } while (0)
; #define PG8_MMA(ai, bj, At, Bt) do { __builtin_amdgcn_s_setprio(1); _Pragma("unroll") for (int m = 0; m < 4; ++m) _Pragma("unroll") for (int n = 0; n < 2; ++n) _Pragma("unroll") for (int k = 0; k < 2; ++k) \
;         acc[ai][bj][m][n] = __builtin_amdgcn_mfma_f32_16x16x32_bf16(Bt[n][k], At[m][k], acc[ai][bj][m][n], 0, 0, 0); __builtin_amdgcn_s_setprio(0); } while (0)
; #define PG8_WAIT_V(n) asm volatile("s_waitcnt vmcnt(" #n ")" ::: "memory")
; #define PG8_WAIT_L(n) asm volatile("s_waitcnt lgkmcnt(" #n ")" ::: "memory")
; #define PG8_BAR __builtin_amdgcn_s_barrier()
; #define PG8_SCHED __builtin_amdgcn_sched_barrier(0)
; template <class Epi, class Sched, bool ALIGN_EPI = false, bool SP2 = false>
; __device__ __forceinline__ void gemm_phase(PG8_LAS unsigned char* lds, const Gemm g, const Sched& S, const Epi& E) {
;     ...
;             PG8_WAIT_V(8); PG8_WAIT_L(0); PG8_BAR; PG8_MMA(1, 0, At, B0); PG8_MMA(1, 1, At, B1); PG8_BAR; PG8_SCHED;
;             PG8_LDB(B0, 1, 0); PG8_LDB(B1, 1, 1); PG8_SCHED; PG8_LDA(At, 1, 0); PG8_STAGE(PG8_SA(0, 1), a2 + hstep, voffA);
;             PG8_WAIT_V(8); PG8_WAIT_L(0); PG8_BAR; PG8_MMA(0, 0, At, B0); PG8_MMA(0, 1, At, B1); PG8_BAR; PG8_SCHED;
	v_mfma_f32_16x16x32_bf16 v[92:95], v[128:131], v[186:189], v[92:95]
	v_mfma_f32_16x16x32_bf16 v[88:91], v[154:157], v[186:189], v[88:91]
	v_mfma_f32_16x16x32_bf16 v[84:87], v[128:131], v[194:197], v[84:87]
	v_mfma_f32_16x16x32_bf16 v[80:83], v[154:157], v[194:197], v[80:83]
	v_mfma_f32_16x16x32_bf16 v[76:79], v[128:131], v[202:205], v[76:79]
	v_mfma_f32_16x16x32_bf16 v[72:75], v[154:157], v[202:205], v[72:75]
	v_mfma_f32_16x16x32_bf16 v[64:67], v[128:131], v[210:213], v[64:67]
	v_mfma_f32_16x16x32_bf16 v[56:59], v[154:157], v[210:213], v[56:59]
	v_mfma_f32_16x16x32_bf16 v[92:95], v[132:135], v[190:193], v[92:95]
	v_mfma_f32_16x16x32_bf16 v[88:91], v[158:161], v[190:193], v[88:91]
	v_mfma_f32_16x16x32_bf16 v[84:87], v[132:135], v[198:201], v[84:87]
	v_mfma_f32_16x16x32_bf16 v[80:83], v[158:161], v[198:201], v[80:83]
	v_mfma_f32_16x16x32_bf16 v[76:79], v[132:135], v[206:209], v[76:79]
	v_mfma_f32_16x16x32_bf16 v[72:75], v[158:161], v[206:209], v[72:75]
	v_mfma_f32_16x16x32_bf16 v[64:67], v[132:135], v[214:217], v[64:67]
	v_mfma_f32_16x16x32_bf16 v[56:59], v[158:161], v[214:217], v[56:59]
	s_setprio 0
	s_setprio 1
	v_mfma_f32_16x16x32_bf16 v[28:31], v[170:173], v[186:189], v[28:31]
	v_mfma_f32_16x16x32_bf16 v[24:27], v[178:181], v[186:189], v[24:27]
	v_mfma_f32_16x16x32_bf16 v[20:23], v[170:173], v[194:197], v[20:23]
	v_mfma_f32_16x16x32_bf16 v[16:19], v[178:181], v[194:197], v[16:19]
	v_mfma_f32_16x16x32_bf16 v[12:15], v[170:173], v[202:205], v[12:15]
	v_mfma_f32_16x16x32_bf16 v[8:11], v[178:181], v[202:205], v[8:11]
	v_mfma_f32_16x16x32_bf16 v[4:7], v[170:173], v[210:213], v[4:7]
	v_mfma_f32_16x16x32_bf16 v[0:3], v[178:181], v[210:213], v[0:3]
	v_mfma_f32_16x16x32_bf16 v[28:31], v[174:177], v[190:193], v[28:31]
	v_mfma_f32_16x16x32_bf16 v[24:27], v[182:185], v[190:193], v[24:27]
	v_mfma_f32_16x16x32_bf16 v[20:23], v[174:177], v[198:201], v[20:23]
	v_mfma_f32_16x16x32_bf16 v[16:19], v[182:185], v[198:201], v[16:19]
	v_mfma_f32_16x16x32_bf16 v[12:15], v[174:177], v[206:209], v[12:15]
	s_setprio 2
	s_barrier
	v_mfma_f32_16x16x32_bf16 v[8:11], v[182:185], v[206:209], v[8:11]
	v_mfma_f32_16x16x32_bf16 v[4:7], v[174:177], v[214:217], v[4:7]
	v_mfma_f32_16x16x32_bf16 v[0:3], v[182:185], v[214:217], v[0:3]
	s_setprio 0
	s_add_i32 s64, 0, 0x18000
	s_add_i32 s65, 0, 0x1c000
	v_add_u32_e32 v158, s64, v165
	v_add_u32_e32 v182, s65, v165
	ds_read_b128 v[128:131], v158
	ds_read_b128 v[132:135], v158 offset:1024
	ds_read_b128 v[154:157], v158 offset:2048
	ds_read_b128 v[158:161], v158 offset:3072
	ds_read_b128 v[170:173], v182
	ds_read_b128 v[174:177], v182 offset:1024
	ds_read_b128 v[178:181], v182 offset:2048
	ds_read_b128 v[182:185], v182 offset:3072
	s_add_u32 s44, s44, 0x200000
	s_addc_u32 s45, s45, 0
	s_mov_b32 m0, s47
	v_lshl_add_u64 v[224:225], s[44:45], 0, v[136:137]
	ds_read_b128 v[186:189], v169 offset:32768
	ds_read_b128 v[190:193], v169 offset:33792
	ds_read_b128 v[194:197], v169 offset:34816
	ds_read_b128 v[198:201], v169 offset:35840
	ds_read_b128 v[202:205], v169 offset:36864
	ds_read_b128 v[206:209], v169 offset:37888
	ds_read_b128 v[210:213], v169 offset:38912
	ds_read_b128 v[214:217], v169 offset:39936
	global_load_lds_dwordx4 v[224:225], off
	s_mov_b32 m0, s48
	v_lshl_add_u64 v[224:225], s[44:45], 0, v[140:141]
	global_load_lds_dwordx4 v[224:225], off
	s_waitcnt vmcnt(8)
	s_waitcnt lgkmcnt(0)
	s_setprio 1
	s_barrier
	v_mfma_f32_16x16x32_bf16 v[124:127], v[128:131], v[186:189], v[124:127]
	v_mfma_f32_16x16x32_bf16 v[120:123], v[154:157], v[186:189], v[120:123]
	v_mfma_f32_16x16x32_bf16 v[116:119], v[128:131], v[194:197], v[116:119]
	v_mfma_f32_16x16x32_bf16 v[112:115], v[154:157], v[194:197], v[112:115]
	v_mfma_f32_16x16x32_bf16 v[108:111], v[128:131], v[202:205], v[108:111]
	v_mfma_f32_16x16x32_bf16 v[104:107], v[154:157], v[202:205], v[104:107]
	v_mfma_f32_16x16x32_bf16 v[100:103], v[128:131], v[210:213], v[100:103]
	v_mfma_f32_16x16x32_bf16 v[96:99], v[154:157], v[210:213], v[96:99]
	v_mfma_f32_16x16x32_bf16 v[124:127], v[132:135], v[190:193], v[124:127]
	v_mfma_f32_16x16x32_bf16 v[120:123], v[158:161], v[190:193], v[120:123]
	v_mfma_f32_16x16x32_bf16 v[116:119], v[132:135], v[198:201], v[116:119]
	v_mfma_f32_16x16x32_bf16 v[112:115], v[158:161], v[198:201], v[112:115]
	v_mfma_f32_16x16x32_bf16 v[108:111], v[132:135], v[206:209], v[108:111]
	v_mfma_f32_16x16x32_bf16 v[104:107], v[158:161], v[206:209], v[104:107]
	v_mfma_f32_16x16x32_bf16 v[100:103], v[132:135], v[214:217], v[100:103]
	v_mfma_f32_16x16x32_bf16 v[96:99], v[158:161], v[214:217], v[96:99]
	s_setprio 0
	s_setprio 1
	v_mfma_f32_16x16x32_bf16 v[68:71], v[170:173], v[186:189], v[68:71]
	v_mfma_f32_16x16x32_bf16 v[60:63], v[178:181], v[186:189], v[60:63]
	v_mfma_f32_16x16x32_bf16 v[52:55], v[170:173], v[194:197], v[52:55]
	v_mfma_f32_16x16x32_bf16 v[48:51], v[178:181], v[194:197], v[48:51]
	v_mfma_f32_16x16x32_bf16 v[44:47], v[170:173], v[202:205], v[44:47]
	v_mfma_f32_16x16x32_bf16 v[40:43], v[178:181], v[202:205], v[40:43]
	v_mfma_f32_16x16x32_bf16 v[36:39], v[170:173], v[210:213], v[36:39]
	v_mfma_f32_16x16x32_bf16 v[32:35], v[178:181], v[210:213], v[32:35]
	v_mfma_f32_16x16x32_bf16 v[68:71], v[174:177], v[190:193], v[68:71]
	v_mfma_f32_16x16x32_bf16 v[60:63], v[182:185], v[190:193], v[60:63]
	v_mfma_f32_16x16x32_bf16 v[52:55], v[174:177], v[198:201], v[52:55]
	v_mfma_f32_16x16x32_bf16 v[48:51], v[182:185], v[198:201], v[48:51]
	v_mfma_f32_16x16x32_bf16 v[44:47], v[174:177], v[206:209], v[44:47]
	s_setprio 2
	s_barrier
; #define PG8_STAGE(bufoff, gbase, voff) do { _Pragma("unroll") for (int _i = 0; _i < 2; ++_i) \
;         __builtin_amdgcn_global_load_lds((const unsigned*)((const char*)(gbase) + (voff)[_i]), (PG8_LAS unsigned*)(lds + (bufoff) + ldsw + _i * 8192), 16, 0, 0); } while (0)
; #define PG8_LDA(dst, b, h) do { _Pragma("unroll") for (int m = 0; m < 4; ++m) _Pragma("unroll") for (int k = 0; k < 2; ++k) dst[m][k] = *(const PG8_LAS bf16x8*)(lds + PG8_SA(b, h) + aoff + m * 2048 + k * 1024); } while (0)
; #define PG8_MMA(ai, bj, At, Bt) do { __builtin_amdgcn_s_setprio(1); _Pragma("unroll") for (int m = 0; m < 4; ++m) _Pragma("unroll") for (int n = 0; n < 2; ++n) _Pragma("unroll") for (int k = 0; k < 2; ++k) \
;         acc[ai][bj][m][n] = __builtin_amdgcn_mfma_f32_16x16x32_bf16(Bt[n][k], At[m][k], acc[ai][bj][m][n], 0, 0, 0); __builtin_amdgcn_s_setprio(0); } while (0)
; #define PG8_WAIT_V(n) asm volatile("s_waitcnt vmcnt(" #n ")" ::: "memory")
; #define PG8_WAIT_L(n) asm volatile("s_waitcnt lgkmcnt(" #n ")" ::: "memory")
; #define PG8_BAR __builtin_amdgcn_s_barrier()
; #define PG8_SCHED __builtin_amdgcn_sched_barrier(0)
; template <class Epi, class Sched, bool ALIGN_EPI = false, bool SP2 = false>
; __device__ __forceinline__ void gemm_phase(PG8_LAS unsigned char* lds, const Gemm g, const Sched& S, const Epi& E) {
;     ...
;         for (int t = 0; t < nt; t += 2) {
;             const bool last = (t == nt - 2);
;     ...
;             PG8_WAIT_V(8); PG8_WAIT_L(0); PG8_BAR; PG8_MMA(0, 0, At, B0); PG8_MMA(0, 1, At, B1); PG8_BAR; PG8_SCHED;
;             PG8_LDA(At, 1, 1); PG8_STAGE(PG8_SB(1, 0), b3, voffB); PG8_STAGE(PG8_SB(1, 1), b3 + hstep, voffB); PG8_STAGE(PG8_SA(1, 0), a3, voffA);
;             PG8_WAIT_V(8); PG8_WAIT_L(0); PG8_BAR; PG8_MMA(1, 0, At, B0); PG8_MMA(1, 1, At, B1); PG8_BAR; PG8_SCHED;
	v_mfma_f32_16x16x32_bf16 v[40:43], v[182:185], v[206:209], v[40:43]
	v_mfma_f32_16x16x32_bf16 v[36:39], v[174:177], v[214:217], v[36:39]
	v_mfma_f32_16x16x32_bf16 v[32:35], v[182:185], v[214:217], v[32:35]
	s_setprio 0
	s_add_i32 s44, s64, s33
	v_lshl_add_u64 v[162:163], v[162:163], 0, s[8:9]
	s_mov_b32 m0, s44
	ds_read_b128 v[186:189], v169 offset:49152
	ds_read_b128 v[190:193], v169 offset:50176
	ds_read_b128 v[194:197], v169 offset:51200
	ds_read_b128 v[198:201], v169 offset:52224
	ds_read_b128 v[202:205], v169 offset:53248
	ds_read_b128 v[206:209], v169 offset:54272
	ds_read_b128 v[210:213], v169 offset:55296
	ds_read_b128 v[214:217], v169 offset:56320
	global_load_lds_dwordx4 v[162:163], off
	s_add_i32 m0, s44, 0x2000
	s_add_u32 s42, s42, 0x200080
	v_lshl_add_u64 v[162:163], v[218:219], 0, s[8:9]
	s_addc_u32 s43, s43, 0
	s_add_i32 s44, s65, s33
	global_load_lds_dwordx4 v[162:163], off
	s_mov_b32 m0, s44
	v_lshl_add_u64 v[162:163], s[42:43], 0, v[138:139]
	global_load_lds_dwordx4 v[162:163], off
	s_add_i32 m0, s44, 0x2000
	v_lshl_add_u64 v[162:163], s[42:43], 0, v[142:143]
	global_load_lds_dwordx4 v[162:163], off
	s_mov_b32 m0, s52
	v_lshl_add_u64 v[162:163], v[220:221], 0, s[8:9]
	global_load_lds_dwordx4 v[162:163], off
	s_mov_b32 m0, s53
	v_lshl_add_u64 v[162:163], v[222:223], 0, s[8:9]
	global_load_lds_dwordx4 v[162:163], off
	s_waitcnt vmcnt(8)
	s_waitcnt lgkmcnt(0)
	s_setprio 1
	s_barrier
	v_mfma_f32_16x16x32_bf16 v[92:95], v[128:131], v[186:189], v[92:95]
	v_mfma_f32_16x16x32_bf16 v[88:91], v[154:157], v[186:189], v[88:91]
	v_mfma_f32_16x16x32_bf16 v[84:87], v[128:131], v[194:197], v[84:87]
	v_mfma_f32_16x16x32_bf16 v[80:83], v[154:157], v[194:197], v[80:83]
	v_mfma_f32_16x16x32_bf16 v[76:79], v[128:131], v[202:205], v[76:79]
	v_mfma_f32_16x16x32_bf16 v[72:75], v[154:157], v[202:205], v[72:75]
	v_mfma_f32_16x16x32_bf16 v[64:67], v[128:131], v[210:213], v[64:67]
	v_mfma_f32_16x16x32_bf16 v[56:59], v[154:157], v[210:213], v[56:59]
	v_mfma_f32_16x16x32_bf16 v[92:95], v[132:135], v[190:193], v[92:95]
	v_mfma_f32_16x16x32_bf16 v[88:91], v[158:161], v[190:193], v[88:91]
	v_mfma_f32_16x16x32_bf16 v[84:87], v[132:135], v[198:201], v[84:87]
	v_mfma_f32_16x16x32_bf16 v[80:83], v[158:161], v[198:201], v[80:83]
	v_mfma_f32_16x16x32_bf16 v[76:79], v[132:135], v[206:209], v[76:79]
	v_mfma_f32_16x16x32_bf16 v[72:75], v[158:161], v[206:209], v[72:75]
	v_mfma_f32_16x16x32_bf16 v[64:67], v[132:135], v[214:217], v[64:67]
	v_mfma_f32_16x16x32_bf16 v[56:59], v[158:161], v[214:217], v[56:59]
	s_setprio 0
	s_setprio 1
	v_mfma_f32_16x16x32_bf16 v[28:31], v[170:173], v[186:189], v[28:31]
	v_mfma_f32_16x16x32_bf16 v[24:27], v[178:181], v[186:189], v[24:27]
	v_mfma_f32_16x16x32_bf16 v[20:23], v[170:173], v[194:197], v[20:23]
	v_mfma_f32_16x16x32_bf16 v[16:19], v[178:181], v[194:197], v[16:19]
	v_mfma_f32_16x16x32_bf16 v[12:15], v[170:173], v[202:205], v[12:15]
	v_mfma_f32_16x16x32_bf16 v[8:11], v[178:181], v[202:205], v[8:11]
	v_mfma_f32_16x16x32_bf16 v[4:7], v[170:173], v[210:213], v[4:7]
	v_mfma_f32_16x16x32_bf16 v[0:3], v[178:181], v[210:213], v[0:3]
	v_mfma_f32_16x16x32_bf16 v[28:31], v[174:177], v[190:193], v[28:31]
	v_mfma_f32_16x16x32_bf16 v[24:27], v[182:185], v[190:193], v[24:27]
	v_mfma_f32_16x16x32_bf16 v[20:23], v[174:177], v[198:201], v[20:23]
	v_mfma_f32_16x16x32_bf16 v[16:19], v[182:185], v[198:201], v[16:19]
	v_mfma_f32_16x16x32_bf16 v[12:15], v[174:177], v[206:209], v[12:15]
	s_setprio 2
	s_barrier
	v_mfma_f32_16x16x32_bf16 v[8:11], v[182:185], v[206:209], v[8:11]
	v_mfma_f32_16x16x32_bf16 v[4:7], v[174:177], v[214:217], v[4:7]
	v_mfma_f32_16x16x32_bf16 v[0:3], v[182:185], v[214:217], v[0:3]
	s_setprio 0
	s_add_i32 s63, s63, 2
	s_add_u32 s40, s40, 0x100
	s_addc_u32 s41, s41, 0
	s_add_u32 s61, s61, 0x100
	s_addc_u32 s62, s62, 0
	s_cmpk_gt_u32 s63, 0x7d
	s_cbranch_scc0 .LBB0_1219
	s_and_b64 vcc, exec, s[10:11]
	s_cbranch_vccz .LBB0_1222
	s_barrier
